# all 7 GEMM K-loops: LDS-DMA staging rebalanced 4+4 per super-phase (As[b][0] moved to the A-staging super-phase), SP2 waits vmcnt 8->6
# speedup vs baseline: 1.0107x; 1.0107x over previous
; #define PG8_STAGE(bufoff, gbase, voff) do { _Pragma("unroll") for (int _i = 0; _i < 2; ++_i) \
;         __builtin_amdgcn_global_load_lds((const unsigned*)((const char*)(gbase) + (voff)[_i]), (PG8_LAS unsigned*)(lds + (bufoff) + ldsw + _i * 8192), 16, 0, 0); } while (0)
; #define PG8_LDA(dst, b, h) do { _Pragma("unroll") for (int m = 0; m < 4; ++m) _Pragma("unroll") for (int k = 0; k < 2; ++k) dst[m][k] = *(const PG8_LAS bf16x8*)(lds + PG8_SA(b, h) + aoff + m * 2048 + k * 1024); } while (0)
; #define PG8_LDB(dst, b, h) do { _Pragma("unroll") for (int n = 0; n < 2; ++n) _Pragma("unroll") for (int k = 0; k < 2; ++k) dst[n][k] = *(const PG8_LAS bf16x8*)(lds + PG8_SB(b, h) + boff + n * 2048 + k * 1024); } while (0)
; #define PG8_MMA(ai, bj, At, Bt) do { __builtin_amdgcn_s_setprio(1); _Pragma("unroll") for (int m = 0; m < 4; ++m) _Pragma("unroll") for (int n = 0; n < 2; ++n) _Pragma("unroll") for (int k = 0; k < 2; ++k) \
;         acc[ai][bj][m][n] = __builtin_amdgcn_mfma_f32_16x16x32_bf16(Bt[n][k], At[m][k], acc[ai][bj][m][n], 0, 0, 0); __builtin_amdgcn_s_setprio(0); } while (0)
; #define PG8_WAIT_V(n) asm volatile("s_waitcnt vmcnt(" #n ")" ::: "memory")
; #define PG8_WAIT_L(n) asm volatile("s_waitcnt lgkmcnt(" #n ")" ::: "memory")
; #define PG8_BAR __builtin_amdgcn_s_barrier()
; #define PG8_SCHED __builtin_amdgcn_sched_barrier(0)
; template <class Epi, class Sched, bool ALIGN_EPI = false, bool SP2 = false>
; __device__ __forceinline__ void gemm_phase(PG8_LAS unsigned char* lds, const Gemm g, const Sched& S, const Epi& E) {
;     ...
;             PG8_LDB(B0, 0, 0); PG8_LDB(B1, 0, 1); PG8_SCHED; PG8_LDA(At, 0, 0); PG8_STAGE(PG8_SA(1, 1), a1 + hstep, voffA);
;             PG8_WAIT_V(8); PG8_WAIT_L(0); PG8_BAR; PG8_MMA(0, 0, At, B0); PG8_MMA(0, 1, At, B1); PG8_BAR; PG8_SCHED;
;             PG8_LDA(At, 0, 1); PG8_STAGE(PG8_SB(0, 0), b2, voffB); PG8_STAGE(PG8_SB(0, 1), b2 + hstep, voffB); PG8_STAGE(PG8_SA(0, 0), a2, voffA);
;             PG8_WAIT_V(8); PG8_WAIT_L(0); PG8_BAR; PG8_MMA(1, 0, At, B0); PG8_MMA(1, 1, At, B1); PG8_BAR; PG8_SCHED;
.LBB0_309:
	s_add_u32 s40, s54, 0xfff80080
	s_addc_u32 s41, s55, -1
	s_add_i32 s36, 0, 0x10000
	s_cmp_eq_u32 s7, 28
	s_cselect_b32 s97, s9, s41
	s_cselect_b32 s96, s35, s40
	v_add_u32_e32 v156, s36, v164
	s_cselect_b32 s85, s87, vcc_hi
	s_cselect_b32 s84, s91, vcc_lo
	s_add_i32 s37, 0, 0x14000
	ds_read_b128 v[130:133], v156
	ds_read_b128 v[168:171], v156 offset:1024
	ds_read_b128 v[172:175], v156 offset:2048
	ds_read_b128 v[176:179], v156 offset:3072
	v_add_u32_e32 v156, s37, v164
	ds_read_b128 v[180:183], v156
	ds_read_b128 v[188:191], v156 offset:1024
	ds_read_b128 v[192:195], v156 offset:2048
	ds_read_b128 v[196:199], v156 offset:3072
	v_lshl_add_u64 v[156:157], s[54:55], 0, v[146:147]
	s_add_i32 m0, s82, 0xc000
	ds_read_b128 v[200:203], v166
	ds_read_b128 v[204:207], v166 offset:1024
	ds_read_b128 v[208:211], v166 offset:2048
	ds_read_b128 v[212:215], v166 offset:3072
	ds_read_b128 v[216:219], v166 offset:4096
	ds_read_b128 v[220:223], v166 offset:5120
	ds_read_b128 v[224:227], v166 offset:6144
	ds_read_b128 v[228:231], v166 offset:7168
	s_add_u32 s98, s54, 0xfff80000
	s_addc_u32 s99, s55, -1
	s_mov_b32 m0, s60
	s_nop 0
	global_load_lds_dwordx4 v146, s[98:99]
	s_mov_b32 m0, s61
	s_nop 0
	global_load_lds_dwordx4 v148, s[98:99]
	s_add_i32 m0, s82, 0xc000
	s_nop 0
	global_load_lds_dwordx4 v[156:157], off
	v_lshl_add_u64 v[156:157], s[54:55], 0, v[148:149]
	s_add_i32 m0, s82, 0xe000
	s_nop 0
	global_load_lds_dwordx4 v[156:157], off
	s_waitcnt vmcnt(8)
	s_waitcnt lgkmcnt(0)
	s_barrier
	s_setprio 1
	s_waitcnt lgkmcnt(0)
	v_mfma_f32_16x16x32_bf16 v[126:129], v[130:133], v[200:203], v[126:129]
	v_mfma_f32_16x16x32_bf16 v[122:125], v[172:175], v[200:203], v[122:125]
	v_mfma_f32_16x16x32_bf16 v[110:113], v[130:133], v[208:211], v[110:113]
	v_mfma_f32_16x16x32_bf16 v[106:109], v[172:175], v[208:211], v[106:109]
	v_mfma_f32_16x16x32_bf16 v[94:97], v[130:133], v[216:219], v[94:97]
	v_mfma_f32_16x16x32_bf16 v[90:93], v[172:175], v[216:219], v[90:93]
	v_mfma_f32_16x16x32_bf16 v[78:81], v[130:133], v[224:227], v[78:81]
	v_mfma_f32_16x16x32_bf16 v[74:77], v[172:175], v[224:227], v[74:77]
	v_mfma_f32_16x16x32_bf16 v[126:129], v[168:171], v[204:207], v[126:129]
	v_mfma_f32_16x16x32_bf16 v[122:125], v[176:179], v[204:207], v[122:125]
	v_mfma_f32_16x16x32_bf16 v[110:113], v[168:171], v[212:215], v[110:113]
	v_mfma_f32_16x16x32_bf16 v[106:109], v[176:179], v[212:215], v[106:109]
	v_mfma_f32_16x16x32_bf16 v[94:97], v[168:171], v[220:223], v[94:97]
	v_mfma_f32_16x16x32_bf16 v[90:93], v[176:179], v[220:223], v[90:93]
	v_mfma_f32_16x16x32_bf16 v[78:81], v[168:171], v[228:231], v[78:81]
	v_mfma_f32_16x16x32_bf16 v[74:77], v[176:179], v[228:231], v[74:77]
	s_setprio 0
	s_setprio 1
	v_mfma_f32_16x16x32_bf16 v[118:121], v[180:183], v[200:203], v[118:121]
	v_mfma_f32_16x16x32_bf16 v[114:117], v[192:195], v[200:203], v[114:117]
	v_mfma_f32_16x16x32_bf16 v[102:105], v[180:183], v[208:211], v[102:105]
	v_mfma_f32_16x16x32_bf16 v[98:101], v[192:195], v[208:211], v[98:101]
	v_mfma_f32_16x16x32_bf16 v[86:89], v[180:183], v[216:219], v[86:89]
	v_mfma_f32_16x16x32_bf16 v[82:85], v[192:195], v[216:219], v[82:85]
	v_mfma_f32_16x16x32_bf16 v[70:73], v[180:183], v[224:227], v[70:73]
	v_mfma_f32_16x16x32_bf16 v[66:69], v[192:195], v[224:227], v[66:69]
	v_mfma_f32_16x16x32_bf16 v[118:121], v[188:191], v[204:207], v[118:121]
	v_mfma_f32_16x16x32_bf16 v[114:117], v[196:199], v[204:207], v[114:117]
	v_mfma_f32_16x16x32_bf16 v[102:105], v[188:191], v[212:215], v[102:105]
	v_mfma_f32_16x16x32_bf16 v[98:101], v[196:199], v[212:215], v[98:101]
	v_mfma_f32_16x16x32_bf16 v[86:89], v[188:191], v[220:223], v[86:89]
	v_mfma_f32_16x16x32_bf16 v[82:85], v[196:199], v[220:223], v[82:85]
	v_mfma_f32_16x16x32_bf16 v[70:73], v[188:191], v[228:231], v[70:73]
	v_mfma_f32_16x16x32_bf16 v[66:69], v[196:199], v[228:231], v[66:69]
	s_setprio 0
	s_barrier
	s_add_i32 s36, s36, s20
	v_lshl_add_u64 v[156:157], s[84:85], 0, v[138:139]
	s_mov_b32 m0, s36
	ds_read_b128 v[200:203], v166 offset:16384
	ds_read_b128 v[204:207], v166 offset:17408
	ds_read_b128 v[208:211], v166 offset:18432
	ds_read_b128 v[212:215], v166 offset:19456
	ds_read_b128 v[216:219], v166 offset:20480
	ds_read_b128 v[220:223], v166 offset:21504
	ds_read_b128 v[224:227], v166 offset:22528
	ds_read_b128 v[228:231], v166 offset:23552
	global_load_lds_dwordx4 v[156:157], off
	s_add_i32 m0, s36, 0x2000
	s_add_u32 s40, s84, 0x80000
	v_lshl_add_u64 v[184:185], s[84:85], 0, v[142:143]
	s_addc_u32 s41, s85, 0
	s_add_i32 s36, s37, s20
	global_load_lds_dwordx4 v[184:185], off
	v_lshl_add_u64 v[232:233], s[40:41], 0, v[138:139]
	s_mov_b32 m0, s36
	v_lshl_add_u64 v[234:235], s[96:97], 0, v[140:141]
	global_load_lds_dwordx4 v[232:233], off
	v_lshl_add_u64 v[232:233], s[40:41], 0, v[142:143]
	s_add_i32 m0, s36, 0x2000
	s_nop 0
	global_load_lds_dwordx4 v[232:233], off
	v_lshl_add_u64 v[232:233], s[96:97], 0, v[136:137]
	s_mov_b32 m0, s82
	s_nop 0
	s_mov_b32 m0, s83
	s_nop 0
	s_waitcnt vmcnt(6)
	s_waitcnt lgkmcnt(0)
	s_barrier
; #define PG8_STAGE(bufoff, gbase, voff) do { _Pragma("unroll") for (int _i = 0; _i < 2; ++_i) \
;         __builtin_amdgcn_global_load_lds((const unsigned*)((const char*)(gbase) + (voff)[_i]), (PG8_LAS unsigned*)(lds + (bufoff) + ldsw + _i * 8192), 16, 0, 0); } while (0)
; #define PG8_LDA(dst, b, h) do { _Pragma("unroll") for (int m = 0; m < 4; ++m) _Pragma("unroll") for (int k = 0; k < 2; ++k) dst[m][k] = *(const PG8_LAS bf16x8*)(lds + PG8_SA(b, h) + aoff + m * 2048 + k * 1024); } while (0)
; #define PG8_LDB(dst, b, h) do { _Pragma("unroll") for (int n = 0; n < 2; ++n) _Pragma("unroll") for (int k = 0; k < 2; ++k) dst[n][k] = *(const PG8_LAS bf16x8*)(lds + PG8_SB(b, h) + boff + n * 2048 + k * 1024); } while (0)
; #define PG8_MMA(ai, bj, At, Bt) do { __builtin_amdgcn_s_setprio(1); _Pragma("unroll") for (int m = 0; m < 4; ++m) _Pragma("unroll") for (int n = 0; n < 2; ++n) _Pragma("unroll") for (int k = 0; k < 2; ++k) \
;         acc[ai][bj][m][n] = __builtin_amdgcn_mfma_f32_16x16x32_bf16(Bt[n][k], At[m][k], acc[ai][bj][m][n], 0, 0, 0); __builtin_amdgcn_s_setprio(0); } while (0)
; #define PG8_WAIT_V(n) asm volatile("s_waitcnt vmcnt(" #n ")" ::: "memory")
; #define PG8_WAIT_L(n) asm volatile("s_waitcnt lgkmcnt(" #n ")" ::: "memory")
; #define PG8_BAR __builtin_amdgcn_s_barrier()
; #define PG8_SCHED __builtin_amdgcn_sched_barrier(0)
; template <class Epi, class Sched, bool ALIGN_EPI = false, bool SP2 = false>
; __device__ __forceinline__ void gemm_phase(PG8_LAS unsigned char* lds, const Gemm g, const Sched& S, const Epi& E) {
;     ...
;             PG8_WAIT_V(8); PG8_WAIT_L(0); PG8_BAR; PG8_MMA(1, 0, At, B0); PG8_MMA(1, 1, At, B1); PG8_BAR; PG8_SCHED;
;             PG8_LDB(B0, 1, 0); PG8_LDB(B1, 1, 1); PG8_SCHED; PG8_LDA(At, 1, 0); PG8_STAGE(PG8_SA(0, 1), a2 + hstep, voffA);
;             PG8_WAIT_V(8); PG8_WAIT_L(0); PG8_BAR; PG8_MMA(0, 0, At, B0); PG8_MMA(0, 1, At, B1); PG8_BAR; PG8_SCHED;
	s_setprio 1
	s_waitcnt lgkmcnt(0)
	v_mfma_f32_16x16x32_bf16 v[62:65], v[130:133], v[200:203], v[62:65]
	v_mfma_f32_16x16x32_bf16 v[58:61], v[172:175], v[200:203], v[58:61]
	v_mfma_f32_16x16x32_bf16 v[46:49], v[130:133], v[208:211], v[46:49]
	v_mfma_f32_16x16x32_bf16 v[42:45], v[172:175], v[208:211], v[42:45]
	v_mfma_f32_16x16x32_bf16 v[30:33], v[130:133], v[216:219], v[30:33]
	v_mfma_f32_16x16x32_bf16 v[26:29], v[172:175], v[216:219], v[26:29]
	v_mfma_f32_16x16x32_bf16 v[14:17], v[130:133], v[224:227], v[14:17]
	v_mfma_f32_16x16x32_bf16 v[10:13], v[172:175], v[224:227], v[10:13]
	v_mfma_f32_16x16x32_bf16 v[62:65], v[168:171], v[204:207], v[62:65]
	v_mfma_f32_16x16x32_bf16 v[58:61], v[176:179], v[204:207], v[58:61]
	v_mfma_f32_16x16x32_bf16 v[46:49], v[168:171], v[212:215], v[46:49]
	v_mfma_f32_16x16x32_bf16 v[42:45], v[176:179], v[212:215], v[42:45]
	v_mfma_f32_16x16x32_bf16 v[30:33], v[168:171], v[220:223], v[30:33]
	v_mfma_f32_16x16x32_bf16 v[26:29], v[176:179], v[220:223], v[26:29]
	v_mfma_f32_16x16x32_bf16 v[14:17], v[168:171], v[228:231], v[14:17]
	v_mfma_f32_16x16x32_bf16 v[10:13], v[176:179], v[228:231], v[10:13]
	s_setprio 0
	s_setprio 1
	v_mfma_f32_16x16x32_bf16 v[54:57], v[180:183], v[200:203], v[54:57]
	v_mfma_f32_16x16x32_bf16 v[50:53], v[192:195], v[200:203], v[50:53]
	v_mfma_f32_16x16x32_bf16 v[38:41], v[180:183], v[208:211], v[38:41]
	v_mfma_f32_16x16x32_bf16 v[34:37], v[192:195], v[208:211], v[34:37]
	v_mfma_f32_16x16x32_bf16 v[22:25], v[180:183], v[216:219], v[22:25]
	v_mfma_f32_16x16x32_bf16 v[18:21], v[192:195], v[216:219], v[18:21]
	v_mfma_f32_16x16x32_bf16 v[6:9], v[180:183], v[224:227], v[6:9]
	v_mfma_f32_16x16x32_bf16 v[2:5], v[192:195], v[224:227], v[2:5]
	v_mfma_f32_16x16x32_bf16 v[54:57], v[188:191], v[204:207], v[54:57]
	v_mfma_f32_16x16x32_bf16 v[50:53], v[196:199], v[204:207], v[50:53]
	v_mfma_f32_16x16x32_bf16 v[38:41], v[188:191], v[212:215], v[38:41]
	v_mfma_f32_16x16x32_bf16 v[34:37], v[196:199], v[212:215], v[34:37]
	v_mfma_f32_16x16x32_bf16 v[22:25], v[188:191], v[220:223], v[22:25]
	v_mfma_f32_16x16x32_bf16 v[18:21], v[196:199], v[220:223], v[18:21]
	v_mfma_f32_16x16x32_bf16 v[6:9], v[188:191], v[228:231], v[6:9]
	v_mfma_f32_16x16x32_bf16 v[2:5], v[196:199], v[228:231], v[2:5]
	s_setprio 0
	s_barrier
	s_add_i32 s36, 0, 0x18000
	v_add_u32_e32 v167, s36, v164
	s_add_i32 s37, 0, 0x1c000
	ds_read_b128 v[130:133], v167
	ds_read_b128 v[168:171], v167 offset:1024
	ds_read_b128 v[172:175], v167 offset:2048
	ds_read_b128 v[176:179], v167 offset:3072
	v_add_u32_e32 v167, s37, v164
	ds_read_b128 v[180:183], v167
	ds_read_b128 v[188:191], v167 offset:1024
	ds_read_b128 v[192:195], v167 offset:2048
	ds_read_b128 v[196:199], v167 offset:3072
	s_add_u32 s40, s96, 0x80000
	s_addc_u32 s41, s97, 0
	s_mov_b32 m0, s3
	v_lshl_add_u64 v[236:237], s[40:41], 0, v[136:137]
	ds_read_b128 v[200:203], v166 offset:32768
	ds_read_b128 v[204:207], v166 offset:33792
	ds_read_b128 v[208:211], v166 offset:34816
	ds_read_b128 v[212:215], v166 offset:35840
	ds_read_b128 v[216:219], v166 offset:36864
	ds_read_b128 v[220:223], v166 offset:37888
	ds_read_b128 v[224:227], v166 offset:38912
	ds_read_b128 v[228:231], v166 offset:39936
	s_add_u32 s98, s40, 0xfff80000
	s_addc_u32 s99, s41, -1
	s_mov_b32 m0, s82
	s_nop 0
	global_load_lds_dwordx4 v136, s[98:99]
	s_mov_b32 m0, s83
	s_nop 0
	global_load_lds_dwordx4 v140, s[98:99]
	s_mov_b32 m0, s3
	s_nop 0
	global_load_lds_dwordx4 v[236:237], off
	v_lshl_add_u64 v[236:237], s[40:41], 0, v[140:141]
	s_mov_b32 m0, s74
	s_nop 0
	global_load_lds_dwordx4 v[236:237], off
	s_waitcnt vmcnt(8)
	s_waitcnt lgkmcnt(0)
	s_barrier
	s_setprio 1
	s_waitcnt lgkmcnt(0)
	v_mfma_f32_16x16x32_bf16 v[126:129], v[130:133], v[200:203], v[126:129]
	v_mfma_f32_16x16x32_bf16 v[122:125], v[172:175], v[200:203], v[122:125]
	v_mfma_f32_16x16x32_bf16 v[110:113], v[130:133], v[208:211], v[110:113]
	v_mfma_f32_16x16x32_bf16 v[106:109], v[172:175], v[208:211], v[106:109]
	v_mfma_f32_16x16x32_bf16 v[94:97], v[130:133], v[216:219], v[94:97]
	v_mfma_f32_16x16x32_bf16 v[90:93], v[172:175], v[216:219], v[90:93]
	v_mfma_f32_16x16x32_bf16 v[78:81], v[130:133], v[224:227], v[78:81]
	v_mfma_f32_16x16x32_bf16 v[74:77], v[172:175], v[224:227], v[74:77]
	v_mfma_f32_16x16x32_bf16 v[126:129], v[168:171], v[204:207], v[126:129]
	v_mfma_f32_16x16x32_bf16 v[122:125], v[176:179], v[204:207], v[122:125]
	v_mfma_f32_16x16x32_bf16 v[110:113], v[168:171], v[212:215], v[110:113]
	v_mfma_f32_16x16x32_bf16 v[106:109], v[176:179], v[212:215], v[106:109]
	v_mfma_f32_16x16x32_bf16 v[94:97], v[168:171], v[220:223], v[94:97]
	v_mfma_f32_16x16x32_bf16 v[90:93], v[176:179], v[220:223], v[90:93]
	v_mfma_f32_16x16x32_bf16 v[78:81], v[168:171], v[228:231], v[78:81]
	v_mfma_f32_16x16x32_bf16 v[74:77], v[176:179], v[228:231], v[74:77]
	s_setprio 0
	s_setprio 1
	v_mfma_f32_16x16x32_bf16 v[118:121], v[180:183], v[200:203], v[118:121]
	v_mfma_f32_16x16x32_bf16 v[114:117], v[192:195], v[200:203], v[114:117]
	v_mfma_f32_16x16x32_bf16 v[102:105], v[180:183], v[208:211], v[102:105]
	v_mfma_f32_16x16x32_bf16 v[98:101], v[192:195], v[208:211], v[98:101]
	v_mfma_f32_16x16x32_bf16 v[86:89], v[180:183], v[216:219], v[86:89]
	v_mfma_f32_16x16x32_bf16 v[82:85], v[192:195], v[216:219], v[82:85]
	v_mfma_f32_16x16x32_bf16 v[70:73], v[180:183], v[224:227], v[70:73]
	v_mfma_f32_16x16x32_bf16 v[66:69], v[192:195], v[224:227], v[66:69]
	v_mfma_f32_16x16x32_bf16 v[118:121], v[188:191], v[204:207], v[118:121]
	v_mfma_f32_16x16x32_bf16 v[114:117], v[196:199], v[204:207], v[114:117]
	v_mfma_f32_16x16x32_bf16 v[102:105], v[188:191], v[212:215], v[102:105]
	v_mfma_f32_16x16x32_bf16 v[98:101], v[196:199], v[212:215], v[98:101]
	v_mfma_f32_16x16x32_bf16 v[86:89], v[188:191], v[220:223], v[86:89]
	v_mfma_f32_16x16x32_bf16 v[82:85], v[196:199], v[220:223], v[82:85]
	v_mfma_f32_16x16x32_bf16 v[70:73], v[188:191], v[228:231], v[70:73]
	v_mfma_f32_16x16x32_bf16 v[66:69], v[196:199], v[228:231], v[66:69]
	s_setprio 0
	s_barrier
; #define PG8_STAGE(bufoff, gbase, voff) do { _Pragma("unroll") for (int _i = 0; _i < 2; ++_i) \
;         __builtin_amdgcn_global_load_lds((const unsigned*)((const char*)(gbase) + (voff)[_i]), (PG8_LAS unsigned*)(lds + (bufoff) + ldsw + _i * 8192), 16, 0, 0); } while (0)
; #define PG8_LDA(dst, b, h) do { _Pragma("unroll") for (int m = 0; m < 4; ++m) _Pragma("unroll") for (int k = 0; k < 2; ++k) dst[m][k] = *(const PG8_LAS bf16x8*)(lds + PG8_SA(b, h) + aoff + m * 2048 + k * 1024); } while (0)
; #define PG8_MMA(ai, bj, At, Bt) do { __builtin_amdgcn_s_setprio(1); _Pragma("unroll") for (int m = 0; m < 4; ++m) _Pragma("unroll") for (int n = 0; n < 2; ++n) _Pragma("unroll") for (int k = 0; k < 2; ++k) \
;         acc[ai][bj][m][n] = __builtin_amdgcn_mfma_f32_16x16x32_bf16(Bt[n][k], At[m][k], acc[ai][bj][m][n], 0, 0, 0); __builtin_amdgcn_s_setprio(0); } while (0)
; #define PG8_WAIT_V(n) asm volatile("s_waitcnt vmcnt(" #n ")" ::: "memory")
; #define PG8_WAIT_L(n) asm volatile("s_waitcnt lgkmcnt(" #n ")" ::: "memory")
; #define PG8_BAR __builtin_amdgcn_s_barrier()
; #define PG8_SCHED __builtin_amdgcn_sched_barrier(0)
; template <class Epi, class Sched, bool ALIGN_EPI = false, bool SP2 = false>
; __device__ __forceinline__ void gemm_phase(PG8_LAS unsigned char* lds, const Gemm g, const Sched& S, const Epi& E) {
;     ...
;         for (int t = 0; t < nt; t += 2) {
;             const bool last = (t == nt - 2);
;             const char* a1 = cA + (size_t)(t + 1) * kstep;
;             const char* a2 = last ? nA : cA + (size_t)(t + 2) * kstep; const char* b2 = last ? nB : cB + (size_t)(t + 2) * kstep;
;     ...
;             PG8_LDA(At, 1, 1); PG8_STAGE(PG8_SB(1, 0), b3, voffB); PG8_STAGE(PG8_SB(1, 1), b3 + hstep, voffB); PG8_STAGE(PG8_SA(1, 0), a3, voffA);
;             PG8_WAIT_V(8); PG8_WAIT_L(0); PG8_BAR; PG8_MMA(1, 0, At, B0); PG8_MMA(1, 1, At, B1); PG8_BAR; PG8_SCHED;
	s_add_i32 s36, s36, s20
	v_lshl_add_u64 v[156:157], v[156:157], 0, s[42:43]
	s_mov_b32 m0, s36
	ds_read_b128 v[200:203], v166 offset:49152
	ds_read_b128 v[204:207], v166 offset:50176
	ds_read_b128 v[208:211], v166 offset:51200
	ds_read_b128 v[212:215], v166 offset:52224
	ds_read_b128 v[216:219], v166 offset:53248
	ds_read_b128 v[220:223], v166 offset:54272
	ds_read_b128 v[224:227], v166 offset:55296
	ds_read_b128 v[228:231], v166 offset:56320
	global_load_lds_dwordx4 v[156:157], off
	s_add_i32 m0, s36, 0x2000
	s_add_u32 s40, s84, 0x80080
	v_lshl_add_u64 v[156:157], v[184:185], 0, s[42:43]
	s_addc_u32 s41, s85, 0
	s_add_i32 s36, s37, s20
	global_load_lds_dwordx4 v[156:157], off
	v_lshl_add_u64 v[156:157], s[40:41], 0, v[138:139]
	s_mov_b32 m0, s36
	s_nop 0
	global_load_lds_dwordx4 v[156:157], off
	v_lshl_add_u64 v[156:157], s[40:41], 0, v[142:143]
	s_add_i32 m0, s36, 0x2000
	s_nop 0
	global_load_lds_dwordx4 v[156:157], off
	v_lshl_add_u64 v[156:157], v[232:233], 0, s[42:43]
	s_mov_b32 m0, s60
	s_nop 0
	v_lshl_add_u64 v[156:157], v[234:235], 0, s[42:43]
	s_mov_b32 m0, s61
	s_nop 0
	s_waitcnt vmcnt(6)
	s_waitcnt lgkmcnt(0)
	s_barrier
	s_setprio 1
	s_waitcnt lgkmcnt(0)
	v_mfma_f32_16x16x32_bf16 v[62:65], v[130:133], v[200:203], v[62:65]
	v_mfma_f32_16x16x32_bf16 v[58:61], v[172:175], v[200:203], v[58:61]
	v_mfma_f32_16x16x32_bf16 v[46:49], v[130:133], v[208:211], v[46:49]
	v_mfma_f32_16x16x32_bf16 v[42:45], v[172:175], v[208:211], v[42:45]
	v_mfma_f32_16x16x32_bf16 v[30:33], v[130:133], v[216:219], v[30:33]
	v_mfma_f32_16x16x32_bf16 v[26:29], v[172:175], v[216:219], v[26:29]
	v_mfma_f32_16x16x32_bf16 v[14:17], v[130:133], v[224:227], v[14:17]
	v_mfma_f32_16x16x32_bf16 v[10:13], v[172:175], v[224:227], v[10:13]
	v_mfma_f32_16x16x32_bf16 v[62:65], v[168:171], v[204:207], v[62:65]
	v_mfma_f32_16x16x32_bf16 v[58:61], v[176:179], v[204:207], v[58:61]
	v_mfma_f32_16x16x32_bf16 v[46:49], v[168:171], v[212:215], v[46:49]
	v_mfma_f32_16x16x32_bf16 v[42:45], v[176:179], v[212:215], v[42:45]
	v_mfma_f32_16x16x32_bf16 v[30:33], v[168:171], v[220:223], v[30:33]
	v_mfma_f32_16x16x32_bf16 v[26:29], v[176:179], v[220:223], v[26:29]
	v_mfma_f32_16x16x32_bf16 v[14:17], v[168:171], v[228:231], v[14:17]
	v_mfma_f32_16x16x32_bf16 v[10:13], v[176:179], v[228:231], v[10:13]
	s_setprio 0
	s_setprio 1
	v_mfma_f32_16x16x32_bf16 v[54:57], v[180:183], v[200:203], v[54:57]
	v_mfma_f32_16x16x32_bf16 v[50:53], v[192:195], v[200:203], v[50:53]
	v_mfma_f32_16x16x32_bf16 v[38:41], v[180:183], v[208:211], v[38:41]
	v_mfma_f32_16x16x32_bf16 v[34:37], v[192:195], v[208:211], v[34:37]
	v_mfma_f32_16x16x32_bf16 v[22:25], v[180:183], v[216:219], v[22:25]
	v_mfma_f32_16x16x32_bf16 v[18:21], v[192:195], v[216:219], v[18:21]
	v_mfma_f32_16x16x32_bf16 v[6:9], v[180:183], v[224:227], v[6:9]
	v_mfma_f32_16x16x32_bf16 v[2:5], v[192:195], v[224:227], v[2:5]
	v_mfma_f32_16x16x32_bf16 v[54:57], v[188:191], v[204:207], v[54:57]
	v_mfma_f32_16x16x32_bf16 v[50:53], v[196:199], v[204:207], v[50:53]
	v_mfma_f32_16x16x32_bf16 v[38:41], v[188:191], v[212:215], v[38:41]
	v_mfma_f32_16x16x32_bf16 v[34:37], v[196:199], v[212:215], v[34:37]
	v_mfma_f32_16x16x32_bf16 v[22:25], v[188:191], v[220:223], v[22:25]
	v_mfma_f32_16x16x32_bf16 v[18:21], v[196:199], v[220:223], v[18:21]
	v_mfma_f32_16x16x32_bf16 v[6:9], v[188:191], v[228:231], v[6:9]
	v_mfma_f32_16x16x32_bf16 v[2:5], v[196:199], v[228:231], v[2:5]
	s_setprio 0
	s_barrier
	s_add_i32 s7, s7, 2
	s_add_u32 s54, s54, 0x100
	s_addc_u32 s55, s55, 0
	s_add_u32 vcc_lo, vcc_lo, 0x100
	s_addc_u32 vcc_hi, vcc_hi, 0
	s_cmp_gt_u32 s7, 29
	s_cbranch_scc0 .LBB0_309
	s_and_b64 vcc, exec, s[72:73]
	s_cbranch_vccz .LBB0_312
	s_barrier

; #define PG8_STAGE(bufoff, gbase, voff) do { _Pragma("unroll") for (int _i = 0; _i < 2; ++_i) \
;         __builtin_amdgcn_global_load_lds((const unsigned*)((const char*)(gbase) + (voff)[_i]), (PG8_LAS unsigned*)(lds + (bufoff) + ldsw + _i * 8192), 16, 0, 0); } while (0)
; #define PG8_LDA(dst, b, h) do { _Pragma("unroll") for (int m = 0; m < 4; ++m) _Pragma("unroll") for (int k = 0; k < 2; ++k) dst[m][k] = *(const PG8_LAS bf16x8*)(lds + PG8_SA(b, h) + aoff + m * 2048 + k * 1024); } while (0)
; #define PG8_LDB(dst, b, h) do { _Pragma("unroll") for (int n = 0; n < 2; ++n) _Pragma("unroll") for (int k = 0; k < 2; ++k) dst[n][k] = *(const PG8_LAS bf16x8*)(lds + PG8_SB(b, h) + boff + n * 2048 + k * 1024); } while (0)
; #define PG8_MMA(ai, bj, At, Bt) do { __builtin_amdgcn_s_setprio(1); _Pragma("unroll") for (int m = 0; m < 4; ++m) _Pragma("unroll") for (int n = 0; n < 2; ++n) _Pragma("unroll") for (int k = 0; k < 2; ++k) \
;         acc[ai][bj][m][n] = __builtin_amdgcn_mfma_f32_16x16x32_bf16(Bt[n][k], At[m][k], acc[ai][bj][m][n], 0, 0, 0); __builtin_amdgcn_s_setprio(0); } while (0)
; #define PG8_WAIT_V(n) asm volatile("s_waitcnt vmcnt(" #n ")" ::: "memory")
; #define PG8_WAIT_L(n) asm volatile("s_waitcnt lgkmcnt(" #n ")" ::: "memory")
; #define PG8_BAR __builtin_amdgcn_s_barrier()
; #define PG8_SCHED __builtin_amdgcn_sched_barrier(0)
; template <class Epi, class Sched, bool ALIGN_EPI = false, bool SP2 = false>
; __device__ __forceinline__ void gemm_phase(PG8_LAS unsigned char* lds, const Gemm g, const Sched& S, const Epi& E) {
;     ...
;             PG8_LDB(B0, 0, 0); PG8_LDB(B1, 0, 1); PG8_SCHED; PG8_LDA(At, 0, 0); PG8_STAGE(PG8_SA(1, 1), a1 + hstep, voffA);
;             PG8_WAIT_V(8); PG8_WAIT_L(0); PG8_BAR; PG8_MMA(0, 0, At, B0); PG8_MMA(0, 1, At, B1); PG8_BAR; PG8_SCHED;
;             PG8_LDA(At, 0, 1); PG8_STAGE(PG8_SB(0, 0), b2, voffB); PG8_STAGE(PG8_SB(0, 1), b2 + hstep, voffB); PG8_STAGE(PG8_SA(0, 0), a2, voffA);
;             PG8_WAIT_V(8); PG8_WAIT_L(0); PG8_BAR; PG8_MMA(1, 0, At, B0); PG8_MMA(1, 1, At, B1); PG8_BAR; PG8_SCHED;
.LBB0_592:
	ds_read_b128 v[156:159], v152
	ds_read_b128 v[160:163], v152 offset:1024
	ds_read_b128 v[164:167], v152 offset:2048
	ds_read_b128 v[168:171], v152 offset:3072
	ds_read_b128 v[172:175], v153
	ds_read_b128 v[176:179], v153 offset:1024
	ds_read_b128 v[180:183], v153 offset:2048
	ds_read_b128 v[188:191], v153 offset:3072
	s_add_u32 s46, s44, 0xfff80080
	s_addc_u32 s47, s45, -1
	s_cmp_eq_u32 s55, 28
	s_cselect_b32 s49, s35, s47
	s_cselect_b32 s48, s51, s46
	s_cselect_b32 s47, s37, s54
	s_cselect_b32 s46, s52, s53
	v_lshl_add_u64 v[148:149], s[44:45], 0, v[140:141]
	s_add_i32 m0, s17, 0xc000
	ds_read_b128 v[192:195], v154
	ds_read_b128 v[196:199], v154 offset:1024
	ds_read_b128 v[200:203], v154 offset:2048
	ds_read_b128 v[204:207], v154 offset:3072
	ds_read_b128 v[208:211], v154 offset:4096
	ds_read_b128 v[212:215], v154 offset:5120
	ds_read_b128 v[216:219], v154 offset:6144
	ds_read_b128 v[220:223], v154 offset:7168
	s_add_u32 s98, s44, 0xfff80000
	s_addc_u32 s99, s45, -1
	s_mov_b32 m0, s21
	s_nop 0
	global_load_lds_dwordx4 v140, s[98:99]
	s_mov_b32 m0, s33
	s_nop 0
	global_load_lds_dwordx4 v142, s[98:99]
	s_add_i32 m0, s17, 0xc000
	s_nop 0
	global_load_lds_dwordx4 v[148:149], off
	v_lshl_add_u64 v[148:149], s[44:45], 0, v[142:143]
	s_add_i32 m0, s17, 0xe000
	s_nop 0
	global_load_lds_dwordx4 v[148:149], off
	s_waitcnt vmcnt(8)
	s_waitcnt lgkmcnt(0)
	s_barrier
	s_setprio 1
	s_waitcnt lgkmcnt(0)
	v_mfma_f32_16x16x32_bf16 v[126:129], v[156:159], v[192:195], v[126:129]
	v_mfma_f32_16x16x32_bf16 v[122:125], v[164:167], v[192:195], v[122:125]
	v_mfma_f32_16x16x32_bf16 v[118:121], v[156:159], v[200:203], v[118:121]
	v_mfma_f32_16x16x32_bf16 v[110:113], v[164:167], v[200:203], v[110:113]
	v_mfma_f32_16x16x32_bf16 v[102:105], v[156:159], v[208:211], v[102:105]
	v_mfma_f32_16x16x32_bf16 v[94:97], v[164:167], v[208:211], v[94:97]
	v_mfma_f32_16x16x32_bf16 v[86:89], v[156:159], v[216:219], v[86:89]
	v_mfma_f32_16x16x32_bf16 v[78:81], v[164:167], v[216:219], v[78:81]
	v_mfma_f32_16x16x32_bf16 v[126:129], v[160:163], v[196:199], v[126:129]
	v_mfma_f32_16x16x32_bf16 v[122:125], v[168:171], v[196:199], v[122:125]
	v_mfma_f32_16x16x32_bf16 v[118:121], v[160:163], v[204:207], v[118:121]
	v_mfma_f32_16x16x32_bf16 v[110:113], v[168:171], v[204:207], v[110:113]
	v_mfma_f32_16x16x32_bf16 v[102:105], v[160:163], v[212:215], v[102:105]
	v_mfma_f32_16x16x32_bf16 v[94:97], v[168:171], v[212:215], v[94:97]
	v_mfma_f32_16x16x32_bf16 v[86:89], v[160:163], v[220:223], v[86:89]
	v_mfma_f32_16x16x32_bf16 v[78:81], v[168:171], v[220:223], v[78:81]
	s_setprio 0
	s_setprio 1
	v_mfma_f32_16x16x32_bf16 v[114:117], v[172:175], v[192:195], v[114:117]
	v_mfma_f32_16x16x32_bf16 v[106:109], v[180:183], v[192:195], v[106:109]
	v_mfma_f32_16x16x32_bf16 v[98:101], v[172:175], v[200:203], v[98:101]
	v_mfma_f32_16x16x32_bf16 v[90:93], v[180:183], v[200:203], v[90:93]
	v_mfma_f32_16x16x32_bf16 v[82:85], v[172:175], v[208:211], v[82:85]
	v_mfma_f32_16x16x32_bf16 v[74:77], v[180:183], v[208:211], v[74:77]
	v_mfma_f32_16x16x32_bf16 v[70:73], v[172:175], v[216:219], v[70:73]
	v_mfma_f32_16x16x32_bf16 v[66:69], v[180:183], v[216:219], v[66:69]
	v_mfma_f32_16x16x32_bf16 v[114:117], v[176:179], v[196:199], v[114:117]
	v_mfma_f32_16x16x32_bf16 v[106:109], v[188:191], v[196:199], v[106:109]
	v_mfma_f32_16x16x32_bf16 v[98:101], v[176:179], v[204:207], v[98:101]
	v_mfma_f32_16x16x32_bf16 v[90:93], v[188:191], v[204:207], v[90:93]
	v_mfma_f32_16x16x32_bf16 v[82:85], v[176:179], v[212:215], v[82:85]
	v_mfma_f32_16x16x32_bf16 v[74:77], v[188:191], v[212:215], v[74:77]
	v_mfma_f32_16x16x32_bf16 v[70:73], v[176:179], v[220:223], v[70:73]
	v_mfma_f32_16x16x32_bf16 v[66:69], v[188:191], v[220:223], v[66:69]
	s_setprio 0
	s_barrier
	s_add_i32 s56, s43, s16
	v_lshl_add_u64 v[148:149], s[46:47], 0, v[132:133]
	s_mov_b32 m0, s56
	ds_read_b128 v[192:195], v154 offset:16384
	ds_read_b128 v[196:199], v154 offset:17408
	ds_read_b128 v[200:203], v154 offset:18432
	ds_read_b128 v[204:207], v154 offset:19456
	ds_read_b128 v[208:211], v154 offset:20480
	ds_read_b128 v[212:215], v154 offset:21504
	ds_read_b128 v[216:219], v154 offset:22528
	ds_read_b128 v[220:223], v154 offset:23552
	global_load_lds_dwordx4 v[148:149], off
	s_add_i32 m0, s56, 0x2000
	s_add_u32 s56, s46, 0x80000
	v_lshl_add_u64 v[184:185], s[46:47], 0, v[136:137]
	s_addc_u32 s57, s47, 0
	s_add_i32 s58, s50, s16
	global_load_lds_dwordx4 v[184:185], off
	v_lshl_add_u64 v[224:225], s[56:57], 0, v[132:133]
	s_mov_b32 m0, s58
	v_lshl_add_u64 v[226:227], s[48:49], 0, v[134:135]
	global_load_lds_dwordx4 v[224:225], off
	v_lshl_add_u64 v[224:225], s[56:57], 0, v[136:137]
	s_add_i32 m0, s58, 0x2000
	s_nop 0
	global_load_lds_dwordx4 v[224:225], off
	v_lshl_add_u64 v[224:225], s[48:49], 0, v[130:131]
	s_mov_b32 m0, s17
	s_nop 0
	s_mov_b32 m0, s18
	s_nop 0
	s_waitcnt vmcnt(6)
	s_waitcnt lgkmcnt(0)
	s_barrier
; #define PG8_STAGE(bufoff, gbase, voff) do { _Pragma("unroll") for (int _i = 0; _i < 2; ++_i) \
;         __builtin_amdgcn_global_load_lds((const unsigned*)((const char*)(gbase) + (voff)[_i]), (PG8_LAS unsigned*)(lds + (bufoff) + ldsw + _i * 8192), 16, 0, 0); } while (0)
; #define PG8_LDA(dst, b, h) do { _Pragma("unroll") for (int m = 0; m < 4; ++m) _Pragma("unroll") for (int k = 0; k < 2; ++k) dst[m][k] = *(const PG8_LAS bf16x8*)(lds + PG8_SA(b, h) + aoff + m * 2048 + k * 1024); } while (0)
; #define PG8_LDB(dst, b, h) do { _Pragma("unroll") for (int n = 0; n < 2; ++n) _Pragma("unroll") for (int k = 0; k < 2; ++k) dst[n][k] = *(const PG8_LAS bf16x8*)(lds + PG8_SB(b, h) + boff + n * 2048 + k * 1024); } while (0)
; #define PG8_MMA(ai, bj, At, Bt) do { __builtin_amdgcn_s_setprio(1); _Pragma("unroll") for (int m = 0; m < 4; ++m) _Pragma("unroll") for (int n = 0; n < 2; ++n) _Pragma("unroll") for (int k = 0; k < 2; ++k) \
;         acc[ai][bj][m][n] = __builtin_amdgcn_mfma_f32_16x16x32_bf16(Bt[n][k], At[m][k], acc[ai][bj][m][n], 0, 0, 0); __builtin_amdgcn_s_setprio(0); } while (0)
; #define PG8_WAIT_V(n) asm volatile("s_waitcnt vmcnt(" #n ")" ::: "memory")
; #define PG8_WAIT_L(n) asm volatile("s_waitcnt lgkmcnt(" #n ")" ::: "memory")
; #define PG8_BAR __builtin_amdgcn_s_barrier()
; #define PG8_SCHED __builtin_amdgcn_sched_barrier(0)
; template <class Epi, class Sched, bool ALIGN_EPI = false, bool SP2 = false>
; __device__ __forceinline__ void gemm_phase(PG8_LAS unsigned char* lds, const Gemm g, const Sched& S, const Epi& E) {
;     ...
;             PG8_WAIT_V(8); PG8_WAIT_L(0); PG8_BAR; PG8_MMA(1, 0, At, B0); PG8_MMA(1, 1, At, B1); PG8_BAR; PG8_SCHED;
;             PG8_LDB(B0, 1, 0); PG8_LDB(B1, 1, 1); PG8_SCHED; PG8_LDA(At, 1, 0); PG8_STAGE(PG8_SA(0, 1), a2 + hstep, voffA);
;             PG8_WAIT_V(8); PG8_WAIT_L(0); PG8_BAR; PG8_MMA(0, 0, At, B0); PG8_MMA(0, 1, At, B1); PG8_BAR; PG8_SCHED;
	s_setprio 1
	s_waitcnt lgkmcnt(0)
	v_mfma_f32_16x16x32_bf16 v[62:65], v[156:159], v[192:195], v[62:65]
	v_mfma_f32_16x16x32_bf16 v[58:61], v[164:167], v[192:195], v[58:61]
	v_mfma_f32_16x16x32_bf16 v[54:57], v[156:159], v[200:203], v[54:57]
	v_mfma_f32_16x16x32_bf16 v[46:49], v[164:167], v[200:203], v[46:49]
	v_mfma_f32_16x16x32_bf16 v[38:41], v[156:159], v[208:211], v[38:41]
	v_mfma_f32_16x16x32_bf16 v[30:33], v[164:167], v[208:211], v[30:33]
	v_mfma_f32_16x16x32_bf16 v[22:25], v[156:159], v[216:219], v[22:25]
	v_mfma_f32_16x16x32_bf16 v[14:17], v[164:167], v[216:219], v[14:17]
	v_mfma_f32_16x16x32_bf16 v[62:65], v[160:163], v[196:199], v[62:65]
	v_mfma_f32_16x16x32_bf16 v[58:61], v[168:171], v[196:199], v[58:61]
	v_mfma_f32_16x16x32_bf16 v[54:57], v[160:163], v[204:207], v[54:57]
	v_mfma_f32_16x16x32_bf16 v[46:49], v[168:171], v[204:207], v[46:49]
	v_mfma_f32_16x16x32_bf16 v[38:41], v[160:163], v[212:215], v[38:41]
	v_mfma_f32_16x16x32_bf16 v[30:33], v[168:171], v[212:215], v[30:33]
	v_mfma_f32_16x16x32_bf16 v[22:25], v[160:163], v[220:223], v[22:25]
	v_mfma_f32_16x16x32_bf16 v[14:17], v[168:171], v[220:223], v[14:17]
	s_setprio 0
	s_setprio 1
	v_mfma_f32_16x16x32_bf16 v[50:53], v[172:175], v[192:195], v[50:53]
	v_mfma_f32_16x16x32_bf16 v[42:45], v[180:183], v[192:195], v[42:45]
	v_mfma_f32_16x16x32_bf16 v[34:37], v[172:175], v[200:203], v[34:37]
	v_mfma_f32_16x16x32_bf16 v[26:29], v[180:183], v[200:203], v[26:29]
	v_mfma_f32_16x16x32_bf16 v[18:21], v[172:175], v[208:211], v[18:21]
	v_mfma_f32_16x16x32_bf16 v[10:13], v[180:183], v[208:211], v[10:13]
	v_mfma_f32_16x16x32_bf16 v[6:9], v[172:175], v[216:219], v[6:9]
	v_mfma_f32_16x16x32_bf16 v[2:5], v[180:183], v[216:219], v[2:5]
	v_mfma_f32_16x16x32_bf16 v[50:53], v[176:179], v[196:199], v[50:53]
	v_mfma_f32_16x16x32_bf16 v[42:45], v[188:191], v[196:199], v[42:45]
	v_mfma_f32_16x16x32_bf16 v[34:37], v[176:179], v[204:207], v[34:37]
	v_mfma_f32_16x16x32_bf16 v[26:29], v[188:191], v[204:207], v[26:29]
	v_mfma_f32_16x16x32_bf16 v[18:21], v[176:179], v[212:215], v[18:21]
	v_mfma_f32_16x16x32_bf16 v[10:13], v[188:191], v[212:215], v[10:13]
	v_mfma_f32_16x16x32_bf16 v[6:9], v[176:179], v[220:223], v[6:9]
	v_mfma_f32_16x16x32_bf16 v[2:5], v[188:191], v[220:223], v[2:5]
	s_setprio 0
	s_barrier
	s_add_i32 s56, 0, 0x18000
	v_add_u32_e32 v155, s56, v151
	s_add_i32 s57, 0, 0x1c000
	ds_read_b128 v[156:159], v155
	ds_read_b128 v[160:163], v155 offset:1024
	ds_read_b128 v[164:167], v155 offset:2048
	ds_read_b128 v[168:171], v155 offset:3072
	v_add_u32_e32 v155, s57, v151
	ds_read_b128 v[172:175], v155
	ds_read_b128 v[176:179], v155 offset:1024
	ds_read_b128 v[180:183], v155 offset:2048
	ds_read_b128 v[188:191], v155 offset:3072
	s_add_u32 s48, s48, 0x80000
	s_addc_u32 s49, s49, 0
	s_mov_b32 m0, s19
	v_lshl_add_u64 v[228:229], s[48:49], 0, v[130:131]
	ds_read_b128 v[192:195], v154 offset:32768
	ds_read_b128 v[196:199], v154 offset:33792
	ds_read_b128 v[200:203], v154 offset:34816
	ds_read_b128 v[204:207], v154 offset:35840
	ds_read_b128 v[208:211], v154 offset:36864
	ds_read_b128 v[212:215], v154 offset:37888
	ds_read_b128 v[216:219], v154 offset:38912
	ds_read_b128 v[220:223], v154 offset:39936
	s_add_u32 s98, s48, 0xfff80000
	s_addc_u32 s99, s49, -1
	s_mov_b32 m0, s17
	s_nop 0
	global_load_lds_dwordx4 v130, s[98:99]
	s_mov_b32 m0, s18
	s_nop 0
	global_load_lds_dwordx4 v134, s[98:99]
	s_mov_b32 m0, s19
	s_nop 0
	global_load_lds_dwordx4 v[228:229], off
	v_lshl_add_u64 v[228:229], s[48:49], 0, v[134:135]
	s_mov_b32 m0, s20
	s_nop 0
	global_load_lds_dwordx4 v[228:229], off
	s_waitcnt vmcnt(8)
	s_waitcnt lgkmcnt(0)
	s_barrier
	s_setprio 1
	s_waitcnt lgkmcnt(0)
	v_mfma_f32_16x16x32_bf16 v[126:129], v[156:159], v[192:195], v[126:129]
	v_mfma_f32_16x16x32_bf16 v[122:125], v[164:167], v[192:195], v[122:125]
	v_mfma_f32_16x16x32_bf16 v[118:121], v[156:159], v[200:203], v[118:121]
	v_mfma_f32_16x16x32_bf16 v[110:113], v[164:167], v[200:203], v[110:113]
	v_mfma_f32_16x16x32_bf16 v[102:105], v[156:159], v[208:211], v[102:105]
	v_mfma_f32_16x16x32_bf16 v[94:97], v[164:167], v[208:211], v[94:97]
	v_mfma_f32_16x16x32_bf16 v[86:89], v[156:159], v[216:219], v[86:89]
	v_mfma_f32_16x16x32_bf16 v[78:81], v[164:167], v[216:219], v[78:81]
	v_mfma_f32_16x16x32_bf16 v[126:129], v[160:163], v[196:199], v[126:129]
	v_mfma_f32_16x16x32_bf16 v[122:125], v[168:171], v[196:199], v[122:125]
	v_mfma_f32_16x16x32_bf16 v[118:121], v[160:163], v[204:207], v[118:121]
	v_mfma_f32_16x16x32_bf16 v[110:113], v[168:171], v[204:207], v[110:113]
	v_mfma_f32_16x16x32_bf16 v[102:105], v[160:163], v[212:215], v[102:105]
	v_mfma_f32_16x16x32_bf16 v[94:97], v[168:171], v[212:215], v[94:97]
	v_mfma_f32_16x16x32_bf16 v[86:89], v[160:163], v[220:223], v[86:89]
	v_mfma_f32_16x16x32_bf16 v[78:81], v[168:171], v[220:223], v[78:81]
	s_setprio 0
	s_setprio 1
	v_mfma_f32_16x16x32_bf16 v[114:117], v[172:175], v[192:195], v[114:117]
	v_mfma_f32_16x16x32_bf16 v[106:109], v[180:183], v[192:195], v[106:109]
	v_mfma_f32_16x16x32_bf16 v[98:101], v[172:175], v[200:203], v[98:101]
	v_mfma_f32_16x16x32_bf16 v[90:93], v[180:183], v[200:203], v[90:93]
	v_mfma_f32_16x16x32_bf16 v[82:85], v[172:175], v[208:211], v[82:85]
	v_mfma_f32_16x16x32_bf16 v[74:77], v[180:183], v[208:211], v[74:77]
	v_mfma_f32_16x16x32_bf16 v[70:73], v[172:175], v[216:219], v[70:73]
	v_mfma_f32_16x16x32_bf16 v[66:69], v[180:183], v[216:219], v[66:69]
	v_mfma_f32_16x16x32_bf16 v[114:117], v[176:179], v[196:199], v[114:117]
	v_mfma_f32_16x16x32_bf16 v[106:109], v[188:191], v[196:199], v[106:109]
	v_mfma_f32_16x16x32_bf16 v[98:101], v[176:179], v[204:207], v[98:101]
	v_mfma_f32_16x16x32_bf16 v[90:93], v[188:191], v[204:207], v[90:93]
	v_mfma_f32_16x16x32_bf16 v[82:85], v[176:179], v[212:215], v[82:85]
	v_mfma_f32_16x16x32_bf16 v[74:77], v[188:191], v[212:215], v[74:77]
	v_mfma_f32_16x16x32_bf16 v[70:73], v[176:179], v[220:223], v[70:73]
	v_mfma_f32_16x16x32_bf16 v[66:69], v[188:191], v[220:223], v[66:69]
	s_setprio 0
	s_barrier
; #define PG8_STAGE(bufoff, gbase, voff) do { _Pragma("unroll") for (int _i = 0; _i < 2; ++_i) \
;         __builtin_amdgcn_global_load_lds((const unsigned*)((const char*)(gbase) + (voff)[_i]), (PG8_LAS unsigned*)(lds + (bufoff) + ldsw + _i * 8192), 16, 0, 0); } while (0)
; #define PG8_LDA(dst, b, h) do { _Pragma("unroll") for (int m = 0; m < 4; ++m) _Pragma("unroll") for (int k = 0; k < 2; ++k) dst[m][k] = *(const PG8_LAS bf16x8*)(lds + PG8_SA(b, h) + aoff + m * 2048 + k * 1024); } while (0)
; #define PG8_MMA(ai, bj, At, Bt) do { __builtin_amdgcn_s_setprio(1); _Pragma("unroll") for (int m = 0; m < 4; ++m) _Pragma("unroll") for (int n = 0; n < 2; ++n) _Pragma("unroll") for (int k = 0; k < 2; ++k) \
;         acc[ai][bj][m][n] = __builtin_amdgcn_mfma_f32_16x16x32_bf16(Bt[n][k], At[m][k], acc[ai][bj][m][n], 0, 0, 0); __builtin_amdgcn_s_setprio(0); } while (0)
; #define PG8_WAIT_V(n) asm volatile("s_waitcnt vmcnt(" #n ")" ::: "memory")
; #define PG8_WAIT_L(n) asm volatile("s_waitcnt lgkmcnt(" #n ")" ::: "memory")
; #define PG8_BAR __builtin_amdgcn_s_barrier()
; #define PG8_SCHED __builtin_amdgcn_sched_barrier(0)
; template <class Epi, class Sched, bool ALIGN_EPI = false, bool SP2 = false>
; __device__ __forceinline__ void gemm_phase(PG8_LAS unsigned char* lds, const Gemm g, const Sched& S, const Epi& E) {
;     ...
;         for (int t = 0; t < nt; t += 2) {
;             const bool last = (t == nt - 2);
;             const char* a1 = cA + (size_t)(t + 1) * kstep;
;             const char* a2 = last ? nA : cA + (size_t)(t + 2) * kstep; const char* b2 = last ? nB : cB + (size_t)(t + 2) * kstep;
;     ...
;             PG8_LDA(At, 1, 1); PG8_STAGE(PG8_SB(1, 0), b3, voffB); PG8_STAGE(PG8_SB(1, 1), b3 + hstep, voffB); PG8_STAGE(PG8_SA(1, 0), a3, voffA);
;             PG8_WAIT_V(8); PG8_WAIT_L(0); PG8_BAR; PG8_MMA(1, 0, At, B0); PG8_MMA(1, 1, At, B1); PG8_BAR; PG8_SCHED;
	s_add_i32 s48, s56, s16
	v_lshl_add_u64 v[148:149], v[148:149], 0, s[26:27]
	s_mov_b32 m0, s48
	ds_read_b128 v[192:195], v154 offset:49152
	ds_read_b128 v[196:199], v154 offset:50176
	ds_read_b128 v[200:203], v154 offset:51200
	ds_read_b128 v[204:207], v154 offset:52224
	ds_read_b128 v[208:211], v154 offset:53248
	ds_read_b128 v[212:215], v154 offset:54272
	ds_read_b128 v[216:219], v154 offset:55296
	ds_read_b128 v[220:223], v154 offset:56320
	global_load_lds_dwordx4 v[148:149], off
	s_add_i32 m0, s48, 0x2000
	s_add_u32 s46, s46, 0x80080
	v_lshl_add_u64 v[148:149], v[184:185], 0, s[26:27]
	s_addc_u32 s47, s47, 0
	s_add_i32 s48, s57, s16
	global_load_lds_dwordx4 v[148:149], off
	v_lshl_add_u64 v[148:149], s[46:47], 0, v[132:133]
	s_mov_b32 m0, s48
	s_nop 0
	global_load_lds_dwordx4 v[148:149], off
	v_lshl_add_u64 v[148:149], s[46:47], 0, v[136:137]
	s_add_i32 m0, s48, 0x2000
	s_nop 0
	global_load_lds_dwordx4 v[148:149], off
	v_lshl_add_u64 v[148:149], v[224:225], 0, s[26:27]
	s_mov_b32 m0, s21
	s_nop 0
	v_lshl_add_u64 v[148:149], v[226:227], 0, s[26:27]
	s_mov_b32 m0, s33
	s_nop 0
	s_waitcnt vmcnt(6)
	s_waitcnt lgkmcnt(0)
	s_barrier
	s_setprio 1
	s_waitcnt lgkmcnt(0)
	v_mfma_f32_16x16x32_bf16 v[62:65], v[156:159], v[192:195], v[62:65]
	v_mfma_f32_16x16x32_bf16 v[58:61], v[164:167], v[192:195], v[58:61]
	v_mfma_f32_16x16x32_bf16 v[54:57], v[156:159], v[200:203], v[54:57]
	v_mfma_f32_16x16x32_bf16 v[46:49], v[164:167], v[200:203], v[46:49]
	v_mfma_f32_16x16x32_bf16 v[38:41], v[156:159], v[208:211], v[38:41]
	v_mfma_f32_16x16x32_bf16 v[30:33], v[164:167], v[208:211], v[30:33]
	v_mfma_f32_16x16x32_bf16 v[22:25], v[156:159], v[216:219], v[22:25]
	v_mfma_f32_16x16x32_bf16 v[14:17], v[164:167], v[216:219], v[14:17]
	v_mfma_f32_16x16x32_bf16 v[62:65], v[160:163], v[196:199], v[62:65]
	v_mfma_f32_16x16x32_bf16 v[58:61], v[168:171], v[196:199], v[58:61]
	v_mfma_f32_16x16x32_bf16 v[54:57], v[160:163], v[204:207], v[54:57]
	v_mfma_f32_16x16x32_bf16 v[46:49], v[168:171], v[204:207], v[46:49]
	v_mfma_f32_16x16x32_bf16 v[38:41], v[160:163], v[212:215], v[38:41]
	v_mfma_f32_16x16x32_bf16 v[30:33], v[168:171], v[212:215], v[30:33]
	v_mfma_f32_16x16x32_bf16 v[22:25], v[160:163], v[220:223], v[22:25]
	v_mfma_f32_16x16x32_bf16 v[14:17], v[168:171], v[220:223], v[14:17]
	s_setprio 0
	s_setprio 1
	v_mfma_f32_16x16x32_bf16 v[50:53], v[172:175], v[192:195], v[50:53]
	v_mfma_f32_16x16x32_bf16 v[42:45], v[180:183], v[192:195], v[42:45]
	v_mfma_f32_16x16x32_bf16 v[34:37], v[172:175], v[200:203], v[34:37]
	v_mfma_f32_16x16x32_bf16 v[26:29], v[180:183], v[200:203], v[26:29]
	v_mfma_f32_16x16x32_bf16 v[18:21], v[172:175], v[208:211], v[18:21]
	v_mfma_f32_16x16x32_bf16 v[10:13], v[180:183], v[208:211], v[10:13]
	v_mfma_f32_16x16x32_bf16 v[6:9], v[172:175], v[216:219], v[6:9]
	v_mfma_f32_16x16x32_bf16 v[2:5], v[180:183], v[216:219], v[2:5]
	v_mfma_f32_16x16x32_bf16 v[50:53], v[176:179], v[196:199], v[50:53]
	v_mfma_f32_16x16x32_bf16 v[42:45], v[188:191], v[196:199], v[42:45]
	v_mfma_f32_16x16x32_bf16 v[34:37], v[176:179], v[204:207], v[34:37]
	v_mfma_f32_16x16x32_bf16 v[26:29], v[188:191], v[204:207], v[26:29]
	v_mfma_f32_16x16x32_bf16 v[18:21], v[176:179], v[212:215], v[18:21]
	v_mfma_f32_16x16x32_bf16 v[10:13], v[188:191], v[212:215], v[10:13]
	v_mfma_f32_16x16x32_bf16 v[6:9], v[176:179], v[220:223], v[6:9]
	v_mfma_f32_16x16x32_bf16 v[2:5], v[188:191], v[220:223], v[2:5]
	s_setprio 0
	s_barrier
	s_add_i32 s55, s55, 2
	s_add_u32 s44, s44, 0x100
	s_addc_u32 s45, s45, 0
	s_add_u32 s53, s53, 0x100
	s_addc_u32 s54, s54, 0
	s_cmp_gt_u32 s55, 29
	s_cbranch_scc0 .LBB0_592
	s_and_b64 vcc, exec, s[28:29]
	s_cbranch_vccz .LBB0_595
	s_barrier

; #define PG8_STAGE(bufoff, gbase, voff) do { _Pragma("unroll") for (int _i = 0; _i < 2; ++_i) \
;         __builtin_amdgcn_global_load_lds((const unsigned*)((const char*)(gbase) + (voff)[_i]), (PG8_LAS unsigned*)(lds + (bufoff) + ldsw + _i * 8192), 16, 0, 0); } while (0)
; #define PG8_LDA(dst, b, h) do { _Pragma("unroll") for (int m = 0; m < 4; ++m) _Pragma("unroll") for (int k = 0; k < 2; ++k) dst[m][k] = *(const PG8_LAS bf16x8*)(lds + PG8_SA(b, h) + aoff + m * 2048 + k * 1024); } while (0)
; #define PG8_LDB(dst, b, h) do { _Pragma("unroll") for (int n = 0; n < 2; ++n) _Pragma("unroll") for (int k = 0; k < 2; ++k) dst[n][k] = *(const PG8_LAS bf16x8*)(lds + PG8_SB(b, h) + boff + n * 2048 + k * 1024); } while (0)
; #define PG8_MMA(ai, bj, At, Bt) do { __builtin_amdgcn_s_setprio(1); _Pragma("unroll") for (int m = 0; m < 4; ++m) _Pragma("unroll") for (int n = 0; n < 2; ++n) _Pragma("unroll") for (int k = 0; k < 2; ++k) \
;         acc[ai][bj][m][n] = __builtin_amdgcn_mfma_f32_16x16x32_bf16(Bt[n][k], At[m][k], acc[ai][bj][m][n], 0, 0, 0); __builtin_amdgcn_s_setprio(0); } while (0)
; #define PG8_WAIT_V(n) asm volatile("s_waitcnt vmcnt(" #n ")" ::: "memory")
; #define PG8_WAIT_L(n) asm volatile("s_waitcnt lgkmcnt(" #n ")" ::: "memory")
; #define PG8_BAR __builtin_amdgcn_s_barrier()
; #define PG8_SCHED __builtin_amdgcn_sched_barrier(0)
; template <class Epi, class Sched, bool ALIGN_EPI = false, bool SP2 = false>
; __device__ __forceinline__ void gemm_phase(PG8_LAS unsigned char* lds, const Gemm g, const Sched& S, const Epi& E) {
;     ...
;             PG8_LDB(B0, 0, 0); PG8_LDB(B1, 0, 1); PG8_SCHED; PG8_LDA(At, 0, 0); PG8_STAGE(PG8_SA(1, 1), a1 + hstep, voffA);
;             PG8_WAIT_V(8); PG8_WAIT_L(0); PG8_BAR; PG8_MMA(0, 0, At, B0); PG8_MMA(0, 1, At, B1); PG8_BAR; PG8_SCHED;
;             PG8_LDA(At, 0, 1); PG8_STAGE(PG8_SB(0, 0), b2, voffB); PG8_STAGE(PG8_SB(0, 1), b2 + hstep, voffB); PG8_STAGE(PG8_SA(0, 0), a2, voffA);
;             PG8_WAIT_V(8); PG8_WAIT_L(0); PG8_BAR; PG8_MMA(1, 0, At, B0); PG8_MMA(1, 1, At, B1); PG8_BAR; PG8_SCHED;
.LBB0_650:
	ds_read_b128 v[154:157], v150
	ds_read_b128 v[158:161], v150 offset:1024
	ds_read_b128 v[162:165], v150 offset:2048
	ds_read_b128 v[166:169], v150 offset:3072
	ds_read_b128 v[170:173], v151
	ds_read_b128 v[174:177], v151 offset:1024
	ds_read_b128 v[178:181], v151 offset:2048
	ds_read_b128 v[182:185], v151 offset:3072
	s_add_u32 s44, s42, 0xfff80080
	s_addc_u32 s45, s43, -1
	s_cmp_eq_u32 s59, 28
	s_cselect_b32 s47, s35, s45
	s_cselect_b32 s46, s55, s44
	s_cselect_b32 s45, s31, s58
	s_cselect_b32 s44, s56, s57
	v_lshl_add_u64 v[146:147], s[42:43], 0, v[140:141]
	s_add_i32 m0, s17, 0xc000
	ds_read_b128 v[188:191], v152
	ds_read_b128 v[192:195], v152 offset:1024
	ds_read_b128 v[196:199], v152 offset:2048
	ds_read_b128 v[200:203], v152 offset:3072
	ds_read_b128 v[204:207], v152 offset:4096
	ds_read_b128 v[208:211], v152 offset:5120
	ds_read_b128 v[212:215], v152 offset:6144
	ds_read_b128 v[216:219], v152 offset:7168
	s_add_u32 s98, s42, 0xfff80000
	s_addc_u32 s99, s43, -1
	s_mov_b32 m0, s21
	s_nop 0
	global_load_lds_dwordx4 v140, s[98:99]
	s_mov_b32 m0, s33
	s_nop 0
	global_load_lds_dwordx4 v142, s[98:99]
	s_add_i32 m0, s17, 0xc000
	s_nop 0
	global_load_lds_dwordx4 v[146:147], off
	v_lshl_add_u64 v[146:147], s[42:43], 0, v[142:143]
	s_add_i32 m0, s17, 0xe000
	s_nop 0
	global_load_lds_dwordx4 v[146:147], off
	s_waitcnt vmcnt(8)
	s_waitcnt lgkmcnt(0)
	s_barrier
	s_setprio 1
	s_waitcnt lgkmcnt(0)
	v_mfma_f32_16x16x32_bf16 v[126:129], v[154:157], v[188:191], v[126:129]
	v_mfma_f32_16x16x32_bf16 v[122:125], v[162:165], v[188:191], v[122:125]
	v_mfma_f32_16x16x32_bf16 v[118:121], v[154:157], v[196:199], v[118:121]
	v_mfma_f32_16x16x32_bf16 v[110:113], v[162:165], v[196:199], v[110:113]
	v_mfma_f32_16x16x32_bf16 v[102:105], v[154:157], v[204:207], v[102:105]
	v_mfma_f32_16x16x32_bf16 v[94:97], v[162:165], v[204:207], v[94:97]
	v_mfma_f32_16x16x32_bf16 v[86:89], v[154:157], v[212:215], v[86:89]
	v_mfma_f32_16x16x32_bf16 v[78:81], v[162:165], v[212:215], v[78:81]
	v_mfma_f32_16x16x32_bf16 v[126:129], v[158:161], v[192:195], v[126:129]
	v_mfma_f32_16x16x32_bf16 v[122:125], v[166:169], v[192:195], v[122:125]
	v_mfma_f32_16x16x32_bf16 v[118:121], v[158:161], v[200:203], v[118:121]
	v_mfma_f32_16x16x32_bf16 v[110:113], v[166:169], v[200:203], v[110:113]
	v_mfma_f32_16x16x32_bf16 v[102:105], v[158:161], v[208:211], v[102:105]
	v_mfma_f32_16x16x32_bf16 v[94:97], v[166:169], v[208:211], v[94:97]
	v_mfma_f32_16x16x32_bf16 v[86:89], v[158:161], v[216:219], v[86:89]
	v_mfma_f32_16x16x32_bf16 v[78:81], v[166:169], v[216:219], v[78:81]
	s_setprio 0
	s_setprio 1
	v_mfma_f32_16x16x32_bf16 v[114:117], v[170:173], v[188:191], v[114:117]
	v_mfma_f32_16x16x32_bf16 v[106:109], v[178:181], v[188:191], v[106:109]
	v_mfma_f32_16x16x32_bf16 v[98:101], v[170:173], v[196:199], v[98:101]
	v_mfma_f32_16x16x32_bf16 v[90:93], v[178:181], v[196:199], v[90:93]
	v_mfma_f32_16x16x32_bf16 v[82:85], v[170:173], v[204:207], v[82:85]
	v_mfma_f32_16x16x32_bf16 v[74:77], v[178:181], v[204:207], v[74:77]
	v_mfma_f32_16x16x32_bf16 v[70:73], v[170:173], v[212:215], v[70:73]
	v_mfma_f32_16x16x32_bf16 v[66:69], v[178:181], v[212:215], v[66:69]
	v_mfma_f32_16x16x32_bf16 v[114:117], v[174:177], v[192:195], v[114:117]
	v_mfma_f32_16x16x32_bf16 v[106:109], v[182:185], v[192:195], v[106:109]
	v_mfma_f32_16x16x32_bf16 v[98:101], v[174:177], v[200:203], v[98:101]
	v_mfma_f32_16x16x32_bf16 v[90:93], v[182:185], v[200:203], v[90:93]
	v_mfma_f32_16x16x32_bf16 v[82:85], v[174:177], v[208:211], v[82:85]
	v_mfma_f32_16x16x32_bf16 v[74:77], v[182:185], v[208:211], v[74:77]
	v_mfma_f32_16x16x32_bf16 v[70:73], v[174:177], v[216:219], v[70:73]
	v_mfma_f32_16x16x32_bf16 v[66:69], v[182:185], v[216:219], v[66:69]
	s_setprio 0
	s_barrier
	s_add_i32 s60, s48, s16
	v_lshl_add_u64 v[146:147], s[44:45], 0, v[132:133]
	s_mov_b32 m0, s60
	ds_read_b128 v[188:191], v152 offset:16384
	ds_read_b128 v[192:195], v152 offset:17408
	ds_read_b128 v[196:199], v152 offset:18432
	ds_read_b128 v[200:203], v152 offset:19456
	ds_read_b128 v[204:207], v152 offset:20480
	ds_read_b128 v[208:211], v152 offset:21504
	ds_read_b128 v[212:215], v152 offset:22528
	ds_read_b128 v[216:219], v152 offset:23552
	global_load_lds_dwordx4 v[146:147], off
	s_add_i32 m0, s60, 0x2000
	s_add_u32 s60, s44, 0x80000
	v_lshl_add_u64 v[220:221], s[44:45], 0, v[136:137]
	s_addc_u32 s61, s45, 0
	s_add_i32 s62, s49, s16
	global_load_lds_dwordx4 v[220:221], off
	v_lshl_add_u64 v[222:223], s[60:61], 0, v[132:133]
	s_mov_b32 m0, s62
	v_lshl_add_u64 v[224:225], s[46:47], 0, v[134:135]
	global_load_lds_dwordx4 v[222:223], off
	v_lshl_add_u64 v[222:223], s[60:61], 0, v[136:137]
	s_add_i32 m0, s62, 0x2000
	s_nop 0
	global_load_lds_dwordx4 v[222:223], off
	v_lshl_add_u64 v[222:223], s[46:47], 0, v[130:131]
	s_mov_b32 m0, s17
	s_nop 0
	s_mov_b32 m0, s18
	s_nop 0
	s_waitcnt vmcnt(6)
	s_waitcnt lgkmcnt(0)
	s_barrier
; #define PG8_STAGE(bufoff, gbase, voff) do { _Pragma("unroll") for (int _i = 0; _i < 2; ++_i) \
;         __builtin_amdgcn_global_load_lds((const unsigned*)((const char*)(gbase) + (voff)[_i]), (PG8_LAS unsigned*)(lds + (bufoff) + ldsw + _i * 8192), 16, 0, 0); } while (0)
; #define PG8_LDA(dst, b, h) do { _Pragma("unroll") for (int m = 0; m < 4; ++m) _Pragma("unroll") for (int k = 0; k < 2; ++k) dst[m][k] = *(const PG8_LAS bf16x8*)(lds + PG8_SA(b, h) + aoff + m * 2048 + k * 1024); } while (0)
; #define PG8_LDB(dst, b, h) do { _Pragma("unroll") for (int n = 0; n < 2; ++n) _Pragma("unroll") for (int k = 0; k < 2; ++k) dst[n][k] = *(const PG8_LAS bf16x8*)(lds + PG8_SB(b, h) + boff + n * 2048 + k * 1024); } while (0)
; #define PG8_MMA(ai, bj, At, Bt) do { __builtin_amdgcn_s_setprio(1); _Pragma("unroll") for (int m = 0; m < 4; ++m) _Pragma("unroll") for (int n = 0; n < 2; ++n) _Pragma("unroll") for (int k = 0; k < 2; ++k) \
;         acc[ai][bj][m][n] = __builtin_amdgcn_mfma_f32_16x16x32_bf16(Bt[n][k], At[m][k], acc[ai][bj][m][n], 0, 0, 0); __builtin_amdgcn_s_setprio(0); } while (0)
; #define PG8_WAIT_V(n) asm volatile("s_waitcnt vmcnt(" #n ")" ::: "memory")
; #define PG8_WAIT_L(n) asm volatile("s_waitcnt lgkmcnt(" #n ")" ::: "memory")
; #define PG8_BAR __builtin_amdgcn_s_barrier()
; #define PG8_SCHED __builtin_amdgcn_sched_barrier(0)
; template <class Epi, class Sched, bool ALIGN_EPI = false, bool SP2 = false>
; __device__ __forceinline__ void gemm_phase(PG8_LAS unsigned char* lds, const Gemm g, const Sched& S, const Epi& E) {
;     ...
;             PG8_WAIT_V(8); PG8_WAIT_L(0); PG8_BAR; PG8_MMA(1, 0, At, B0); PG8_MMA(1, 1, At, B1); PG8_BAR; PG8_SCHED;
;             PG8_LDB(B0, 1, 0); PG8_LDB(B1, 1, 1); PG8_SCHED; PG8_LDA(At, 1, 0); PG8_STAGE(PG8_SA(0, 1), a2 + hstep, voffA);
;             PG8_WAIT_V(8); PG8_WAIT_L(0); PG8_BAR; PG8_MMA(0, 0, At, B0); PG8_MMA(0, 1, At, B1); PG8_BAR; PG8_SCHED;
	s_setprio 1
	s_waitcnt lgkmcnt(0)
	v_mfma_f32_16x16x32_bf16 v[62:65], v[154:157], v[188:191], v[62:65]
	v_mfma_f32_16x16x32_bf16 v[58:61], v[162:165], v[188:191], v[58:61]
	v_mfma_f32_16x16x32_bf16 v[54:57], v[154:157], v[196:199], v[54:57]
	v_mfma_f32_16x16x32_bf16 v[46:49], v[162:165], v[196:199], v[46:49]
	v_mfma_f32_16x16x32_bf16 v[38:41], v[154:157], v[204:207], v[38:41]
	v_mfma_f32_16x16x32_bf16 v[30:33], v[162:165], v[204:207], v[30:33]
	v_mfma_f32_16x16x32_bf16 v[22:25], v[154:157], v[212:215], v[22:25]
	v_mfma_f32_16x16x32_bf16 v[14:17], v[162:165], v[212:215], v[14:17]
	v_mfma_f32_16x16x32_bf16 v[62:65], v[158:161], v[192:195], v[62:65]
	v_mfma_f32_16x16x32_bf16 v[58:61], v[166:169], v[192:195], v[58:61]
	v_mfma_f32_16x16x32_bf16 v[54:57], v[158:161], v[200:203], v[54:57]
	v_mfma_f32_16x16x32_bf16 v[46:49], v[166:169], v[200:203], v[46:49]
	v_mfma_f32_16x16x32_bf16 v[38:41], v[158:161], v[208:211], v[38:41]
	v_mfma_f32_16x16x32_bf16 v[30:33], v[166:169], v[208:211], v[30:33]
	v_mfma_f32_16x16x32_bf16 v[22:25], v[158:161], v[216:219], v[22:25]
	v_mfma_f32_16x16x32_bf16 v[14:17], v[166:169], v[216:219], v[14:17]
	s_setprio 0
	s_setprio 1
	v_mfma_f32_16x16x32_bf16 v[50:53], v[170:173], v[188:191], v[50:53]
	v_mfma_f32_16x16x32_bf16 v[42:45], v[178:181], v[188:191], v[42:45]
	v_mfma_f32_16x16x32_bf16 v[34:37], v[170:173], v[196:199], v[34:37]
	v_mfma_f32_16x16x32_bf16 v[26:29], v[178:181], v[196:199], v[26:29]
	v_mfma_f32_16x16x32_bf16 v[18:21], v[170:173], v[204:207], v[18:21]
	v_mfma_f32_16x16x32_bf16 v[10:13], v[178:181], v[204:207], v[10:13]
	v_mfma_f32_16x16x32_bf16 v[6:9], v[170:173], v[212:215], v[6:9]
	v_mfma_f32_16x16x32_bf16 v[2:5], v[178:181], v[212:215], v[2:5]
	v_mfma_f32_16x16x32_bf16 v[50:53], v[174:177], v[192:195], v[50:53]
	v_mfma_f32_16x16x32_bf16 v[42:45], v[182:185], v[192:195], v[42:45]
	v_mfma_f32_16x16x32_bf16 v[34:37], v[174:177], v[200:203], v[34:37]
	v_mfma_f32_16x16x32_bf16 v[26:29], v[182:185], v[200:203], v[26:29]
	v_mfma_f32_16x16x32_bf16 v[18:21], v[174:177], v[208:211], v[18:21]
	v_mfma_f32_16x16x32_bf16 v[10:13], v[182:185], v[208:211], v[10:13]
	v_mfma_f32_16x16x32_bf16 v[6:9], v[174:177], v[216:219], v[6:9]
	v_mfma_f32_16x16x32_bf16 v[2:5], v[182:185], v[216:219], v[2:5]
	s_setprio 0
	s_barrier
	s_add_i32 s60, 0, 0x18000
	v_add_u32_e32 v153, s60, v149
	s_add_i32 s61, 0, 0x1c000
	ds_read_b128 v[154:157], v153
	ds_read_b128 v[158:161], v153 offset:1024
	ds_read_b128 v[162:165], v153 offset:2048
	ds_read_b128 v[166:169], v153 offset:3072
	v_add_u32_e32 v153, s61, v149
	ds_read_b128 v[170:173], v153
	ds_read_b128 v[174:177], v153 offset:1024
	ds_read_b128 v[178:181], v153 offset:2048
	ds_read_b128 v[182:185], v153 offset:3072
	s_add_u32 s46, s46, 0x80000
	s_addc_u32 s47, s47, 0
	s_mov_b32 m0, s19
	v_lshl_add_u64 v[226:227], s[46:47], 0, v[130:131]
	ds_read_b128 v[188:191], v152 offset:32768
	ds_read_b128 v[192:195], v152 offset:33792
	ds_read_b128 v[196:199], v152 offset:34816
	ds_read_b128 v[200:203], v152 offset:35840
	ds_read_b128 v[204:207], v152 offset:36864
	ds_read_b128 v[208:211], v152 offset:37888
	ds_read_b128 v[212:215], v152 offset:38912
	ds_read_b128 v[216:219], v152 offset:39936
	s_add_u32 s98, s46, 0xfff80000
	s_addc_u32 s99, s47, -1
	s_mov_b32 m0, s17
	s_nop 0
	global_load_lds_dwordx4 v130, s[98:99]
	s_mov_b32 m0, s18
	s_nop 0
	global_load_lds_dwordx4 v134, s[98:99]
	s_mov_b32 m0, s19
	s_nop 0
	global_load_lds_dwordx4 v[226:227], off
	v_lshl_add_u64 v[226:227], s[46:47], 0, v[134:135]
	s_mov_b32 m0, s20
	s_nop 0
	global_load_lds_dwordx4 v[226:227], off
	s_waitcnt vmcnt(8)
	s_waitcnt lgkmcnt(0)
	s_barrier
	s_setprio 1
	s_waitcnt lgkmcnt(0)
	v_mfma_f32_16x16x32_bf16 v[126:129], v[154:157], v[188:191], v[126:129]
	v_mfma_f32_16x16x32_bf16 v[122:125], v[162:165], v[188:191], v[122:125]
	v_mfma_f32_16x16x32_bf16 v[118:121], v[154:157], v[196:199], v[118:121]
	v_mfma_f32_16x16x32_bf16 v[110:113], v[162:165], v[196:199], v[110:113]
	v_mfma_f32_16x16x32_bf16 v[102:105], v[154:157], v[204:207], v[102:105]
	v_mfma_f32_16x16x32_bf16 v[94:97], v[162:165], v[204:207], v[94:97]
	v_mfma_f32_16x16x32_bf16 v[86:89], v[154:157], v[212:215], v[86:89]
	v_mfma_f32_16x16x32_bf16 v[78:81], v[162:165], v[212:215], v[78:81]
	v_mfma_f32_16x16x32_bf16 v[126:129], v[158:161], v[192:195], v[126:129]
	v_mfma_f32_16x16x32_bf16 v[122:125], v[166:169], v[192:195], v[122:125]
	v_mfma_f32_16x16x32_bf16 v[118:121], v[158:161], v[200:203], v[118:121]
	v_mfma_f32_16x16x32_bf16 v[110:113], v[166:169], v[200:203], v[110:113]
	v_mfma_f32_16x16x32_bf16 v[102:105], v[158:161], v[208:211], v[102:105]
	v_mfma_f32_16x16x32_bf16 v[94:97], v[166:169], v[208:211], v[94:97]
	v_mfma_f32_16x16x32_bf16 v[86:89], v[158:161], v[216:219], v[86:89]
	v_mfma_f32_16x16x32_bf16 v[78:81], v[166:169], v[216:219], v[78:81]
	s_setprio 0
	s_setprio 1
	v_mfma_f32_16x16x32_bf16 v[114:117], v[170:173], v[188:191], v[114:117]
	v_mfma_f32_16x16x32_bf16 v[106:109], v[178:181], v[188:191], v[106:109]
	v_mfma_f32_16x16x32_bf16 v[98:101], v[170:173], v[196:199], v[98:101]
	v_mfma_f32_16x16x32_bf16 v[90:93], v[178:181], v[196:199], v[90:93]
	v_mfma_f32_16x16x32_bf16 v[82:85], v[170:173], v[204:207], v[82:85]
	v_mfma_f32_16x16x32_bf16 v[74:77], v[178:181], v[204:207], v[74:77]
	v_mfma_f32_16x16x32_bf16 v[70:73], v[170:173], v[212:215], v[70:73]
	v_mfma_f32_16x16x32_bf16 v[66:69], v[178:181], v[212:215], v[66:69]
	v_mfma_f32_16x16x32_bf16 v[114:117], v[174:177], v[192:195], v[114:117]
	v_mfma_f32_16x16x32_bf16 v[106:109], v[182:185], v[192:195], v[106:109]
	v_mfma_f32_16x16x32_bf16 v[98:101], v[174:177], v[200:203], v[98:101]
	v_mfma_f32_16x16x32_bf16 v[90:93], v[182:185], v[200:203], v[90:93]
	v_mfma_f32_16x16x32_bf16 v[82:85], v[174:177], v[208:211], v[82:85]
	v_mfma_f32_16x16x32_bf16 v[74:77], v[182:185], v[208:211], v[74:77]
	v_mfma_f32_16x16x32_bf16 v[70:73], v[174:177], v[216:219], v[70:73]
	v_mfma_f32_16x16x32_bf16 v[66:69], v[182:185], v[216:219], v[66:69]
	s_setprio 0
	s_barrier
; #define PG8_STAGE(bufoff, gbase, voff) do { _Pragma("unroll") for (int _i = 0; _i < 2; ++_i) \
;         __builtin_amdgcn_global_load_lds((const unsigned*)((const char*)(gbase) + (voff)[_i]), (PG8_LAS unsigned*)(lds + (bufoff) + ldsw + _i * 8192), 16, 0, 0); } while (0)
; #define PG8_LDA(dst, b, h) do { _Pragma("unroll") for (int m = 0; m < 4; ++m) _Pragma("unroll") for (int k = 0; k < 2; ++k) dst[m][k] = *(const PG8_LAS bf16x8*)(lds + PG8_SA(b, h) + aoff + m * 2048 + k * 1024); } while (0)
; #define PG8_MMA(ai, bj, At, Bt) do { __builtin_amdgcn_s_setprio(1); _Pragma("unroll") for (int m = 0; m < 4; ++m) _Pragma("unroll") for (int n = 0; n < 2; ++n) _Pragma("unroll") for (int k = 0; k < 2; ++k) \
;         acc[ai][bj][m][n] = __builtin_amdgcn_mfma_f32_16x16x32_bf16(Bt[n][k], At[m][k], acc[ai][bj][m][n], 0, 0, 0); __builtin_amdgcn_s_setprio(0); } while (0)
; #define PG8_WAIT_V(n) asm volatile("s_waitcnt vmcnt(" #n ")" ::: "memory")
; #define PG8_WAIT_L(n) asm volatile("s_waitcnt lgkmcnt(" #n ")" ::: "memory")
; #define PG8_BAR __builtin_amdgcn_s_barrier()
; #define PG8_SCHED __builtin_amdgcn_sched_barrier(0)
; template <class Epi, class Sched, bool ALIGN_EPI = false, bool SP2 = false>
; __device__ __forceinline__ void gemm_phase(PG8_LAS unsigned char* lds, const Gemm g, const Sched& S, const Epi& E) {
;     ...
;         for (int t = 0; t < nt; t += 2) {
;             const bool last = (t == nt - 2);
;             const char* a1 = cA + (size_t)(t + 1) * kstep;
;             const char* a2 = last ? nA : cA + (size_t)(t + 2) * kstep; const char* b2 = last ? nB : cB + (size_t)(t + 2) * kstep;
;     ...
;             PG8_LDA(At, 1, 1); PG8_STAGE(PG8_SB(1, 0), b3, voffB); PG8_STAGE(PG8_SB(1, 1), b3 + hstep, voffB); PG8_STAGE(PG8_SA(1, 0), a3, voffA);
;             PG8_WAIT_V(8); PG8_WAIT_L(0); PG8_BAR; PG8_MMA(1, 0, At, B0); PG8_MMA(1, 1, At, B1); PG8_BAR; PG8_SCHED;
	s_add_i32 s46, s60, s16
	v_lshl_add_u64 v[146:147], v[146:147], 0, s[26:27]
	s_mov_b32 m0, s46
	ds_read_b128 v[188:191], v152 offset:49152
	ds_read_b128 v[192:195], v152 offset:50176
	ds_read_b128 v[196:199], v152 offset:51200
	ds_read_b128 v[200:203], v152 offset:52224
	ds_read_b128 v[204:207], v152 offset:53248
	ds_read_b128 v[208:211], v152 offset:54272
	ds_read_b128 v[212:215], v152 offset:55296
	ds_read_b128 v[216:219], v152 offset:56320
	global_load_lds_dwordx4 v[146:147], off
	s_add_i32 m0, s46, 0x2000
	s_add_u32 s44, s44, 0x80080
	v_lshl_add_u64 v[146:147], v[220:221], 0, s[26:27]
	s_addc_u32 s45, s45, 0
	s_add_i32 s46, s61, s16
	global_load_lds_dwordx4 v[146:147], off
	v_lshl_add_u64 v[146:147], s[44:45], 0, v[132:133]
	s_mov_b32 m0, s46
	s_nop 0
	global_load_lds_dwordx4 v[146:147], off
	v_lshl_add_u64 v[146:147], s[44:45], 0, v[136:137]
	s_add_i32 m0, s46, 0x2000
	s_nop 0
	global_load_lds_dwordx4 v[146:147], off
	v_lshl_add_u64 v[146:147], v[222:223], 0, s[26:27]
	s_mov_b32 m0, s21
	s_nop 0
	v_lshl_add_u64 v[146:147], v[224:225], 0, s[26:27]
	s_mov_b32 m0, s33
	s_nop 0
	s_waitcnt vmcnt(6)
	s_waitcnt lgkmcnt(0)
	s_barrier
	s_setprio 1
	s_waitcnt lgkmcnt(0)
	v_mfma_f32_16x16x32_bf16 v[62:65], v[154:157], v[188:191], v[62:65]
	v_mfma_f32_16x16x32_bf16 v[58:61], v[162:165], v[188:191], v[58:61]
	v_mfma_f32_16x16x32_bf16 v[54:57], v[154:157], v[196:199], v[54:57]
	v_mfma_f32_16x16x32_bf16 v[46:49], v[162:165], v[196:199], v[46:49]
	v_mfma_f32_16x16x32_bf16 v[38:41], v[154:157], v[204:207], v[38:41]
	v_mfma_f32_16x16x32_bf16 v[30:33], v[162:165], v[204:207], v[30:33]
	v_mfma_f32_16x16x32_bf16 v[22:25], v[154:157], v[212:215], v[22:25]
	v_mfma_f32_16x16x32_bf16 v[14:17], v[162:165], v[212:215], v[14:17]
	v_mfma_f32_16x16x32_bf16 v[62:65], v[158:161], v[192:195], v[62:65]
	v_mfma_f32_16x16x32_bf16 v[58:61], v[166:169], v[192:195], v[58:61]
	v_mfma_f32_16x16x32_bf16 v[54:57], v[158:161], v[200:203], v[54:57]
	v_mfma_f32_16x16x32_bf16 v[46:49], v[166:169], v[200:203], v[46:49]
	v_mfma_f32_16x16x32_bf16 v[38:41], v[158:161], v[208:211], v[38:41]
	v_mfma_f32_16x16x32_bf16 v[30:33], v[166:169], v[208:211], v[30:33]
	v_mfma_f32_16x16x32_bf16 v[22:25], v[158:161], v[216:219], v[22:25]
	v_mfma_f32_16x16x32_bf16 v[14:17], v[166:169], v[216:219], v[14:17]
	s_setprio 0
	s_setprio 1
	v_mfma_f32_16x16x32_bf16 v[50:53], v[170:173], v[188:191], v[50:53]
	v_mfma_f32_16x16x32_bf16 v[42:45], v[178:181], v[188:191], v[42:45]
	v_mfma_f32_16x16x32_bf16 v[34:37], v[170:173], v[196:199], v[34:37]
	v_mfma_f32_16x16x32_bf16 v[26:29], v[178:181], v[196:199], v[26:29]
	v_mfma_f32_16x16x32_bf16 v[18:21], v[170:173], v[204:207], v[18:21]
	v_mfma_f32_16x16x32_bf16 v[10:13], v[178:181], v[204:207], v[10:13]
	v_mfma_f32_16x16x32_bf16 v[6:9], v[170:173], v[212:215], v[6:9]
	v_mfma_f32_16x16x32_bf16 v[2:5], v[178:181], v[212:215], v[2:5]
	v_mfma_f32_16x16x32_bf16 v[50:53], v[174:177], v[192:195], v[50:53]
	v_mfma_f32_16x16x32_bf16 v[42:45], v[182:185], v[192:195], v[42:45]
	v_mfma_f32_16x16x32_bf16 v[34:37], v[174:177], v[200:203], v[34:37]
	v_mfma_f32_16x16x32_bf16 v[26:29], v[182:185], v[200:203], v[26:29]
	v_mfma_f32_16x16x32_bf16 v[18:21], v[174:177], v[208:211], v[18:21]
	v_mfma_f32_16x16x32_bf16 v[10:13], v[182:185], v[208:211], v[10:13]
	v_mfma_f32_16x16x32_bf16 v[6:9], v[174:177], v[216:219], v[6:9]
	v_mfma_f32_16x16x32_bf16 v[2:5], v[182:185], v[216:219], v[2:5]
	s_setprio 0
	s_barrier
	s_add_i32 s59, s59, 2
	s_add_u32 s42, s42, 0x100
	s_addc_u32 s43, s43, 0
	s_add_u32 s57, s57, 0x100
	s_addc_u32 s58, s58, 0
	s_cmp_gt_u32 s59, 29
	s_cbranch_scc0 .LBB0_650
	s_and_b64 vcc, exec, s[28:29]
	s_cbranch_vccz .LBB0_653
	s_barrier

; #define PG8_STAGE(bufoff, gbase, voff) do { _Pragma("unroll") for (int _i = 0; _i < 2; ++_i) \
;         __builtin_amdgcn_global_load_lds((const unsigned*)((const char*)(gbase) + (voff)[_i]), (PG8_LAS unsigned*)(lds + (bufoff) + ldsw + _i * 8192), 16, 0, 0); } while (0)
; #define PG8_LDA(dst, b, h) do { _Pragma("unroll") for (int m = 0; m < 4; ++m) _Pragma("unroll") for (int k = 0; k < 2; ++k) dst[m][k] = *(const PG8_LAS bf16x8*)(lds + PG8_SA(b, h) + aoff + m * 2048 + k * 1024); } while (0)
; #define PG8_LDB(dst, b, h) do { _Pragma("unroll") for (int n = 0; n < 2; ++n) _Pragma("unroll") for (int k = 0; k < 2; ++k) dst[n][k] = *(const PG8_LAS bf16x8*)(lds + PG8_SB(b, h) + boff + n * 2048 + k * 1024); } while (0)
; #define PG8_MMA(ai, bj, At, Bt) do { __builtin_amdgcn_s_setprio(1); _Pragma("unroll") for (int m = 0; m < 4; ++m) _Pragma("unroll") for (int n = 0; n < 2; ++n) _Pragma("unroll") for (int k = 0; k < 2; ++k) \
;         acc[ai][bj][m][n] = __builtin_amdgcn_mfma_f32_16x16x32_bf16(Bt[n][k], At[m][k], acc[ai][bj][m][n], 0, 0, 0); __builtin_amdgcn_s_setprio(0); } while (0)
; #define PG8_WAIT_V(n) asm volatile("s_waitcnt vmcnt(" #n ")" ::: "memory")
; #define PG8_WAIT_L(n) asm volatile("s_waitcnt lgkmcnt(" #n ")" ::: "memory")
; #define PG8_BAR __builtin_amdgcn_s_barrier()
; #define PG8_SCHED __builtin_amdgcn_sched_barrier(0)
; template <class Epi, class Sched, bool ALIGN_EPI = false, bool SP2 = false>
; __device__ __forceinline__ void gemm_phase(PG8_LAS unsigned char* lds, const Gemm g, const Sched& S, const Epi& E) {
;     ...
;             PG8_LDB(B0, 0, 0); PG8_LDB(B1, 0, 1); PG8_SCHED; PG8_LDA(At, 0, 0); PG8_STAGE(PG8_SA(1, 1), a1 + hstep, voffA);
;             PG8_WAIT_V(8); PG8_WAIT_L(0); PG8_BAR; PG8_MMA(0, 0, At, B0); PG8_MMA(0, 1, At, B1); PG8_BAR; PG8_SCHED;
;             PG8_LDA(At, 0, 1); PG8_STAGE(PG8_SB(0, 0), b2, voffB); PG8_STAGE(PG8_SB(0, 1), b2 + hstep, voffB); PG8_STAGE(PG8_SA(0, 0), a2, voffA);
;             PG8_WAIT_V(8); PG8_WAIT_L(0); PG8_BAR; PG8_MMA(1, 0, At, B0); PG8_MMA(1, 1, At, B1); PG8_BAR; PG8_SCHED;
.LBB0_816:
	s_add_u32 s46, s44, 0xfffc0080
	s_addc_u32 s47, s45, -1
	s_add_i32 s63, 0, 0x10000
	s_cmp_eq_u32 s62, 12
	s_cselect_b32 s49, s7, s47
	s_cselect_b32 s48, s37, s46
	v_add_u32_e32 v138, s63, v170
	s_cselect_b32 s47, s35, s61
	s_cselect_b32 s46, s59, s60
	s_add_i32 s66, 0, 0x14000
	ds_read_b128 v[130:133], v138
	ds_read_b128 v[134:137], v138 offset:1024
	ds_read_b128 v[156:159], v138 offset:2048
	ds_read_b128 v[160:163], v138 offset:3072
	v_add_u32_e32 v138, s66, v170
	ds_read_b128 v[174:177], v138
	ds_read_b128 v[178:181], v138 offset:1024
	ds_read_b128 v[182:185], v138 offset:2048
	ds_read_b128 v[188:191], v138 offset:3072
	v_lshl_add_u64 v[138:139], s[44:45], 0, v[148:149]
	s_add_i32 m0, s43, 0xc000
	ds_read_b128 v[192:195], v172
	ds_read_b128 v[196:199], v172 offset:1024
	ds_read_b128 v[200:203], v172 offset:2048
	ds_read_b128 v[204:207], v172 offset:3072
	ds_read_b128 v[208:211], v172 offset:4096
	ds_read_b128 v[212:215], v172 offset:5120
	ds_read_b128 v[216:219], v172 offset:6144
	ds_read_b128 v[220:223], v172 offset:7168
	s_add_u32 s98, s44, 0xfffc0000
	s_addc_u32 s99, s45, -1
	s_mov_b32 m0, s56
	s_nop 0
	global_load_lds_dwordx4 v148, s[98:99]
	s_mov_b32 m0, s57
	s_nop 0
	global_load_lds_dwordx4 v150, s[98:99]
	s_add_i32 m0, s43, 0xc000
	s_nop 0
	global_load_lds_dwordx4 v[138:139], off
	v_lshl_add_u64 v[138:139], s[44:45], 0, v[150:151]
	s_add_i32 m0, s43, 0xe000
	s_nop 0
	global_load_lds_dwordx4 v[138:139], off
	s_waitcnt vmcnt(8)
	s_waitcnt lgkmcnt(0)
	s_barrier
	s_setprio 1
	s_waitcnt lgkmcnt(0)
	v_mfma_f32_16x16x32_bf16 v[126:129], v[130:133], v[192:195], v[126:129]
	v_mfma_f32_16x16x32_bf16 v[122:125], v[156:159], v[192:195], v[122:125]
	v_mfma_f32_16x16x32_bf16 v[110:113], v[130:133], v[200:203], v[110:113]
	v_mfma_f32_16x16x32_bf16 v[106:109], v[156:159], v[200:203], v[106:109]
	v_mfma_f32_16x16x32_bf16 v[94:97], v[130:133], v[208:211], v[94:97]
	v_mfma_f32_16x16x32_bf16 v[90:93], v[156:159], v[208:211], v[90:93]
	v_mfma_f32_16x16x32_bf16 v[78:81], v[130:133], v[216:219], v[78:81]
	v_mfma_f32_16x16x32_bf16 v[74:77], v[156:159], v[216:219], v[74:77]
	v_mfma_f32_16x16x32_bf16 v[126:129], v[134:137], v[196:199], v[126:129]
	v_mfma_f32_16x16x32_bf16 v[122:125], v[160:163], v[196:199], v[122:125]
	v_mfma_f32_16x16x32_bf16 v[110:113], v[134:137], v[204:207], v[110:113]
	v_mfma_f32_16x16x32_bf16 v[106:109], v[160:163], v[204:207], v[106:109]
	v_mfma_f32_16x16x32_bf16 v[94:97], v[134:137], v[212:215], v[94:97]
	v_mfma_f32_16x16x32_bf16 v[90:93], v[160:163], v[212:215], v[90:93]
	v_mfma_f32_16x16x32_bf16 v[78:81], v[134:137], v[220:223], v[78:81]
	v_mfma_f32_16x16x32_bf16 v[74:77], v[160:163], v[220:223], v[74:77]
	s_setprio 0
	s_setprio 1
	v_mfma_f32_16x16x32_bf16 v[118:121], v[174:177], v[192:195], v[118:121]
	v_mfma_f32_16x16x32_bf16 v[114:117], v[182:185], v[192:195], v[114:117]
	v_mfma_f32_16x16x32_bf16 v[102:105], v[174:177], v[200:203], v[102:105]
	v_mfma_f32_16x16x32_bf16 v[98:101], v[182:185], v[200:203], v[98:101]
	v_mfma_f32_16x16x32_bf16 v[86:89], v[174:177], v[208:211], v[86:89]
	v_mfma_f32_16x16x32_bf16 v[82:85], v[182:185], v[208:211], v[82:85]
	v_mfma_f32_16x16x32_bf16 v[70:73], v[174:177], v[216:219], v[70:73]
	v_mfma_f32_16x16x32_bf16 v[66:69], v[182:185], v[216:219], v[66:69]
	v_mfma_f32_16x16x32_bf16 v[118:121], v[178:181], v[196:199], v[118:121]
	v_mfma_f32_16x16x32_bf16 v[114:117], v[188:191], v[196:199], v[114:117]
	v_mfma_f32_16x16x32_bf16 v[102:105], v[178:181], v[204:207], v[102:105]
	v_mfma_f32_16x16x32_bf16 v[98:101], v[188:191], v[204:207], v[98:101]
	v_mfma_f32_16x16x32_bf16 v[86:89], v[178:181], v[212:215], v[86:89]
	v_mfma_f32_16x16x32_bf16 v[82:85], v[188:191], v[212:215], v[82:85]
	v_mfma_f32_16x16x32_bf16 v[70:73], v[178:181], v[220:223], v[70:73]
	v_mfma_f32_16x16x32_bf16 v[66:69], v[188:191], v[220:223], v[66:69]
	s_setprio 0
	s_barrier
	s_add_i32 s63, s63, s52
	v_lshl_add_u64 v[138:139], s[46:47], 0, v[142:143]
	s_mov_b32 m0, s63
	ds_read_b128 v[192:195], v172 offset:16384
	ds_read_b128 v[196:199], v172 offset:17408
	ds_read_b128 v[200:203], v172 offset:18432
	ds_read_b128 v[204:207], v172 offset:19456
	ds_read_b128 v[208:211], v172 offset:20480
	ds_read_b128 v[212:215], v172 offset:21504
	ds_read_b128 v[216:219], v172 offset:22528
	ds_read_b128 v[220:223], v172 offset:23552
	global_load_lds_dwordx4 v[138:139], off
	s_add_i32 m0, s63, 0x2000
	s_add_u32 s64, s46, 0x40000
	v_lshl_add_u64 v[224:225], s[46:47], 0, v[146:147]
	s_addc_u32 s65, s47, 0
	s_add_i32 s63, s66, s52
	global_load_lds_dwordx4 v[224:225], off
	v_lshl_add_u64 v[226:227], s[64:65], 0, v[142:143]
	s_mov_b32 m0, s63
	v_lshl_add_u64 v[228:229], s[48:49], 0, v[144:145]
	global_load_lds_dwordx4 v[226:227], off
	v_lshl_add_u64 v[226:227], s[64:65], 0, v[146:147]
	s_add_i32 m0, s63, 0x2000
	s_nop 0
	global_load_lds_dwordx4 v[226:227], off
	v_lshl_add_u64 v[226:227], s[48:49], 0, v[140:141]
	s_mov_b32 m0, s43
	s_nop 0
	s_mov_b32 m0, s53
	s_nop 0
	s_waitcnt vmcnt(6)
	s_waitcnt lgkmcnt(0)
	s_barrier
; #define PG8_STAGE(bufoff, gbase, voff) do { _Pragma("unroll") for (int _i = 0; _i < 2; ++_i) \
;         __builtin_amdgcn_global_load_lds((const unsigned*)((const char*)(gbase) + (voff)[_i]), (PG8_LAS unsigned*)(lds + (bufoff) + ldsw + _i * 8192), 16, 0, 0); } while (0)
; #define PG8_LDA(dst, b, h) do { _Pragma("unroll") for (int m = 0; m < 4; ++m) _Pragma("unroll") for (int k = 0; k < 2; ++k) dst[m][k] = *(const PG8_LAS bf16x8*)(lds + PG8_SA(b, h) + aoff + m * 2048 + k * 1024); } while (0)
; #define PG8_LDB(dst, b, h) do { _Pragma("unroll") for (int n = 0; n < 2; ++n) _Pragma("unroll") for (int k = 0; k < 2; ++k) dst[n][k] = *(const PG8_LAS bf16x8*)(lds + PG8_SB(b, h) + boff + n * 2048 + k * 1024); } while (0)
; #define PG8_MMA(ai, bj, At, Bt) do { __builtin_amdgcn_s_setprio(1); _Pragma("unroll") for (int m = 0; m < 4; ++m) _Pragma("unroll") for (int n = 0; n < 2; ++n) _Pragma("unroll") for (int k = 0; k < 2; ++k) \
;         acc[ai][bj][m][n] = __builtin_amdgcn_mfma_f32_16x16x32_bf16(Bt[n][k], At[m][k], acc[ai][bj][m][n], 0, 0, 0); __builtin_amdgcn_s_setprio(0); } while (0)
; #define PG8_WAIT_V(n) asm volatile("s_waitcnt vmcnt(" #n ")" ::: "memory")
; #define PG8_WAIT_L(n) asm volatile("s_waitcnt lgkmcnt(" #n ")" ::: "memory")
; #define PG8_BAR __builtin_amdgcn_s_barrier()
; #define PG8_SCHED __builtin_amdgcn_sched_barrier(0)
; template <class Epi, class Sched, bool ALIGN_EPI = false, bool SP2 = false>
; __device__ __forceinline__ void gemm_phase(PG8_LAS unsigned char* lds, const Gemm g, const Sched& S, const Epi& E) {
;     ...
;             PG8_WAIT_V(8); PG8_WAIT_L(0); PG8_BAR; PG8_MMA(1, 0, At, B0); PG8_MMA(1, 1, At, B1); PG8_BAR; PG8_SCHED;
;             PG8_LDB(B0, 1, 0); PG8_LDB(B1, 1, 1); PG8_SCHED; PG8_LDA(At, 1, 0); PG8_STAGE(PG8_SA(0, 1), a2 + hstep, voffA);
;             PG8_WAIT_V(8); PG8_WAIT_L(0); PG8_BAR; PG8_MMA(0, 0, At, B0); PG8_MMA(0, 1, At, B1); PG8_BAR; PG8_SCHED;
	s_setprio 1
	s_waitcnt lgkmcnt(0)
	v_mfma_f32_16x16x32_bf16 v[62:65], v[130:133], v[192:195], v[62:65]
	v_mfma_f32_16x16x32_bf16 v[58:61], v[156:159], v[192:195], v[58:61]
	v_mfma_f32_16x16x32_bf16 v[46:49], v[130:133], v[200:203], v[46:49]
	v_mfma_f32_16x16x32_bf16 v[42:45], v[156:159], v[200:203], v[42:45]
	v_mfma_f32_16x16x32_bf16 v[30:33], v[130:133], v[208:211], v[30:33]
	v_mfma_f32_16x16x32_bf16 v[26:29], v[156:159], v[208:211], v[26:29]
	v_mfma_f32_16x16x32_bf16 v[14:17], v[130:133], v[216:219], v[14:17]
	v_mfma_f32_16x16x32_bf16 v[10:13], v[156:159], v[216:219], v[10:13]
	v_mfma_f32_16x16x32_bf16 v[62:65], v[134:137], v[196:199], v[62:65]
	v_mfma_f32_16x16x32_bf16 v[58:61], v[160:163], v[196:199], v[58:61]
	v_mfma_f32_16x16x32_bf16 v[46:49], v[134:137], v[204:207], v[46:49]
	v_mfma_f32_16x16x32_bf16 v[42:45], v[160:163], v[204:207], v[42:45]
	v_mfma_f32_16x16x32_bf16 v[30:33], v[134:137], v[212:215], v[30:33]
	v_mfma_f32_16x16x32_bf16 v[26:29], v[160:163], v[212:215], v[26:29]
	v_mfma_f32_16x16x32_bf16 v[14:17], v[134:137], v[220:223], v[14:17]
	v_mfma_f32_16x16x32_bf16 v[10:13], v[160:163], v[220:223], v[10:13]
	s_setprio 0
	s_setprio 1
	v_mfma_f32_16x16x32_bf16 v[54:57], v[174:177], v[192:195], v[54:57]
	v_mfma_f32_16x16x32_bf16 v[50:53], v[182:185], v[192:195], v[50:53]
	v_mfma_f32_16x16x32_bf16 v[38:41], v[174:177], v[200:203], v[38:41]
	v_mfma_f32_16x16x32_bf16 v[34:37], v[182:185], v[200:203], v[34:37]
	v_mfma_f32_16x16x32_bf16 v[22:25], v[174:177], v[208:211], v[22:25]
	v_mfma_f32_16x16x32_bf16 v[18:21], v[182:185], v[208:211], v[18:21]
	v_mfma_f32_16x16x32_bf16 v[6:9], v[174:177], v[216:219], v[6:9]
	v_mfma_f32_16x16x32_bf16 v[2:5], v[182:185], v[216:219], v[2:5]
	v_mfma_f32_16x16x32_bf16 v[54:57], v[178:181], v[196:199], v[54:57]
	v_mfma_f32_16x16x32_bf16 v[50:53], v[188:191], v[196:199], v[50:53]
	v_mfma_f32_16x16x32_bf16 v[38:41], v[178:181], v[204:207], v[38:41]
	v_mfma_f32_16x16x32_bf16 v[34:37], v[188:191], v[204:207], v[34:37]
	v_mfma_f32_16x16x32_bf16 v[22:25], v[178:181], v[212:215], v[22:25]
	v_mfma_f32_16x16x32_bf16 v[18:21], v[188:191], v[212:215], v[18:21]
	v_mfma_f32_16x16x32_bf16 v[6:9], v[178:181], v[220:223], v[6:9]
	v_mfma_f32_16x16x32_bf16 v[2:5], v[188:191], v[220:223], v[2:5]
	s_setprio 0
	s_barrier
	s_add_i32 s63, 0, 0x18000
	s_add_i32 s64, 0, 0x1c000
	v_add_u32_e32 v160, s63, v170
	v_add_u32_e32 v173, s64, v170
	ds_read_b128 v[130:133], v160
	ds_read_b128 v[134:137], v160 offset:1024
	ds_read_b128 v[156:159], v160 offset:2048
	ds_read_b128 v[160:163], v160 offset:3072
	ds_read_b128 v[174:177], v173
	ds_read_b128 v[178:181], v173 offset:1024
	ds_read_b128 v[182:185], v173 offset:2048
	ds_read_b128 v[188:191], v173 offset:3072
	s_add_u32 s48, s48, 0x40000
	s_addc_u32 s49, s49, 0
	s_mov_b32 m0, s54
	v_lshl_add_u64 v[230:231], s[48:49], 0, v[140:141]
	ds_read_b128 v[192:195], v172 offset:32768
	ds_read_b128 v[196:199], v172 offset:33792
	ds_read_b128 v[200:203], v172 offset:34816
	ds_read_b128 v[204:207], v172 offset:35840
	ds_read_b128 v[208:211], v172 offset:36864
	ds_read_b128 v[212:215], v172 offset:37888
	ds_read_b128 v[216:219], v172 offset:38912
	ds_read_b128 v[220:223], v172 offset:39936
	s_add_u32 s98, s48, 0xfffc0000
	s_addc_u32 s99, s49, -1
	s_mov_b32 m0, s43
	s_nop 0
	global_load_lds_dwordx4 v140, s[98:99]
	s_mov_b32 m0, s53
	s_nop 0
	global_load_lds_dwordx4 v144, s[98:99]
	s_mov_b32 m0, s54
	s_nop 0
	global_load_lds_dwordx4 v[230:231], off
	v_lshl_add_u64 v[230:231], s[48:49], 0, v[144:145]
	s_mov_b32 m0, s55
	s_nop 0
	global_load_lds_dwordx4 v[230:231], off
	s_waitcnt vmcnt(8)
	s_waitcnt lgkmcnt(0)
	s_barrier
	s_setprio 1
	s_waitcnt lgkmcnt(0)
	v_mfma_f32_16x16x32_bf16 v[126:129], v[130:133], v[192:195], v[126:129]
	v_mfma_f32_16x16x32_bf16 v[122:125], v[156:159], v[192:195], v[122:125]
	v_mfma_f32_16x16x32_bf16 v[110:113], v[130:133], v[200:203], v[110:113]
	v_mfma_f32_16x16x32_bf16 v[106:109], v[156:159], v[200:203], v[106:109]
	v_mfma_f32_16x16x32_bf16 v[94:97], v[130:133], v[208:211], v[94:97]
	v_mfma_f32_16x16x32_bf16 v[90:93], v[156:159], v[208:211], v[90:93]
	v_mfma_f32_16x16x32_bf16 v[78:81], v[130:133], v[216:219], v[78:81]
	v_mfma_f32_16x16x32_bf16 v[74:77], v[156:159], v[216:219], v[74:77]
	v_mfma_f32_16x16x32_bf16 v[126:129], v[134:137], v[196:199], v[126:129]
	v_mfma_f32_16x16x32_bf16 v[122:125], v[160:163], v[196:199], v[122:125]
	v_mfma_f32_16x16x32_bf16 v[110:113], v[134:137], v[204:207], v[110:113]
	v_mfma_f32_16x16x32_bf16 v[106:109], v[160:163], v[204:207], v[106:109]
	v_mfma_f32_16x16x32_bf16 v[94:97], v[134:137], v[212:215], v[94:97]
	v_mfma_f32_16x16x32_bf16 v[90:93], v[160:163], v[212:215], v[90:93]
	v_mfma_f32_16x16x32_bf16 v[78:81], v[134:137], v[220:223], v[78:81]
	v_mfma_f32_16x16x32_bf16 v[74:77], v[160:163], v[220:223], v[74:77]
	s_setprio 0
	s_setprio 1
	v_mfma_f32_16x16x32_bf16 v[118:121], v[174:177], v[192:195], v[118:121]
	v_mfma_f32_16x16x32_bf16 v[114:117], v[182:185], v[192:195], v[114:117]
	v_mfma_f32_16x16x32_bf16 v[102:105], v[174:177], v[200:203], v[102:105]
	v_mfma_f32_16x16x32_bf16 v[98:101], v[182:185], v[200:203], v[98:101]
	v_mfma_f32_16x16x32_bf16 v[86:89], v[174:177], v[208:211], v[86:89]
	v_mfma_f32_16x16x32_bf16 v[82:85], v[182:185], v[208:211], v[82:85]
	v_mfma_f32_16x16x32_bf16 v[70:73], v[174:177], v[216:219], v[70:73]
	v_mfma_f32_16x16x32_bf16 v[66:69], v[182:185], v[216:219], v[66:69]
	v_mfma_f32_16x16x32_bf16 v[118:121], v[178:181], v[196:199], v[118:121]
	v_mfma_f32_16x16x32_bf16 v[114:117], v[188:191], v[196:199], v[114:117]
	v_mfma_f32_16x16x32_bf16 v[102:105], v[178:181], v[204:207], v[102:105]
	v_mfma_f32_16x16x32_bf16 v[98:101], v[188:191], v[204:207], v[98:101]
	v_mfma_f32_16x16x32_bf16 v[86:89], v[178:181], v[212:215], v[86:89]
	v_mfma_f32_16x16x32_bf16 v[82:85], v[188:191], v[212:215], v[82:85]
	v_mfma_f32_16x16x32_bf16 v[70:73], v[178:181], v[220:223], v[70:73]
	v_mfma_f32_16x16x32_bf16 v[66:69], v[188:191], v[220:223], v[66:69]
	s_setprio 0
	s_barrier
; #define PG8_STAGE(bufoff, gbase, voff) do { _Pragma("unroll") for (int _i = 0; _i < 2; ++_i) \
;         __builtin_amdgcn_global_load_lds((const unsigned*)((const char*)(gbase) + (voff)[_i]), (PG8_LAS unsigned*)(lds + (bufoff) + ldsw + _i * 8192), 16, 0, 0); } while (0)
; #define PG8_LDA(dst, b, h) do { _Pragma("unroll") for (int m = 0; m < 4; ++m) _Pragma("unroll") for (int k = 0; k < 2; ++k) dst[m][k] = *(const PG8_LAS bf16x8*)(lds + PG8_SA(b, h) + aoff + m * 2048 + k * 1024); } while (0)
; #define PG8_MMA(ai, bj, At, Bt) do { __builtin_amdgcn_s_setprio(1); _Pragma("unroll") for (int m = 0; m < 4; ++m) _Pragma("unroll") for (int n = 0; n < 2; ++n) _Pragma("unroll") for (int k = 0; k < 2; ++k) \
;         acc[ai][bj][m][n] = __builtin_amdgcn_mfma_f32_16x16x32_bf16(Bt[n][k], At[m][k], acc[ai][bj][m][n], 0, 0, 0); __builtin_amdgcn_s_setprio(0); } while (0)
; #define PG8_WAIT_V(n) asm volatile("s_waitcnt vmcnt(" #n ")" ::: "memory")
; #define PG8_WAIT_L(n) asm volatile("s_waitcnt lgkmcnt(" #n ")" ::: "memory")
; #define PG8_BAR __builtin_amdgcn_s_barrier()
; #define PG8_SCHED __builtin_amdgcn_sched_barrier(0)
; template <class Epi, class Sched, bool ALIGN_EPI = false, bool SP2 = false>
; __device__ __forceinline__ void gemm_phase(PG8_LAS unsigned char* lds, const Gemm g, const Sched& S, const Epi& E) {
;     ...
;         for (int t = 0; t < nt; t += 2) {
;             const bool last = (t == nt - 2);
;             const char* a1 = cA + (size_t)(t + 1) * kstep;
;             const char* a2 = last ? nA : cA + (size_t)(t + 2) * kstep; const char* b2 = last ? nB : cB + (size_t)(t + 2) * kstep;
;     ...
;             PG8_LDA(At, 1, 1); PG8_STAGE(PG8_SB(1, 0), b3, voffB); PG8_STAGE(PG8_SB(1, 1), b3 + hstep, voffB); PG8_STAGE(PG8_SA(1, 0), a3, voffA);
;             PG8_WAIT_V(8); PG8_WAIT_L(0); PG8_BAR; PG8_MMA(1, 0, At, B0); PG8_MMA(1, 1, At, B1); PG8_BAR; PG8_SCHED;
	s_add_i32 s48, s63, s52
	v_lshl_add_u64 v[138:139], v[138:139], 0, s[22:23]
	s_mov_b32 m0, s48
	ds_read_b128 v[192:195], v172 offset:49152
	ds_read_b128 v[196:199], v172 offset:50176
	ds_read_b128 v[200:203], v172 offset:51200
	ds_read_b128 v[204:207], v172 offset:52224
	ds_read_b128 v[208:211], v172 offset:53248
	ds_read_b128 v[212:215], v172 offset:54272
	ds_read_b128 v[216:219], v172 offset:55296
	ds_read_b128 v[220:223], v172 offset:56320
	global_load_lds_dwordx4 v[138:139], off
	s_add_i32 m0, s48, 0x2000
	s_add_u32 s46, s46, 0x40080
	v_lshl_add_u64 v[138:139], v[224:225], 0, s[22:23]
	s_addc_u32 s47, s47, 0
	s_add_i32 s48, s64, s52
	global_load_lds_dwordx4 v[138:139], off
	v_lshl_add_u64 v[138:139], s[46:47], 0, v[142:143]
	s_mov_b32 m0, s48
	s_nop 0
	global_load_lds_dwordx4 v[138:139], off
	v_lshl_add_u64 v[138:139], s[46:47], 0, v[146:147]
	s_add_i32 m0, s48, 0x2000
	s_nop 0
	global_load_lds_dwordx4 v[138:139], off
	v_lshl_add_u64 v[138:139], v[226:227], 0, s[22:23]
	s_mov_b32 m0, s56
	s_nop 0
	v_lshl_add_u64 v[138:139], v[228:229], 0, s[22:23]
	s_mov_b32 m0, s57
	s_nop 0
	s_waitcnt vmcnt(6)
	s_waitcnt lgkmcnt(0)
	s_barrier
	s_setprio 1
	s_waitcnt lgkmcnt(0)
	v_mfma_f32_16x16x32_bf16 v[62:65], v[130:133], v[192:195], v[62:65]
	v_mfma_f32_16x16x32_bf16 v[58:61], v[156:159], v[192:195], v[58:61]
	v_mfma_f32_16x16x32_bf16 v[46:49], v[130:133], v[200:203], v[46:49]
	v_mfma_f32_16x16x32_bf16 v[42:45], v[156:159], v[200:203], v[42:45]
	v_mfma_f32_16x16x32_bf16 v[30:33], v[130:133], v[208:211], v[30:33]
	v_mfma_f32_16x16x32_bf16 v[26:29], v[156:159], v[208:211], v[26:29]
	v_mfma_f32_16x16x32_bf16 v[14:17], v[130:133], v[216:219], v[14:17]
	v_mfma_f32_16x16x32_bf16 v[10:13], v[156:159], v[216:219], v[10:13]
	v_mfma_f32_16x16x32_bf16 v[62:65], v[134:137], v[196:199], v[62:65]
	v_mfma_f32_16x16x32_bf16 v[58:61], v[160:163], v[196:199], v[58:61]
	v_mfma_f32_16x16x32_bf16 v[46:49], v[134:137], v[204:207], v[46:49]
	v_mfma_f32_16x16x32_bf16 v[42:45], v[160:163], v[204:207], v[42:45]
	v_mfma_f32_16x16x32_bf16 v[30:33], v[134:137], v[212:215], v[30:33]
	v_mfma_f32_16x16x32_bf16 v[26:29], v[160:163], v[212:215], v[26:29]
	v_mfma_f32_16x16x32_bf16 v[14:17], v[134:137], v[220:223], v[14:17]
	v_mfma_f32_16x16x32_bf16 v[10:13], v[160:163], v[220:223], v[10:13]
	s_setprio 0
	s_setprio 1
	v_mfma_f32_16x16x32_bf16 v[54:57], v[174:177], v[192:195], v[54:57]
	v_mfma_f32_16x16x32_bf16 v[50:53], v[182:185], v[192:195], v[50:53]
	v_mfma_f32_16x16x32_bf16 v[38:41], v[174:177], v[200:203], v[38:41]
	v_mfma_f32_16x16x32_bf16 v[34:37], v[182:185], v[200:203], v[34:37]
	v_mfma_f32_16x16x32_bf16 v[22:25], v[174:177], v[208:211], v[22:25]
	v_mfma_f32_16x16x32_bf16 v[18:21], v[182:185], v[208:211], v[18:21]
	v_mfma_f32_16x16x32_bf16 v[6:9], v[174:177], v[216:219], v[6:9]
	v_mfma_f32_16x16x32_bf16 v[2:5], v[182:185], v[216:219], v[2:5]
	v_mfma_f32_16x16x32_bf16 v[54:57], v[178:181], v[196:199], v[54:57]
	v_mfma_f32_16x16x32_bf16 v[50:53], v[188:191], v[196:199], v[50:53]
	v_mfma_f32_16x16x32_bf16 v[38:41], v[178:181], v[204:207], v[38:41]
	v_mfma_f32_16x16x32_bf16 v[34:37], v[188:191], v[204:207], v[34:37]
	v_mfma_f32_16x16x32_bf16 v[22:25], v[178:181], v[212:215], v[22:25]
	v_mfma_f32_16x16x32_bf16 v[18:21], v[188:191], v[212:215], v[18:21]
	v_mfma_f32_16x16x32_bf16 v[6:9], v[178:181], v[220:223], v[6:9]
	v_mfma_f32_16x16x32_bf16 v[2:5], v[188:191], v[220:223], v[2:5]
	s_setprio 0
	s_barrier
	s_add_i32 s62, s62, 2
	s_add_u32 s44, s44, 0x100
	s_addc_u32 s45, s45, 0
	s_add_u32 s60, s60, 0x100
	s_addc_u32 s61, s61, 0
	s_cmp_gt_u32 s62, 13
	s_cbranch_scc0 .LBB0_816
	s_and_b64 vcc, exec, s[30:31]
	s_cbranch_vccz .LBB0_819
	s_barrier

; #define PG8_STAGE(bufoff, gbase, voff) do { _Pragma("unroll") for (int _i = 0; _i < 2; ++_i) \
;         __builtin_amdgcn_global_load_lds((const unsigned*)((const char*)(gbase) + (voff)[_i]), (PG8_LAS unsigned*)(lds + (bufoff) + ldsw + _i * 8192), 16, 0, 0); } while (0)
; #define PG8_LDA(dst, b, h) do { _Pragma("unroll") for (int m = 0; m < 4; ++m) _Pragma("unroll") for (int k = 0; k < 2; ++k) dst[m][k] = *(const PG8_LAS bf16x8*)(lds + PG8_SA(b, h) + aoff + m * 2048 + k * 1024); } while (0)
; #define PG8_LDB(dst, b, h) do { _Pragma("unroll") for (int n = 0; n < 2; ++n) _Pragma("unroll") for (int k = 0; k < 2; ++k) dst[n][k] = *(const PG8_LAS bf16x8*)(lds + PG8_SB(b, h) + boff + n * 2048 + k * 1024); } while (0)
; #define PG8_MMA(ai, bj, At, Bt) do { __builtin_amdgcn_s_setprio(1); _Pragma("unroll") for (int m = 0; m < 4; ++m) _Pragma("unroll") for (int n = 0; n < 2; ++n) _Pragma("unroll") for (int k = 0; k < 2; ++k) \
;         acc[ai][bj][m][n] = __builtin_amdgcn_mfma_f32_16x16x32_bf16(Bt[n][k], At[m][k], acc[ai][bj][m][n], 0, 0, 0); __builtin_amdgcn_s_setprio(0); } while (0)
; #define PG8_WAIT_V(n) asm volatile("s_waitcnt vmcnt(" #n ")" ::: "memory")
; #define PG8_WAIT_L(n) asm volatile("s_waitcnt lgkmcnt(" #n ")" ::: "memory")
; #define PG8_BAR __builtin_amdgcn_s_barrier()
; #define PG8_SCHED __builtin_amdgcn_sched_barrier(0)
; template <class Epi, class Sched, bool ALIGN_EPI = false, bool SP2 = false>
; __device__ __forceinline__ void gemm_phase(PG8_LAS unsigned char* lds, const Gemm g, const Sched& S, const Epi& E) {
;     ...
;             PG8_LDB(B0, 0, 0); PG8_LDB(B1, 0, 1); PG8_SCHED; PG8_LDA(At, 0, 0); PG8_STAGE(PG8_SA(1, 1), a1 + hstep, voffA);
;             PG8_WAIT_V(8); PG8_WAIT_L(0); PG8_BAR; PG8_MMA(0, 0, At, B0); PG8_MMA(0, 1, At, B1); PG8_BAR; PG8_SCHED;
;             PG8_LDA(At, 0, 1); PG8_STAGE(PG8_SB(0, 0), b2, voffB); PG8_STAGE(PG8_SB(0, 1), b2 + hstep, voffB); PG8_STAGE(PG8_SA(0, 0), a2, voffA);
;             PG8_WAIT_V(8); PG8_WAIT_L(0); PG8_BAR; PG8_MMA(1, 0, At, B0); PG8_MMA(1, 1, At, B1); PG8_BAR; PG8_SCHED;
.LBB0_941:
	ds_read_b128 v[130:133], v165
	ds_read_b128 v[134:137], v165 offset:1024
	ds_read_b128 v[138:141], v165 offset:2048
	ds_read_b128 v[142:145], v165 offset:3072
	ds_read_b128 v[158:161], v166
	ds_read_b128 v[168:171], v166 offset:1024
	ds_read_b128 v[172:175], v166 offset:2048
	ds_read_b128 v[176:179], v166 offset:3072
	s_add_u32 s34, s30, 0xfff80080
	s_addc_u32 s35, s31, -1
	s_cmp_eq_u32 s53, 28
	s_cselect_b32 s37, s23, s35
	s_cselect_b32 s36, s49, s34
	s_cselect_b32 s35, s21, s52
	s_cselect_b32 s34, s50, s51
	v_lshl_add_u64 v[184:185], s[30:31], 0, v[150:151]
	s_add_i32 m0, s17, 0xc000
	ds_read_b128 v[180:183], v167
	ds_read_b128 v[188:191], v167 offset:1024
	ds_read_b128 v[192:195], v167 offset:2048
	ds_read_b128 v[196:199], v167 offset:3072
	ds_read_b128 v[200:203], v167 offset:4096
	ds_read_b128 v[204:207], v167 offset:5120
	ds_read_b128 v[208:211], v167 offset:6144
	ds_read_b128 v[212:215], v167 offset:7168
	s_add_u32 s98, s30, 0xfff80000
	s_addc_u32 s99, s31, -1
	s_mov_b32 m0, s42
	s_nop 0
	global_load_lds_dwordx4 v150, s[98:99]
	s_mov_b32 m0, s43
	s_nop 0
	global_load_lds_dwordx4 v152, s[98:99]
	s_add_i32 m0, s17, 0xc000
	s_nop 0
	global_load_lds_dwordx4 v[184:185], off
	v_lshl_add_u64 v[184:185], s[30:31], 0, v[152:153]
	s_add_i32 m0, s17, 0xe000
	s_nop 0
	global_load_lds_dwordx4 v[184:185], off
	s_waitcnt vmcnt(8)
	s_waitcnt lgkmcnt(0)
	s_barrier
	s_setprio 1
	s_waitcnt lgkmcnt(0)
	v_mfma_f32_16x16x32_bf16 v[126:129], v[130:133], v[180:183], v[126:129]
	v_mfma_f32_16x16x32_bf16 v[122:125], v[138:141], v[180:183], v[122:125]
	v_mfma_f32_16x16x32_bf16 v[114:117], v[130:133], v[192:195], v[114:117]
	v_mfma_f32_16x16x32_bf16 v[110:113], v[138:141], v[192:195], v[110:113]
	v_mfma_f32_16x16x32_bf16 v[98:101], v[130:133], v[200:203], v[98:101]
	v_mfma_f32_16x16x32_bf16 v[94:97], v[138:141], v[200:203], v[94:97]
	v_mfma_f32_16x16x32_bf16 v[82:85], v[130:133], v[208:211], v[82:85]
	v_mfma_f32_16x16x32_bf16 v[78:81], v[138:141], v[208:211], v[78:81]
	v_mfma_f32_16x16x32_bf16 v[126:129], v[134:137], v[188:191], v[126:129]
	v_mfma_f32_16x16x32_bf16 v[122:125], v[142:145], v[188:191], v[122:125]
	v_mfma_f32_16x16x32_bf16 v[114:117], v[134:137], v[196:199], v[114:117]
	v_mfma_f32_16x16x32_bf16 v[110:113], v[142:145], v[196:199], v[110:113]
	v_mfma_f32_16x16x32_bf16 v[98:101], v[134:137], v[204:207], v[98:101]
	v_mfma_f32_16x16x32_bf16 v[94:97], v[142:145], v[204:207], v[94:97]
	v_mfma_f32_16x16x32_bf16 v[82:85], v[134:137], v[212:215], v[82:85]
	v_mfma_f32_16x16x32_bf16 v[78:81], v[142:145], v[212:215], v[78:81]
	s_setprio 0
	s_setprio 1
	v_mfma_f32_16x16x32_bf16 v[118:121], v[158:161], v[180:183], v[118:121]
	v_mfma_f32_16x16x32_bf16 v[106:109], v[172:175], v[180:183], v[106:109]
	v_mfma_f32_16x16x32_bf16 v[102:105], v[158:161], v[192:195], v[102:105]
	v_mfma_f32_16x16x32_bf16 v[90:93], v[172:175], v[192:195], v[90:93]
	v_mfma_f32_16x16x32_bf16 v[86:89], v[158:161], v[200:203], v[86:89]
	v_mfma_f32_16x16x32_bf16 v[74:77], v[172:175], v[200:203], v[74:77]
	v_mfma_f32_16x16x32_bf16 v[70:73], v[158:161], v[208:211], v[70:73]
	v_mfma_f32_16x16x32_bf16 v[66:69], v[172:175], v[208:211], v[66:69]
	v_mfma_f32_16x16x32_bf16 v[118:121], v[168:171], v[188:191], v[118:121]
	v_mfma_f32_16x16x32_bf16 v[106:109], v[176:179], v[188:191], v[106:109]
	v_mfma_f32_16x16x32_bf16 v[102:105], v[168:171], v[196:199], v[102:105]
	v_mfma_f32_16x16x32_bf16 v[90:93], v[176:179], v[196:199], v[90:93]
	v_mfma_f32_16x16x32_bf16 v[86:89], v[168:171], v[204:207], v[86:89]
	v_mfma_f32_16x16x32_bf16 v[74:77], v[176:179], v[204:207], v[74:77]
	v_mfma_f32_16x16x32_bf16 v[70:73], v[168:171], v[212:215], v[70:73]
	v_mfma_f32_16x16x32_bf16 v[66:69], v[176:179], v[212:215], v[66:69]
	s_setprio 0
	s_barrier
	s_add_i32 s54, s46, s16
	v_lshl_add_u64 v[184:185], s[34:35], 0, v[146:147]
	s_mov_b32 m0, s54
	ds_read_b128 v[180:183], v167 offset:16384
	ds_read_b128 v[188:191], v167 offset:17408
	ds_read_b128 v[192:195], v167 offset:18432
	ds_read_b128 v[196:199], v167 offset:19456
	ds_read_b128 v[200:203], v167 offset:20480
	ds_read_b128 v[204:207], v167 offset:21504
	ds_read_b128 v[208:211], v167 offset:22528
	ds_read_b128 v[212:215], v167 offset:23552
	global_load_lds_dwordx4 v[184:185], off
	s_add_i32 m0, s54, 0x2000
	s_add_u32 s54, s34, 0x80000
	v_lshl_add_u64 v[216:217], s[34:35], 0, v[148:149]
	s_addc_u32 s55, s35, 0
	s_add_i32 s56, s47, s16
	global_load_lds_dwordx4 v[216:217], off
	v_lshl_add_u64 v[218:219], s[54:55], 0, v[146:147]
	s_mov_b32 m0, s56
	v_lshl_add_u64 v[220:221], s[36:37], 0, v[148:149]
	global_load_lds_dwordx4 v[218:219], off
	v_lshl_add_u64 v[218:219], s[54:55], 0, v[148:149]
	s_add_i32 m0, s56, 0x2000
	s_nop 0
	global_load_lds_dwordx4 v[218:219], off
	v_lshl_add_u64 v[218:219], s[36:37], 0, v[146:147]
	s_mov_b32 m0, s17
	s_nop 0
	s_mov_b32 m0, s29
	s_nop 0
	s_waitcnt vmcnt(6)
	s_waitcnt lgkmcnt(0)
	s_barrier
; #define PG8_STAGE(bufoff, gbase, voff) do { _Pragma("unroll") for (int _i = 0; _i < 2; ++_i) \
;         __builtin_amdgcn_global_load_lds((const unsigned*)((const char*)(gbase) + (voff)[_i]), (PG8_LAS unsigned*)(lds + (bufoff) + ldsw + _i * 8192), 16, 0, 0); } while (0)
; #define PG8_LDA(dst, b, h) do { _Pragma("unroll") for (int m = 0; m < 4; ++m) _Pragma("unroll") for (int k = 0; k < 2; ++k) dst[m][k] = *(const PG8_LAS bf16x8*)(lds + PG8_SA(b, h) + aoff + m * 2048 + k * 1024); } while (0)
; #define PG8_LDB(dst, b, h) do { _Pragma("unroll") for (int n = 0; n < 2; ++n) _Pragma("unroll") for (int k = 0; k < 2; ++k) dst[n][k] = *(const PG8_LAS bf16x8*)(lds + PG8_SB(b, h) + boff + n * 2048 + k * 1024); } while (0)
; #define PG8_MMA(ai, bj, At, Bt) do { __builtin_amdgcn_s_setprio(1); _Pragma("unroll") for (int m = 0; m < 4; ++m) _Pragma("unroll") for (int n = 0; n < 2; ++n) _Pragma("unroll") for (int k = 0; k < 2; ++k) \
;         acc[ai][bj][m][n] = __builtin_amdgcn_mfma_f32_16x16x32_bf16(Bt[n][k], At[m][k], acc[ai][bj][m][n], 0, 0, 0); __builtin_amdgcn_s_setprio(0); } while (0)
; #define PG8_WAIT_V(n) asm volatile("s_waitcnt vmcnt(" #n ")" ::: "memory")
; #define PG8_WAIT_L(n) asm volatile("s_waitcnt lgkmcnt(" #n ")" ::: "memory")
; #define PG8_BAR __builtin_amdgcn_s_barrier()
; #define PG8_SCHED __builtin_amdgcn_sched_barrier(0)
; template <class Epi, class Sched, bool ALIGN_EPI = false, bool SP2 = false>
; __device__ __forceinline__ void gemm_phase(PG8_LAS unsigned char* lds, const Gemm g, const Sched& S, const Epi& E) {
;     ...
;             PG8_WAIT_V(8); PG8_WAIT_L(0); PG8_BAR; PG8_MMA(1, 0, At, B0); PG8_MMA(1, 1, At, B1); PG8_BAR; PG8_SCHED;
;             PG8_LDB(B0, 1, 0); PG8_LDB(B1, 1, 1); PG8_SCHED; PG8_LDA(At, 1, 0); PG8_STAGE(PG8_SA(0, 1), a2 + hstep, voffA);
;             PG8_WAIT_V(8); PG8_WAIT_L(0); PG8_BAR; PG8_MMA(0, 0, At, B0); PG8_MMA(0, 1, At, B1); PG8_BAR; PG8_SCHED;
	s_setprio 1
	s_waitcnt lgkmcnt(0)
	v_mfma_f32_16x16x32_bf16 v[62:65], v[130:133], v[180:183], v[62:65]
	v_mfma_f32_16x16x32_bf16 v[58:61], v[138:141], v[180:183], v[58:61]
	v_mfma_f32_16x16x32_bf16 v[50:53], v[130:133], v[192:195], v[50:53]
	v_mfma_f32_16x16x32_bf16 v[46:49], v[138:141], v[192:195], v[46:49]
	v_mfma_f32_16x16x32_bf16 v[34:37], v[130:133], v[200:203], v[34:37]
	v_mfma_f32_16x16x32_bf16 v[30:33], v[138:141], v[200:203], v[30:33]
	v_mfma_f32_16x16x32_bf16 v[18:21], v[130:133], v[208:211], v[18:21]
	v_mfma_f32_16x16x32_bf16 v[14:17], v[138:141], v[208:211], v[14:17]
	v_mfma_f32_16x16x32_bf16 v[62:65], v[134:137], v[188:191], v[62:65]
	v_mfma_f32_16x16x32_bf16 v[58:61], v[142:145], v[188:191], v[58:61]
	v_mfma_f32_16x16x32_bf16 v[50:53], v[134:137], v[196:199], v[50:53]
	v_mfma_f32_16x16x32_bf16 v[46:49], v[142:145], v[196:199], v[46:49]
	v_mfma_f32_16x16x32_bf16 v[34:37], v[134:137], v[204:207], v[34:37]
	v_mfma_f32_16x16x32_bf16 v[30:33], v[142:145], v[204:207], v[30:33]
	v_mfma_f32_16x16x32_bf16 v[18:21], v[134:137], v[212:215], v[18:21]
	v_mfma_f32_16x16x32_bf16 v[14:17], v[142:145], v[212:215], v[14:17]
	s_setprio 0
	s_setprio 1
	v_mfma_f32_16x16x32_bf16 v[54:57], v[158:161], v[180:183], v[54:57]
	v_mfma_f32_16x16x32_bf16 v[42:45], v[172:175], v[180:183], v[42:45]
	v_mfma_f32_16x16x32_bf16 v[38:41], v[158:161], v[192:195], v[38:41]
	v_mfma_f32_16x16x32_bf16 v[26:29], v[172:175], v[192:195], v[26:29]
	v_mfma_f32_16x16x32_bf16 v[22:25], v[158:161], v[200:203], v[22:25]
	v_mfma_f32_16x16x32_bf16 v[10:13], v[172:175], v[200:203], v[10:13]
	v_mfma_f32_16x16x32_bf16 v[6:9], v[158:161], v[208:211], v[6:9]
	v_mfma_f32_16x16x32_bf16 v[2:5], v[172:175], v[208:211], v[2:5]
	v_mfma_f32_16x16x32_bf16 v[54:57], v[168:171], v[188:191], v[54:57]
	v_mfma_f32_16x16x32_bf16 v[42:45], v[176:179], v[188:191], v[42:45]
	v_mfma_f32_16x16x32_bf16 v[38:41], v[168:171], v[196:199], v[38:41]
	v_mfma_f32_16x16x32_bf16 v[26:29], v[176:179], v[196:199], v[26:29]
	v_mfma_f32_16x16x32_bf16 v[22:25], v[168:171], v[204:207], v[22:25]
	v_mfma_f32_16x16x32_bf16 v[10:13], v[176:179], v[204:207], v[10:13]
	v_mfma_f32_16x16x32_bf16 v[6:9], v[168:171], v[212:215], v[6:9]
	v_mfma_f32_16x16x32_bf16 v[2:5], v[176:179], v[212:215], v[2:5]
	s_setprio 0
	s_barrier
	s_add_i32 s54, 0, 0x18000
	s_add_i32 s55, 0, 0x1c000
	v_add_u32_e32 v142, s54, v163
	v_add_u32_e32 v176, s55, v163
	ds_read_b128 v[130:133], v142
	ds_read_b128 v[134:137], v142 offset:1024
	ds_read_b128 v[138:141], v142 offset:2048
	ds_read_b128 v[142:145], v142 offset:3072
	ds_read_b128 v[158:161], v176
	ds_read_b128 v[168:171], v176 offset:1024
	ds_read_b128 v[172:175], v176 offset:2048
	ds_read_b128 v[176:179], v176 offset:3072
	s_add_u32 s36, s36, 0x80000
	s_addc_u32 s37, s37, 0
	s_mov_b32 m0, s33
	v_lshl_add_u64 v[222:223], s[36:37], 0, v[146:147]
	ds_read_b128 v[180:183], v167 offset:32768
	ds_read_b128 v[188:191], v167 offset:33792
	ds_read_b128 v[192:195], v167 offset:34816
	ds_read_b128 v[196:199], v167 offset:35840
	ds_read_b128 v[200:203], v167 offset:36864
	ds_read_b128 v[204:207], v167 offset:37888
	ds_read_b128 v[208:211], v167 offset:38912
	ds_read_b128 v[212:215], v167 offset:39936
	s_add_u32 s98, s36, 0xfff80000
	s_addc_u32 s99, s37, -1
	s_mov_b32 m0, s17
	s_nop 0
	global_load_lds_dwordx4 v146, s[98:99]
	s_mov_b32 m0, s29
	s_nop 0
	global_load_lds_dwordx4 v148, s[98:99]
	s_mov_b32 m0, s33
	s_nop 0
	global_load_lds_dwordx4 v[222:223], off
	v_lshl_add_u64 v[222:223], s[36:37], 0, v[148:149]
	s_mov_b32 m0, s38
	s_nop 0
	global_load_lds_dwordx4 v[222:223], off
	s_waitcnt vmcnt(8)
	s_waitcnt lgkmcnt(0)
	s_barrier
	s_setprio 1
	s_waitcnt lgkmcnt(0)
	v_mfma_f32_16x16x32_bf16 v[126:129], v[130:133], v[180:183], v[126:129]
	v_mfma_f32_16x16x32_bf16 v[122:125], v[138:141], v[180:183], v[122:125]
	v_mfma_f32_16x16x32_bf16 v[114:117], v[130:133], v[192:195], v[114:117]
	v_mfma_f32_16x16x32_bf16 v[110:113], v[138:141], v[192:195], v[110:113]
	v_mfma_f32_16x16x32_bf16 v[98:101], v[130:133], v[200:203], v[98:101]
	v_mfma_f32_16x16x32_bf16 v[94:97], v[138:141], v[200:203], v[94:97]
	v_mfma_f32_16x16x32_bf16 v[82:85], v[130:133], v[208:211], v[82:85]
	v_mfma_f32_16x16x32_bf16 v[78:81], v[138:141], v[208:211], v[78:81]
	v_mfma_f32_16x16x32_bf16 v[126:129], v[134:137], v[188:191], v[126:129]
	v_mfma_f32_16x16x32_bf16 v[122:125], v[142:145], v[188:191], v[122:125]
	v_mfma_f32_16x16x32_bf16 v[114:117], v[134:137], v[196:199], v[114:117]
	v_mfma_f32_16x16x32_bf16 v[110:113], v[142:145], v[196:199], v[110:113]
	v_mfma_f32_16x16x32_bf16 v[98:101], v[134:137], v[204:207], v[98:101]
	v_mfma_f32_16x16x32_bf16 v[94:97], v[142:145], v[204:207], v[94:97]
	v_mfma_f32_16x16x32_bf16 v[82:85], v[134:137], v[212:215], v[82:85]
	v_mfma_f32_16x16x32_bf16 v[78:81], v[142:145], v[212:215], v[78:81]
	s_setprio 0
	s_setprio 1
	v_mfma_f32_16x16x32_bf16 v[118:121], v[158:161], v[180:183], v[118:121]
	v_mfma_f32_16x16x32_bf16 v[106:109], v[172:175], v[180:183], v[106:109]
	v_mfma_f32_16x16x32_bf16 v[102:105], v[158:161], v[192:195], v[102:105]
	v_mfma_f32_16x16x32_bf16 v[90:93], v[172:175], v[192:195], v[90:93]
	v_mfma_f32_16x16x32_bf16 v[86:89], v[158:161], v[200:203], v[86:89]
	v_mfma_f32_16x16x32_bf16 v[74:77], v[172:175], v[200:203], v[74:77]
	v_mfma_f32_16x16x32_bf16 v[70:73], v[158:161], v[208:211], v[70:73]
	v_mfma_f32_16x16x32_bf16 v[66:69], v[172:175], v[208:211], v[66:69]
	v_mfma_f32_16x16x32_bf16 v[118:121], v[168:171], v[188:191], v[118:121]
	v_mfma_f32_16x16x32_bf16 v[106:109], v[176:179], v[188:191], v[106:109]
	v_mfma_f32_16x16x32_bf16 v[102:105], v[168:171], v[196:199], v[102:105]
	v_mfma_f32_16x16x32_bf16 v[90:93], v[176:179], v[196:199], v[90:93]
	v_mfma_f32_16x16x32_bf16 v[86:89], v[168:171], v[204:207], v[86:89]
	v_mfma_f32_16x16x32_bf16 v[74:77], v[176:179], v[204:207], v[74:77]
	v_mfma_f32_16x16x32_bf16 v[70:73], v[168:171], v[212:215], v[70:73]
	v_mfma_f32_16x16x32_bf16 v[66:69], v[176:179], v[212:215], v[66:69]
	s_setprio 0
	s_barrier
; #define PG8_STAGE(bufoff, gbase, voff) do { _Pragma("unroll") for (int _i = 0; _i < 2; ++_i) \
;         __builtin_amdgcn_global_load_lds((const unsigned*)((const char*)(gbase) + (voff)[_i]), (PG8_LAS unsigned*)(lds + (bufoff) + ldsw + _i * 8192), 16, 0, 0); } while (0)
; #define PG8_LDA(dst, b, h) do { _Pragma("unroll") for (int m = 0; m < 4; ++m) _Pragma("unroll") for (int k = 0; k < 2; ++k) dst[m][k] = *(const PG8_LAS bf16x8*)(lds + PG8_SA(b, h) + aoff + m * 2048 + k * 1024); } while (0)
; #define PG8_MMA(ai, bj, At, Bt) do { __builtin_amdgcn_s_setprio(1); _Pragma("unroll") for (int m = 0; m < 4; ++m) _Pragma("unroll") for (int n = 0; n < 2; ++n) _Pragma("unroll") for (int k = 0; k < 2; ++k) \
;         acc[ai][bj][m][n] = __builtin_amdgcn_mfma_f32_16x16x32_bf16(Bt[n][k], At[m][k], acc[ai][bj][m][n], 0, 0, 0); __builtin_amdgcn_s_setprio(0); } while (0)
; #define PG8_WAIT_V(n) asm volatile("s_waitcnt vmcnt(" #n ")" ::: "memory")
; #define PG8_WAIT_L(n) asm volatile("s_waitcnt lgkmcnt(" #n ")" ::: "memory")
; #define PG8_BAR __builtin_amdgcn_s_barrier()
; #define PG8_SCHED __builtin_amdgcn_sched_barrier(0)
; template <class Epi, class Sched, bool ALIGN_EPI = false, bool SP2 = false>
; __device__ __forceinline__ void gemm_phase(PG8_LAS unsigned char* lds, const Gemm g, const Sched& S, const Epi& E) {
;     ...
;         for (int t = 0; t < nt; t += 2) {
;             const bool last = (t == nt - 2);
;             const char* a1 = cA + (size_t)(t + 1) * kstep;
;             const char* a2 = last ? nA : cA + (size_t)(t + 2) * kstep; const char* b2 = last ? nB : cB + (size_t)(t + 2) * kstep;
;     ...
;             PG8_LDA(At, 1, 1); PG8_STAGE(PG8_SB(1, 0), b3, voffB); PG8_STAGE(PG8_SB(1, 1), b3 + hstep, voffB); PG8_STAGE(PG8_SA(1, 0), a3, voffA);
;             PG8_WAIT_V(8); PG8_WAIT_L(0); PG8_BAR; PG8_MMA(1, 0, At, B0); PG8_MMA(1, 1, At, B1); PG8_BAR; PG8_SCHED;
	s_add_i32 s36, s54, s16
	v_lshl_add_u64 v[184:185], v[184:185], 0, s[8:9]
	s_mov_b32 m0, s36
	ds_read_b128 v[180:183], v167 offset:49152
	ds_read_b128 v[188:191], v167 offset:50176
	ds_read_b128 v[192:195], v167 offset:51200
	ds_read_b128 v[196:199], v167 offset:52224
	ds_read_b128 v[200:203], v167 offset:53248
	ds_read_b128 v[204:207], v167 offset:54272
	ds_read_b128 v[208:211], v167 offset:55296
	ds_read_b128 v[212:215], v167 offset:56320
	global_load_lds_dwordx4 v[184:185], off
	s_add_i32 m0, s36, 0x2000
	s_add_u32 s34, s34, 0x80080
	v_lshl_add_u64 v[184:185], v[216:217], 0, s[8:9]
	s_addc_u32 s35, s35, 0
	s_add_i32 s36, s55, s16
	global_load_lds_dwordx4 v[184:185], off
	v_lshl_add_u64 v[184:185], s[34:35], 0, v[146:147]
	s_mov_b32 m0, s36
	s_nop 0
	global_load_lds_dwordx4 v[184:185], off
	v_lshl_add_u64 v[184:185], s[34:35], 0, v[148:149]
	s_add_i32 m0, s36, 0x2000
	s_nop 0
	global_load_lds_dwordx4 v[184:185], off
	v_lshl_add_u64 v[184:185], v[218:219], 0, s[8:9]
	s_mov_b32 m0, s42
	s_nop 0
	v_lshl_add_u64 v[184:185], v[220:221], 0, s[8:9]
	s_mov_b32 m0, s43
	s_nop 0
	s_waitcnt vmcnt(6)
	s_waitcnt lgkmcnt(0)
	s_barrier
	s_setprio 1
	s_waitcnt lgkmcnt(0)
	v_mfma_f32_16x16x32_bf16 v[62:65], v[130:133], v[180:183], v[62:65]
	v_mfma_f32_16x16x32_bf16 v[58:61], v[138:141], v[180:183], v[58:61]
	v_mfma_f32_16x16x32_bf16 v[50:53], v[130:133], v[192:195], v[50:53]
	v_mfma_f32_16x16x32_bf16 v[46:49], v[138:141], v[192:195], v[46:49]
	v_mfma_f32_16x16x32_bf16 v[34:37], v[130:133], v[200:203], v[34:37]
	v_mfma_f32_16x16x32_bf16 v[30:33], v[138:141], v[200:203], v[30:33]
	v_mfma_f32_16x16x32_bf16 v[18:21], v[130:133], v[208:211], v[18:21]
	v_mfma_f32_16x16x32_bf16 v[14:17], v[138:141], v[208:211], v[14:17]
	v_mfma_f32_16x16x32_bf16 v[62:65], v[134:137], v[188:191], v[62:65]
	v_mfma_f32_16x16x32_bf16 v[58:61], v[142:145], v[188:191], v[58:61]
	v_mfma_f32_16x16x32_bf16 v[50:53], v[134:137], v[196:199], v[50:53]
	v_mfma_f32_16x16x32_bf16 v[46:49], v[142:145], v[196:199], v[46:49]
	v_mfma_f32_16x16x32_bf16 v[34:37], v[134:137], v[204:207], v[34:37]
	v_mfma_f32_16x16x32_bf16 v[30:33], v[142:145], v[204:207], v[30:33]
	v_mfma_f32_16x16x32_bf16 v[18:21], v[134:137], v[212:215], v[18:21]
	v_mfma_f32_16x16x32_bf16 v[14:17], v[142:145], v[212:215], v[14:17]
	s_setprio 0
	s_setprio 1
	v_mfma_f32_16x16x32_bf16 v[54:57], v[158:161], v[180:183], v[54:57]
	v_mfma_f32_16x16x32_bf16 v[42:45], v[172:175], v[180:183], v[42:45]
	v_mfma_f32_16x16x32_bf16 v[38:41], v[158:161], v[192:195], v[38:41]
	v_mfma_f32_16x16x32_bf16 v[26:29], v[172:175], v[192:195], v[26:29]
	v_mfma_f32_16x16x32_bf16 v[22:25], v[158:161], v[200:203], v[22:25]
	v_mfma_f32_16x16x32_bf16 v[10:13], v[172:175], v[200:203], v[10:13]
	v_mfma_f32_16x16x32_bf16 v[6:9], v[158:161], v[208:211], v[6:9]
	v_mfma_f32_16x16x32_bf16 v[2:5], v[172:175], v[208:211], v[2:5]
	v_mfma_f32_16x16x32_bf16 v[54:57], v[168:171], v[188:191], v[54:57]
	v_mfma_f32_16x16x32_bf16 v[42:45], v[176:179], v[188:191], v[42:45]
	v_mfma_f32_16x16x32_bf16 v[38:41], v[168:171], v[196:199], v[38:41]
	v_mfma_f32_16x16x32_bf16 v[26:29], v[176:179], v[196:199], v[26:29]
	v_mfma_f32_16x16x32_bf16 v[22:25], v[168:171], v[204:207], v[22:25]
	v_mfma_f32_16x16x32_bf16 v[10:13], v[176:179], v[204:207], v[10:13]
	v_mfma_f32_16x16x32_bf16 v[6:9], v[168:171], v[212:215], v[6:9]
	v_mfma_f32_16x16x32_bf16 v[2:5], v[176:179], v[212:215], v[2:5]
	s_setprio 0
	s_barrier
	s_add_i32 s53, s53, 2
	s_add_u32 s30, s30, 0x100
	s_addc_u32 s31, s31, 0
	s_add_u32 s51, s51, 0x100
	s_addc_u32 s52, s52, 0
	s_cmp_gt_u32 s53, 29
	s_cbranch_scc0 .LBB0_941
	s_and_b64 vcc, exec, s[18:19]
	s_cbranch_vccz .LBB0_944
	s_barrier

; template <bool NT_LD, bool NT_ST> DI void norm_row2(const float* xrow0, const float* xrow1, const float* g, const float* sc, const float* sh, bf16* obf0, bf16* obf1, float* of0, float* of1, int lane) {
;     const f32x4* xr0 = (const f32x4*)xrow0 + lane; const f32x4* xr1 = (const f32x4*)xrow1 + lane;
;     f32x4 v0[8], v1[8]; float s0 = 0.f, s1 = 0.f;
; #pragma unroll
;     for (int j = 0; j < 8; ++j) { if (NT_LD) { v0[j] = __builtin_nontemporal_load(xr0 + 64 * j); v1[j] = __builtin_nontemporal_load(xr1 + 64 * j); } else { v0[j] = xr0[64 * j]; v1[j] = xr1[64 * j]; } }
; #pragma unroll
;     for (int j = 0; j < 8; ++j) { s0 += (v0[j].x * v0[j].x + v0[j].y * v0[j].y) + (v0[j].z * v0[j].z + v0[j].w * v0[j].w); s1 += (v1[j].x * v1[j].x + v1[j].y * v1[j].y) + (v1[j].z * v1[j].z + v1[j].w * v1[j].w); }
; #pragma unroll
;     for (int o = 1; o < 64; o <<= 1) { s0 += __shfl_xor(s0, o); s1 += __shfl_xor(s1, o); }
;     const float r0 = 1.0f / sqrtf(s0 * (1.0f / DM) + EPS), r1 = 1.0f / sqrtf(s1 * (1.0f / DM) + EPS);
; __global__ void __launch_bounds__(512, 2) fwd_mega(Args args) {
;     ...
;         for (int m = 2 * gw; m < M; m += 2 * NGW) { const int b = m >> 13; norm_row2<false, false>(out + (size_t)m * DM, out + (size_t)(m + 1) * DM, norm2_g, modall + b * NMOD + 4 * DM, modall + b * NMOD + 3 * DM, H2 + (size_t)m * DM, H2 + (size_t)(m + 1) * DM, nullptr, nullptr, lane); }
.LBB0_1019:
	global_load_dwordx4 v[10:13], v[76:77], off
	global_load_dwordx4 v[14:17], v[76:77], off offset:1024
	v_add_co_u32_e32 v18, vcc, 0x2000, v76
	s_waitcnt lgkmcnt(6)
	global_load_dwordx4 v[6:9], v[76:77], off offset:2048
	global_load_dwordx4 v[2:5], v[76:77], off offset:3072
	global_load_dwordx4 v[58:61], v[64:65], off
	v_addc_co_u32_e32 v19, vcc, 0, v77, vcc
	v_add_co_u32_e32 v22, vcc, 0x1000, v76
	global_load_dwordx4 v[98:101], v[18:19], off
	global_load_dwordx4 v[102:105], v[18:19], off offset:1024
	global_load_dwordx4 v[54:57], v[18:19], off offset:2048
	global_load_dwordx4 v[50:53], v[18:19], off offset:3072
	v_addc_co_u32_e32 v23, vcc, 0, v77, vcc
	v_add_co_u32_e32 v80, vcc, s3, v76
	global_load_dwordx4 v[42:45], v[22:23], off
	global_load_dwordx4 v[34:37], v[22:23], off offset:1024
	global_load_dwordx4 v[18:21], v[22:23], off offset:3072
	global_load_dwordx4 v[26:29], v[22:23], off offset:2048
	v_addc_co_u32_e32 v81, vcc, 0, v77, vcc
	global_load_dwordx4 v[46:49], v[80:81], off
	global_load_dwordx4 v[38:41], v[80:81], off offset:1024
	global_load_dwordx4 v[30:33], v[80:81], off offset:2048
	global_load_dwordx4 v[22:25], v[80:81], off offset:3072
	v_add_co_u32_e64 v78, s[0:1], s9, v74
	s_ashr_i32 s4, s8, 13
	s_nop 0
	v_addc_co_u32_e64 v79, s[0:1], 0, v75, s[0:1]
	s_mul_i32 s0, s4, 0x3000
	s_ashr_i32 s1, s0, 31
	s_lshl_b64 s[0:1], s[0:1], 2
	s_add_u32 s0, s14, s0
	s_addc_u32 s1, s15, s1
	v_lshl_add_u64 v[82:83], v[62:63], 4, s[0:1]
	v_add_co_u32_e32 v80, vcc, s26, v82
	v_lshl_add_u64 v[86:87], v[82:83], 0, s[22:23]
	s_nop 0
	v_addc_co_u32_e32 v81, vcc, 0, v83, vcc
	v_lshl_add_u64 v[88:89], v[82:83], 0, s[24:25]
	v_add_co_u32_e32 v82, vcc, s27, v82
	s_add_i32 s8, s8, s16
	s_nop 0
	v_addc_co_u32_e32 v83, vcc, 0, v83, vcc
	global_load_dwordx4 v[106:109], v[80:81], off offset:-4096
	global_load_dwordx4 v[110:113], v[82:83], off offset:-4096
	v_lshl_add_u64 v[76:77], v[76:77], 0, s[20:21]
	s_cmp_lt_i32 s8, 0x8000
	s_waitcnt vmcnt(18)
	v_mov_b32_e32 v116, v11
	s_waitcnt vmcnt(17)
	v_mov_b32_e32 v117, v15
	v_mov_b32_e32 v120, v13
	v_mov_b32_e32 v121, v17
	v_mov_b32_e32 v114, v10
	v_mov_b32_e32 v115, v14
	v_mov_b32_e32 v118, v12
	v_mov_b32_e32 v119, v16
	s_waitcnt vmcnt(16)
	v_pk_mul_f32 v[122:123], v[8:9], v[8:9]
	v_pk_mul_f32 v[124:125], v[6:7], v[6:7]
	v_pk_mul_f32 v[116:117], v[116:117], v[116:117]
	v_pk_mul_f32 v[120:121], v[120:121], v[120:121]
	s_waitcnt vmcnt(15)
	v_mul_f32_e32 v84, v3, v3
	v_mul_f32_e32 v126, v5, v5
	v_pk_mov_b32 v[128:129], v[124:125], v[122:123] op_sel:[1,0]
	v_mov_b32_e32 v125, v123
	v_pk_fma_f32 v[114:115], v[114:115], v[114:115], v[116:117]
	v_pk_fma_f32 v[116:117], v[118:119], v[118:119], v[120:121]
	s_waitcnt vmcnt(13)
	v_mov_b32_e32 v120, v99
	s_waitcnt vmcnt(12)
	v_mov_b32_e32 v121, v103
	v_mov_b32_e32 v132, v101
	v_mov_b32_e32 v133, v105
	v_pk_fma_f32 v[122:123], v[2:3], v[2:3], v[84:85] op_sel_hi:[1,1,0]
	v_pk_fma_f32 v[126:127], v[4:5], v[4:5], v[126:127] op_sel_hi:[1,1,0]
	v_mov_b32_e32 v118, v98
	v_mov_b32_e32 v119, v102
	v_mov_b32_e32 v130, v100
	v_mov_b32_e32 v131, v104
	v_pk_add_f32 v[124:125], v[128:129], v[124:125]
	s_waitcnt vmcnt(11)
	v_pk_mul_f32 v[128:129], v[56:57], v[56:57]
	v_pk_mul_f32 v[134:135], v[54:55], v[54:55]
	v_pk_add_f32 v[114:115], v[114:115], v[116:117]
	v_pk_mul_f32 v[116:117], v[120:121], v[120:121]
	v_pk_mul_f32 v[120:121], v[132:133], v[132:133]
	v_pk_mov_b32 v[132:133], v[134:135], v[128:129] op_sel:[1,0]
	v_mov_b32_e32 v135, v129
	s_waitcnt vmcnt(9)
	v_mul_f32_e32 v97, v42, v42
	v_mul_f32_e32 v123, v43, v43
	v_mul_f32_e32 v127, v44, v44
	v_mul_f32_e32 v143, v45, v45
	v_pk_add_f32 v[124:125], v[124:125], v[124:125] op_sel:[0,1] op_sel_hi:[1,0]
	v_pk_fma_f32 v[116:117], v[118:119], v[118:119], v[116:117]
	v_pk_fma_f32 v[118:119], v[130:131], v[130:131], v[120:121]
	v_pk_add_f32 v[114:115], v[114:115], v[114:115] op_sel:[0,1] op_sel_hi:[1,0]
	v_mul_f32_e32 v84, v51, v51
	v_mul_f32_e32 v136, v53, v53
	s_waitcnt vmcnt(8)
	v_pk_mul_f32 v[138:139], v[36:37], v[36:37]
	v_pk_mul_f32 v[140:141], v[34:35], v[34:35]
	v_pk_add_f32 v[120:121], v[132:133], v[134:135]
	v_mov_b32_e32 v125, v123
	v_mov_b32_e32 v123, v127
	v_mov_b32_e32 v127, v143
	v_pk_add_f32 v[116:117], v[116:117], v[118:119]
	v_mov_b32_e32 v115, v97
	v_pk_fma_f32 v[128:129], v[50:51], v[50:51], v[84:85] op_sel_hi:[1,1,0]
	v_pk_fma_f32 v[136:137], v[52:53], v[52:53], v[136:137] op_sel_hi:[1,1,0]
	s_waitcnt vmcnt(5)
	v_mul_f32_e32 v149, v46, v46
	v_mul_f32_e32 v150, v47, v47
	v_pk_mov_b32 v[130:131], v[140:141], v[138:139] op_sel:[1,0]
	v_mov_b32_e32 v141, v139
	v_pk_add_f32 v[118:119], v[122:123], v[126:127]
	v_pk_add_f32 v[120:121], v[120:121], v[120:121] op_sel:[0,1] op_sel_hi:[1,0]
	v_pk_add_f32 v[114:115], v[114:115], v[124:125]
	v_pk_add_f32 v[116:117], v[116:117], v[116:117] op_sel:[0,1] op_sel_hi:[1,0]
	v_mul_f32_e32 v84, v27, v27
	v_mul_f32_e32 v142, v29, v29
	v_mul_f32_e32 v129, v48, v48
	v_mul_f32_e32 v137, v49, v49
	s_waitcnt vmcnt(4)
	v_pk_mul_f32 v[132:133], v[40:41], v[40:41]
	v_pk_mul_f32 v[134:135], v[38:39], v[38:39]
	v_pk_add_f32 v[122:123], v[130:131], v[140:141]
	v_mov_b32_e32 v121, v150
	v_pk_add_f32 v[114:115], v[114:115], v[118:119]
	v_mov_b32_e32 v117, v149
	v_mul_f32_e32 v145, v18, v18
	v_mul_f32_e32 v146, v19, v19
	v_mul_f32_e32 v147, v20, v20
	v_mul_f32_e32 v148, v21, v21
	v_pk_fma_f32 v[138:139], v[26:27], v[26:27], v[84:85] op_sel_hi:[1,1,0]
	v_pk_fma_f32 v[142:143], v[28:29], v[28:29], v[142:143] op_sel_hi:[1,1,0]
	v_pk_mov_b32 v[126:127], v[134:135], v[132:133] op_sel:[1,0]
	v_mov_b32_e32 v135, v133
	v_pk_add_f32 v[124:125], v[128:129], v[136:137]
	v_pk_add_f32 v[122:123], v[122:123], v[122:123] op_sel:[0,1] op_sel_hi:[1,0]
	v_pk_add_f32 v[116:117], v[116:117], v[120:121]
	v_pk_add_f32 v[114:115], v[114:115], v[114:115] op_sel:[0,1] op_sel_hi:[1,0]
	s_waitcnt vmcnt(3)
; template <bool NT_LD, bool NT_ST> DI void norm_row2(const float* xrow0, const float* xrow1, const float* g, const float* sc, const float* sh, bf16* obf0, bf16* obf1, float* of0, float* of1, int lane) {
;     ...
;     for (int j = 0; j < 8; ++j) { s0 += (v0[j].x * v0[j].x + v0[j].y * v0[j].y) + (v0[j].z * v0[j].z + v0[j].w * v0[j].w); s1 += (v1[j].x * v1[j].x + v1[j].y * v1[j].y) + (v1[j].z * v1[j].z + v1[j].w * v1[j].w); }
; #pragma unroll
;     for (int o = 1; o < 64; o <<= 1) { s0 += __shfl_xor(s0, o); s1 += __shfl_xor(s1, o); }
;     const float r0 = 1.0f / sqrtf(s0 * (1.0f / DM) + EPS), r1 = 1.0f / sqrtf(s1 * (1.0f / DM) + EPS);
; #pragma unroll
;     for (int j = 0; j < 8; ++j) {
;         const int c4 = lane + 64 * j;
;         const f32x4 gg = ((const f32x4*)g)[c4];
;         f32x4 y0 = v0[j] * r0 * gg, y1 = v1[j] * r1 * gg;
;         if (sc) { const f32x4 a = ((const f32x4*)sc)[c4] + 1.0f, bsh = ((const f32x4*)sh)[c4]; y0 = y0 * a + bsh; y1 = y1 * a + bsh; }
	v_mul_f32_e32 v84, v31, v31
	v_mul_f32_e32 v144, v33, v33
	v_mov_b32_e32 v139, v147
	v_mov_b32_e32 v143, v148
	v_pk_add_f32 v[126:127], v[126:127], v[134:135]
	v_mov_b32_e32 v123, v146
	v_pk_add_f32 v[116:117], v[116:117], v[124:125]
	v_mov_b32_e32 v115, v145
	s_waitcnt vmcnt(2)
	v_mul_f32_e32 v151, v22, v22
	v_mul_f32_e32 v152, v23, v23
	v_mul_f32_e32 v153, v24, v24
	v_mul_f32_e32 v154, v25, v25
	v_pk_fma_f32 v[130:131], v[30:31], v[30:31], v[84:85] op_sel_hi:[1,1,0]
	v_pk_fma_f32 v[132:133], v[32:33], v[32:33], v[144:145] op_sel_hi:[1,1,0]
	v_pk_add_f32 v[128:129], v[138:139], v[142:143]
	v_pk_add_f32 v[118:119], v[126:127], v[126:127] op_sel:[0,1] op_sel_hi:[1,0]
	v_pk_add_f32 v[114:115], v[114:115], v[122:123]
	v_pk_add_f32 v[116:117], v[116:117], v[116:117] op_sel:[0,1] op_sel_hi:[1,0]
	v_mov_b32_e32 v131, v153
	v_mov_b32_e32 v133, v154
	v_mov_b32_e32 v119, v152
	v_pk_add_f32 v[114:115], v[114:115], v[128:129]
	v_mov_b32_e32 v117, v151
	v_pk_add_f32 v[126:127], v[130:131], v[132:133]
	v_add_f32_e32 v84, v114, v115
	v_pk_add_f32 v[114:115], v[116:117], v[118:119]
	ds_bpermute_b32 v97, v85, v84
	v_pk_add_f32 v[114:115], v[114:115], v[126:127]
	s_waitcnt vmcnt(1)
	v_pk_add_f32 v[108:109], v[108:109], 1.0 op_sel_hi:[1,0]
	v_add_f32_e32 v114, v114, v115
	ds_bpermute_b32 v115, v85, v114
	s_waitcnt lgkmcnt(1)
	v_add_f32_e32 v84, v84, v97
	ds_bpermute_b32 v97, v90, v84
	v_pk_add_f32 v[106:107], v[106:107], 1.0 op_sel_hi:[1,0]
	s_waitcnt lgkmcnt(1)
	v_add_f32_e32 v114, v114, v115
	ds_bpermute_b32 v115, v90, v114
	s_waitcnt lgkmcnt(1)
	v_add_f32_e32 v84, v84, v97
	ds_bpermute_b32 v97, v91, v84
	s_waitcnt lgkmcnt(1)
	v_add_f32_e32 v114, v114, v115
	ds_bpermute_b32 v115, v91, v114
	s_waitcnt lgkmcnt(1)
	v_add_f32_e32 v84, v84, v97
	ds_bpermute_b32 v97, v92, v84
	s_waitcnt lgkmcnt(1)
	v_add_f32_e32 v114, v114, v115
	ds_bpermute_b32 v115, v92, v114
	s_waitcnt lgkmcnt(1)
	v_add_f32_e32 v84, v84, v97
	ds_bpermute_b32 v97, v93, v84
	s_waitcnt lgkmcnt(1)
	v_add_f32_e32 v114, v114, v115
	ds_bpermute_b32 v115, v93, v114
	s_waitcnt lgkmcnt(1)
	v_add_f32_e32 v84, v84, v97
	ds_bpermute_b32 v97, v94, v84
	s_waitcnt lgkmcnt(1)
	v_add_f32_e32 v114, v114, v115
	ds_bpermute_b32 v115, v94, v114
	s_waitcnt lgkmcnt(1)
	v_add_f32_e32 v84, v84, v97
	v_fmamk_f32 v84, v84, 0x3a000000, v95
	v_cmp_gt_f32_e32 vcc, s17, v84
	s_waitcnt lgkmcnt(0)
	v_add_f32_e32 v97, v114, v115
	v_mul_f32_e32 v114, 0x4f800000, v84
	v_cndmask_b32_e32 v84, v84, v114, vcc
	v_fmamk_f32 v97, v97, 0x3a000000, v95
	v_sqrt_f32_e32 v114, v84
	v_mul_f32_e32 v115, 0x4f800000, v97
	v_cmp_gt_f32_e64 s[0:1], s17, v97
	v_add_u32_e32 v116, -1, v114
	s_nop 0
	v_cndmask_b32_e64 v97, v97, v115, s[0:1]
	v_sqrt_f32_e32 v115, v97
	v_add_u32_e32 v117, 1, v114
	v_fma_f32 v118, -v116, v114, v84
	v_fma_f32 v119, -v117, v114, v84
	v_cmp_ge_f32_e64 s[4:5], 0, v118
	v_add_u32_e32 v118, 1, v115
	s_nop 0
	v_cndmask_b32_e64 v114, v114, v116, s[4:5]
	v_add_u32_e32 v116, -1, v115
	v_cmp_lt_f32_e64 s[4:5], 0, v119
	v_fma_f32 v119, -v118, v115, v97
	s_nop 0
	v_cndmask_b32_e64 v114, v114, v117, s[4:5]
	v_fma_f32 v117, -v116, v115, v97
	v_cmp_ge_f32_e64 s[4:5], 0, v117
	v_mul_f32_e32 v120, 0x37800000, v114
	v_cndmask_b32_e32 v114, v114, v120, vcc
	v_cndmask_b32_e64 v115, v115, v116, s[4:5]
	v_cmp_lt_f32_e64 s[4:5], 0, v119
	v_cmp_class_f32_e32 vcc, v84, v96
	s_nop 0
	v_cndmask_b32_e64 v115, v115, v118, s[4:5]
	v_cndmask_b32_e32 v84, v114, v84, vcc
	v_mul_f32_e32 v114, 0x37800000, v115
	v_div_scale_f32 v116, s[4:5], v84, v84, 1.0
	v_cndmask_b32_e64 v114, v115, v114, s[0:1]
	v_cmp_class_f32_e64 s[0:1], v97, v96
	v_rcp_f32_e32 v115, v116
	v_div_scale_f32 v117, vcc, 1.0, v84, 1.0
	v_cndmask_b32_e64 v97, v114, v97, s[0:1]
	v_div_scale_f32 v114, s[0:1], v97, v97, 1.0
	v_rcp_f32_e32 v119, v114
	v_fma_f32 v120, -v116, v115, 1.0
	v_fmac_f32_e32 v115, v120, v115
	v_mul_f32_e32 v120, v117, v115
	v_fma_f32 v121, -v114, v119, 1.0
	v_div_scale_f32 v118, s[0:1], 1.0, v97, 1.0
	v_fma_f32 v122, -v116, v120, v117
	v_fmac_f32_e32 v119, v121, v119
	v_fmac_f32_e32 v120, v122, v115
	v_mul_f32_e32 v121, v118, v119
	v_fma_f32 v116, -v116, v120, v117
	v_fma_f32 v117, -v114, v121, v118
	v_fmac_f32_e32 v121, v117, v119
	v_div_fmas_f32 v115, v116, v115, v120
	v_fma_f32 v114, -v114, v121, v118
	s_mov_b64 vcc, s[0:1]
	v_div_fixup_f32 v84, v115, v84, 1.0
	v_div_fmas_f32 v118, v114, v119, v121
	v_pk_mul_f32 v[12:13], v[12:13], v[84:85] op_sel_hi:[1,0]
	v_pk_mul_f32 v[114:115], v[10:11], v[84:85] op_sel_hi:[1,0]
	v_div_fixup_f32 v10, v118, v97, 1.0
	v_pk_mul_f32 v[116:117], v[14:15], v[84:85] op_sel_hi:[1,0]
	v_pk_mul_f32 v[14:15], v[58:59], v[114:115]
	v_pk_mul_f32 v[12:13], v[60:61], v[12:13]
	v_pk_mul_f32 v[100:101], v[100:101], v[10:11] op_sel_hi:[1,0]
	v_pk_mul_f32 v[98:99], v[98:99], v[10:11] op_sel_hi:[1,0]
	s_waitcnt vmcnt(0)
; DI unsigned pk2(float lo, float hi) { f32x2_t v = {lo, hi}; bf16x2_t b = __builtin_convertvector(v, bf16x2_t); return __builtin_bit_cast(unsigned, b); }
; template <bool NT_LD, bool NT_ST> DI void norm_row2(const float* xrow0, const float* xrow1, const float* g, const float* sc, const float* sh, bf16* obf0, bf16* obf1, float* of0, float* of1, int lane) {
;     ...
;     for (int j = 0; j < 8; ++j) {
;         const int c4 = lane + 64 * j;
;         const f32x4 gg = ((const f32x4*)g)[c4];
;         f32x4 y0 = v0[j] * r0 * gg, y1 = v1[j] * r1 * gg;
;         if (sc) { const f32x4 a = ((const f32x4*)sc)[c4] + 1.0f, bsh = ((const f32x4*)sh)[c4]; y0 = y0 * a + bsh; y1 = y1 * a + bsh; }
;         if (obf0) { u32x2 o0; o0.x = pk2(y0.x, y0.y); o0.y = pk2(y0.z, y0.w); ((u32x2*)obf0)[c4] = o0; u32x2 o1; o1.x = pk2(y1.x, y1.y); o1.y = pk2(y1.z, y1.w); ((u32x2*)obf1)[c4] = o1; }
	v_pk_fma_f32 v[12:13], v[108:109], v[12:13], v[112:113]
	v_pk_fma_f32 v[14:15], v[106:107], v[14:15], v[110:111]
	v_pk_mul_f32 v[58:59], v[58:59], v[98:99]
	v_pk_mul_f32 v[60:61], v[60:61], v[100:101]
	v_cvt_pk_bf16_f32 v14, v14, v15
	v_cvt_pk_bf16_f32 v15, v12, v13
	v_pk_fma_f32 v[12:13], v[108:109], v[60:61], v[112:113]
	v_pk_fma_f32 v[58:59], v[106:107], v[58:59], v[110:111]
	global_store_dwordx2 v[74:75], v[14:15], off
	v_cvt_pk_bf16_f32 v14, v58, v59
	v_cvt_pk_bf16_f32 v15, v12, v13
	global_store_dwordx2 v[78:79], v[14:15], off
	global_load_dwordx4 v[12:15], v[64:65], off offset:1024
	s_nop 0
	global_load_dwordx4 v[58:61], v[86:87], off offset:1024
	global_load_dwordx4 v[98:101], v[88:89], off offset:1024
	v_pk_mul_f32 v[16:17], v[16:17], v[84:85] op_sel_hi:[1,0]
	v_pk_mul_f32 v[104:105], v[104:105], v[10:11] op_sel_hi:[1,0]
	v_pk_mul_f32 v[102:103], v[102:103], v[10:11] op_sel_hi:[1,0]
	v_pk_mul_f32 v[8:9], v[8:9], v[84:85] op_sel_hi:[1,0]
	v_pk_mul_f32 v[6:7], v[6:7], v[84:85] op_sel_hi:[1,0]
	v_pk_mul_f32 v[54:55], v[54:55], v[10:11] op_sel_hi:[1,0]
	v_pk_mul_f32 v[4:5], v[4:5], v[84:85] op_sel_hi:[1,0]
	v_pk_mul_f32 v[2:3], v[2:3], v[84:85] op_sel_hi:[1,0]
	v_pk_mul_f32 v[50:51], v[50:51], v[10:11] op_sel_hi:[1,0]
	v_pk_mul_f32 v[42:43], v[42:43], v[84:85] op_sel_hi:[1,0]
	v_pk_mul_f32 v[46:47], v[46:47], v[10:11] op_sel_hi:[1,0]
	v_pk_mul_f32 v[34:35], v[34:35], v[84:85] op_sel_hi:[1,0]
	v_pk_mul_f32 v[38:39], v[38:39], v[10:11] op_sel_hi:[1,0]
	v_pk_mul_f32 v[26:27], v[26:27], v[84:85] op_sel_hi:[1,0]
	v_pk_mul_f32 v[30:31], v[30:31], v[10:11] op_sel_hi:[1,0]
	v_pk_mul_f32 v[18:19], v[18:19], v[84:85] op_sel_hi:[1,0]
	s_waitcnt vmcnt(2)
	v_pk_mul_f32 v[106:107], v[12:13], v[116:117]
	v_pk_mul_f32 v[16:17], v[14:15], v[16:17]
	s_waitcnt vmcnt(1)
	v_pk_add_f32 v[60:61], v[60:61], 1.0 op_sel_hi:[1,0]
	v_pk_add_f32 v[58:59], v[58:59], 1.0 op_sel_hi:[1,0]
	v_pk_mul_f32 v[12:13], v[12:13], v[102:103]
	v_pk_mul_f32 v[14:15], v[14:15], v[104:105]
	s_waitcnt vmcnt(0)
	v_pk_fma_f32 v[16:17], v[60:61], v[16:17], v[100:101]
	v_pk_fma_f32 v[102:103], v[58:59], v[106:107], v[98:99]
	v_pk_fma_f32 v[14:15], v[60:61], v[14:15], v[100:101]
	v_pk_fma_f32 v[12:13], v[58:59], v[12:13], v[98:99]
	v_cvt_pk_bf16_f32 v58, v102, v103
	v_cvt_pk_bf16_f32 v59, v16, v17
	v_cvt_pk_bf16_f32 v12, v12, v13
	v_cvt_pk_bf16_f32 v13, v14, v15
	global_store_dwordx2 v[74:75], v[58:59], off offset:512
	global_store_dwordx2 v[78:79], v[12:13], off offset:512
	global_load_dwordx4 v[12:15], v[64:65], off offset:2048
	s_nop 0
	global_load_dwordx4 v[58:61], v[86:87], off offset:2048
	global_load_dwordx4 v[98:101], v[88:89], off offset:2048
	v_pk_mul_f32 v[16:17], v[56:57], v[10:11] op_sel_hi:[1,0]
	s_waitcnt vmcnt(2)
	v_pk_mul_f32 v[6:7], v[6:7], v[12:13]
	v_pk_mul_f32 v[8:9], v[8:9], v[14:15]
	v_pk_mul_f32 v[12:13], v[54:55], v[12:13]
	v_pk_mul_f32 v[14:15], v[16:17], v[14:15]
	s_waitcnt vmcnt(1)
	v_pk_add_f32 v[16:17], v[60:61], 1.0 op_sel_hi:[1,0]
	v_pk_add_f32 v[54:55], v[58:59], 1.0 op_sel_hi:[1,0]
	s_waitcnt vmcnt(0)
	v_pk_fma_f32 v[8:9], v[8:9], v[16:17], v[100:101]
	v_pk_fma_f32 v[6:7], v[6:7], v[54:55], v[98:99]
	v_pk_fma_f32 v[14:15], v[14:15], v[16:17], v[100:101]
	v_pk_fma_f32 v[12:13], v[12:13], v[54:55], v[98:99]
	v_cvt_pk_bf16_f32 v6, v6, v7
	v_cvt_pk_bf16_f32 v7, v8, v9
	v_cvt_pk_bf16_f32 v8, v12, v13
	v_cvt_pk_bf16_f32 v9, v14, v15
	global_store_dwordx2 v[74:75], v[6:7], off offset:1024
	global_store_dwordx2 v[78:79], v[8:9], off offset:1024
	global_load_dwordx4 v[6:9], v[64:65], off offset:3072
	s_nop 0
	global_load_dwordx4 v[12:15], v[86:87], off offset:3072
	global_load_dwordx4 v[54:57], v[88:89], off offset:3072
	v_pk_mul_f32 v[16:17], v[52:53], v[10:11] op_sel_hi:[1,0]
	s_waitcnt vmcnt(2)
	v_pk_mul_f32 v[2:3], v[2:3], v[6:7]
	v_pk_mul_f32 v[4:5], v[4:5], v[8:9]
	s_waitcnt vmcnt(1)
	v_pk_add_f32 v[14:15], v[14:15], 1.0 op_sel_hi:[1,0]
	v_pk_add_f32 v[12:13], v[12:13], 1.0 op_sel_hi:[1,0]
	v_pk_mul_f32 v[6:7], v[50:51], v[6:7]
	v_pk_mul_f32 v[8:9], v[16:17], v[8:9]
	s_waitcnt vmcnt(0)
; DI unsigned pk2(float lo, float hi) { f32x2_t v = {lo, hi}; bf16x2_t b = __builtin_convertvector(v, bf16x2_t); return __builtin_bit_cast(unsigned, b); }
; template <bool NT_LD, bool NT_ST> DI void norm_row2(const float* xrow0, const float* xrow1, const float* g, const float* sc, const float* sh, bf16* obf0, bf16* obf1, float* of0, float* of1, int lane) {
;     ...
;     for (int j = 0; j < 8; ++j) {
;         const int c4 = lane + 64 * j;
;         const f32x4 gg = ((const f32x4*)g)[c4];
;         f32x4 y0 = v0[j] * r0 * gg, y1 = v1[j] * r1 * gg;
;         if (sc) { const f32x4 a = ((const f32x4*)sc)[c4] + 1.0f, bsh = ((const f32x4*)sh)[c4]; y0 = y0 * a + bsh; y1 = y1 * a + bsh; }
;         if (obf0) { u32x2 o0; o0.x = pk2(y0.x, y0.y); o0.y = pk2(y0.z, y0.w); ((u32x2*)obf0)[c4] = o0; u32x2 o1; o1.x = pk2(y1.x, y1.y); o1.y = pk2(y1.z, y1.w); ((u32x2*)obf1)[c4] = o1; }
;         else if (NT_ST) { __builtin_nontemporal_store(y0, (f32x4*)of0 + c4); __builtin_nontemporal_store(y1, (f32x4*)of1 + c4); }
;         else { ((f32x4*)of0)[c4] = y0; ((f32x4*)of1)[c4] = y1; }
; __global__ void __launch_bounds__(512, 2) fwd_mega(Args args) {
;     ...
;         for (int m = 2 * gw; m < M; m += 2 * NGW) { const int b = m >> 13; norm_row2<false, false>(out + (size_t)m * DM, out + (size_t)(m + 1) * DM, norm2_g, modall + b * NMOD + 4 * DM, modall + b * NMOD + 3 * DM, H2 + (size_t)m * DM, H2 + (size_t)(m + 1) * DM, nullptr, nullptr, lane); }
	v_pk_fma_f32 v[4:5], v[4:5], v[14:15], v[56:57]
	v_pk_fma_f32 v[2:3], v[2:3], v[12:13], v[54:55]
	v_pk_fma_f32 v[8:9], v[8:9], v[14:15], v[56:57]
	v_pk_fma_f32 v[6:7], v[6:7], v[12:13], v[54:55]
	v_cvt_pk_bf16_f32 v2, v2, v3
	v_cvt_pk_bf16_f32 v3, v4, v5
	v_cvt_pk_bf16_f32 v4, v6, v7
	v_cvt_pk_bf16_f32 v5, v8, v9
	global_store_dwordx2 v[74:75], v[2:3], off offset:1536
	global_store_dwordx2 v[78:79], v[4:5], off offset:1536
	global_load_dwordx4 v[2:5], v[66:67], off
	s_nop 0
	global_load_dwordx4 v[6:9], v[80:81], off
	global_load_dwordx4 v[12:15], v[82:83], off
	v_pk_mul_f32 v[16:17], v[44:45], v[84:85] op_sel_hi:[1,0]
	v_pk_mul_f32 v[44:45], v[48:49], v[10:11] op_sel_hi:[1,0]
	s_waitcnt vmcnt(2)
	v_pk_mul_f32 v[42:43], v[42:43], v[2:3]
	v_pk_mul_f32 v[16:17], v[16:17], v[4:5]
	s_waitcnt vmcnt(1)
	v_pk_add_f32 v[8:9], v[8:9], 1.0 op_sel_hi:[1,0]
	v_pk_add_f32 v[6:7], v[6:7], 1.0 op_sel_hi:[1,0]
	v_pk_mul_f32 v[2:3], v[46:47], v[2:3]
	v_pk_mul_f32 v[4:5], v[44:45], v[4:5]
	s_waitcnt vmcnt(0)
	v_pk_fma_f32 v[16:17], v[16:17], v[8:9], v[14:15]
	v_pk_fma_f32 v[42:43], v[42:43], v[6:7], v[12:13]
	v_pk_fma_f32 v[4:5], v[4:5], v[8:9], v[14:15]
	v_pk_fma_f32 v[2:3], v[2:3], v[6:7], v[12:13]
	v_cvt_pk_bf16_f32 v6, v42, v43
	v_cvt_pk_bf16_f32 v7, v16, v17
	v_cvt_pk_bf16_f32 v2, v2, v3
	v_cvt_pk_bf16_f32 v3, v4, v5
	global_store_dwordx2 v[74:75], v[6:7], off offset:2048
	global_store_dwordx2 v[78:79], v[2:3], off offset:2048
	global_load_dwordx4 v[2:5], v[68:69], off
	s_nop 0
	global_load_dwordx4 v[6:9], v[80:81], off offset:1024
	global_load_dwordx4 v[12:15], v[82:83], off offset:1024
	v_pk_mul_f32 v[16:17], v[36:37], v[84:85] op_sel_hi:[1,0]
	v_pk_mul_f32 v[36:37], v[40:41], v[10:11] op_sel_hi:[1,0]
	s_waitcnt vmcnt(2)
	v_pk_mul_f32 v[34:35], v[34:35], v[2:3]
	v_pk_mul_f32 v[16:17], v[16:17], v[4:5]
	s_waitcnt vmcnt(1)
	v_pk_add_f32 v[8:9], v[8:9], 1.0 op_sel_hi:[1,0]
	v_pk_add_f32 v[6:7], v[6:7], 1.0 op_sel_hi:[1,0]
	v_pk_mul_f32 v[2:3], v[38:39], v[2:3]
	v_pk_mul_f32 v[4:5], v[36:37], v[4:5]
	s_waitcnt vmcnt(0)
	v_pk_fma_f32 v[16:17], v[16:17], v[8:9], v[14:15]
	v_pk_fma_f32 v[34:35], v[34:35], v[6:7], v[12:13]
	v_pk_fma_f32 v[4:5], v[4:5], v[8:9], v[14:15]
	v_pk_fma_f32 v[2:3], v[2:3], v[6:7], v[12:13]
	v_cvt_pk_bf16_f32 v6, v34, v35
	v_cvt_pk_bf16_f32 v7, v16, v17
	v_cvt_pk_bf16_f32 v2, v2, v3
	v_cvt_pk_bf16_f32 v3, v4, v5
	global_store_dwordx2 v[74:75], v[6:7], off offset:2560
	global_store_dwordx2 v[78:79], v[2:3], off offset:2560
	global_load_dwordx4 v[2:5], v[70:71], off
	s_nop 0
	global_load_dwordx4 v[6:9], v[80:81], off offset:2048
	global_load_dwordx4 v[12:15], v[82:83], off offset:2048
	v_pk_mul_f32 v[16:17], v[28:29], v[84:85] op_sel_hi:[1,0]
	v_pk_mul_f32 v[28:29], v[32:33], v[10:11] op_sel_hi:[1,0]
	s_waitcnt vmcnt(2)
	v_pk_mul_f32 v[26:27], v[26:27], v[2:3]
	v_pk_mul_f32 v[16:17], v[16:17], v[4:5]
	s_waitcnt vmcnt(1)
	v_pk_add_f32 v[8:9], v[8:9], 1.0 op_sel_hi:[1,0]
	v_pk_add_f32 v[6:7], v[6:7], 1.0 op_sel_hi:[1,0]
	v_pk_mul_f32 v[2:3], v[30:31], v[2:3]
	v_pk_mul_f32 v[4:5], v[28:29], v[4:5]
	s_waitcnt vmcnt(0)
	v_pk_fma_f32 v[16:17], v[16:17], v[8:9], v[14:15]
	v_pk_fma_f32 v[26:27], v[26:27], v[6:7], v[12:13]
	v_pk_fma_f32 v[4:5], v[4:5], v[8:9], v[14:15]
	v_pk_fma_f32 v[2:3], v[2:3], v[6:7], v[12:13]
	v_cvt_pk_bf16_f32 v6, v26, v27
	v_cvt_pk_bf16_f32 v7, v16, v17
	v_cvt_pk_bf16_f32 v2, v2, v3
	v_cvt_pk_bf16_f32 v3, v4, v5
	global_store_dwordx2 v[74:75], v[6:7], off offset:3072
	global_store_dwordx2 v[78:79], v[2:3], off offset:3072
	global_load_dwordx4 v[2:5], v[72:73], off
	s_nop 0
	global_load_dwordx4 v[6:9], v[80:81], off offset:3072
	global_load_dwordx4 v[12:15], v[82:83], off offset:3072
	v_pk_mul_f32 v[16:17], v[20:21], v[84:85] op_sel_hi:[1,0]
	v_pk_mul_f32 v[20:21], v[24:25], v[10:11] op_sel_hi:[1,0]
	v_pk_mul_f32 v[10:11], v[22:23], v[10:11] op_sel_hi:[1,0]
	s_waitcnt vmcnt(2)
	v_pk_mul_f32 v[18:19], v[18:19], v[2:3]
	v_pk_mul_f32 v[16:17], v[16:17], v[4:5]
	s_waitcnt vmcnt(1)
	v_pk_add_f32 v[8:9], v[8:9], 1.0 op_sel_hi:[1,0]
	v_pk_add_f32 v[6:7], v[6:7], 1.0 op_sel_hi:[1,0]
	v_pk_mul_f32 v[2:3], v[10:11], v[2:3]
	v_pk_mul_f32 v[4:5], v[20:21], v[4:5]
	s_waitcnt vmcnt(0)
	v_pk_fma_f32 v[10:11], v[16:17], v[8:9], v[14:15]
	v_pk_fma_f32 v[16:17], v[18:19], v[6:7], v[12:13]
	v_pk_fma_f32 v[4:5], v[4:5], v[8:9], v[14:15]
	v_pk_fma_f32 v[2:3], v[2:3], v[6:7], v[12:13]
	v_cvt_pk_bf16_f32 v6, v16, v17
	v_cvt_pk_bf16_f32 v7, v10, v11
	v_cvt_pk_bf16_f32 v2, v2, v3
	v_cvt_pk_bf16_f32 v3, v4, v5
	global_store_dwordx2 v[74:75], v[6:7], off offset:3584
	global_store_dwordx2 v[78:79], v[2:3], off offset:3584
	v_lshl_add_u64 v[74:75], v[74:75], 0, s[18:19]
	s_cbranch_scc1 .LBB0_1019

; #define PG8_STAGE(bufoff, gbase, voff) do { _Pragma("unroll") for (int _i = 0; _i < 2; ++_i) \
;         __builtin_amdgcn_global_load_lds((const unsigned*)((const char*)(gbase) + (voff)[_i]), (PG8_LAS unsigned*)(lds + (bufoff) + ldsw + _i * 8192), 16, 0, 0); } while (0)
; #define PG8_LDA(dst, b, h) do { _Pragma("unroll") for (int m = 0; m < 4; ++m) _Pragma("unroll") for (int k = 0; k < 2; ++k) dst[m][k] = *(const PG8_LAS bf16x8*)(lds + PG8_SA(b, h) + aoff + m * 2048 + k * 1024); } while (0)
; #define PG8_LDB(dst, b, h) do { _Pragma("unroll") for (int n = 0; n < 2; ++n) _Pragma("unroll") for (int k = 0; k < 2; ++k) dst[n][k] = *(const PG8_LAS bf16x8*)(lds + PG8_SB(b, h) + boff + n * 2048 + k * 1024); } while (0)
; #define PG8_MMA(ai, bj, At, Bt) do { __builtin_amdgcn_s_setprio(1); _Pragma("unroll") for (int m = 0; m < 4; ++m) _Pragma("unroll") for (int n = 0; n < 2; ++n) _Pragma("unroll") for (int k = 0; k < 2; ++k) \
;         acc[ai][bj][m][n] = __builtin_amdgcn_mfma_f32_16x16x32_bf16(Bt[n][k], At[m][k], acc[ai][bj][m][n], 0, 0, 0); __builtin_amdgcn_s_setprio(0); } while (0)
; #define PG8_WAIT_V(n) asm volatile("s_waitcnt vmcnt(" #n ")" ::: "memory")
; #define PG8_WAIT_L(n) asm volatile("s_waitcnt lgkmcnt(" #n ")" ::: "memory")
; #define PG8_BAR __builtin_amdgcn_s_barrier()
; #define PG8_SCHED __builtin_amdgcn_sched_barrier(0)
; template <class Epi, class Sched, bool ALIGN_EPI = false, bool SP2 = false>
; __device__ __forceinline__ void gemm_phase(PG8_LAS unsigned char* lds, const Gemm g, const Sched& S, const Epi& E) {
;     ...
;             PG8_LDB(B0, 0, 0); PG8_LDB(B1, 0, 1); PG8_SCHED; PG8_LDA(At, 0, 0); PG8_STAGE(PG8_SA(1, 1), a1 + hstep, voffA);
;             PG8_WAIT_V(8); PG8_WAIT_L(0); PG8_BAR; PG8_MMA(0, 0, At, B0); PG8_MMA(0, 1, At, B1); PG8_BAR; PG8_SCHED;
;             PG8_LDA(At, 0, 1); PG8_STAGE(PG8_SB(0, 0), b2, voffB); PG8_STAGE(PG8_SB(0, 1), b2 + hstep, voffB); PG8_STAGE(PG8_SA(0, 0), a2, voffA);
;             PG8_WAIT_V(8); PG8_WAIT_L(0); PG8_BAR; PG8_MMA(1, 0, At, B0); PG8_MMA(1, 1, At, B1); PG8_BAR; PG8_SCHED;
.LBB0_1098:
	ds_read_b128 v[154:157], v151
	ds_read_b128 v[158:161], v151 offset:1024
	ds_read_b128 v[162:165], v151 offset:2048
	ds_read_b128 v[166:169], v151 offset:3072
	ds_read_b128 v[170:173], v152
	ds_read_b128 v[174:177], v152 offset:1024
	ds_read_b128 v[178:181], v152 offset:2048
	ds_read_b128 v[182:185], v152 offset:3072
	s_add_u32 s30, s28, 0xfff80080
	s_addc_u32 s31, s29, -1
	s_cmp_eq_u32 s53, 28
	s_cselect_b32 s35, s21, s31
	s_cselect_b32 s34, s49, s30
	s_cselect_b32 s31, s19, s52
	s_cselect_b32 s30, s50, s51
	v_lshl_add_u64 v[146:147], s[28:29], 0, v[138:139]
	s_add_i32 m0, s27, 0xc000
	ds_read_b128 v[188:191], v153
	ds_read_b128 v[192:195], v153 offset:1024
	ds_read_b128 v[196:199], v153 offset:2048
	ds_read_b128 v[200:203], v153 offset:3072
	ds_read_b128 v[204:207], v153 offset:4096
	ds_read_b128 v[208:211], v153 offset:5120
	ds_read_b128 v[212:215], v153 offset:6144
	ds_read_b128 v[216:219], v153 offset:7168
	s_add_u32 s98, s28, 0xfff80000
	s_addc_u32 s99, s29, -1
	s_mov_b32 m0, s41
	s_nop 0
	global_load_lds_dwordx4 v138, s[98:99]
	s_mov_b32 m0, s42
	s_nop 0
	global_load_lds_dwordx4 v140, s[98:99]
	s_add_i32 m0, s27, 0xc000
	s_nop 0
	global_load_lds_dwordx4 v[146:147], off
	v_lshl_add_u64 v[146:147], s[28:29], 0, v[140:141]
	s_add_i32 m0, s27, 0xe000
	s_nop 0
	global_load_lds_dwordx4 v[146:147], off
	s_waitcnt vmcnt(8)
	s_waitcnt lgkmcnt(0)
	s_barrier
	s_setprio 1
	s_waitcnt lgkmcnt(0)
	v_mfma_f32_16x16x32_bf16 v[126:129], v[154:157], v[188:191], v[126:129]
	v_mfma_f32_16x16x32_bf16 v[122:125], v[162:165], v[188:191], v[122:125]
	v_mfma_f32_16x16x32_bf16 v[110:113], v[154:157], v[196:199], v[110:113]
	v_mfma_f32_16x16x32_bf16 v[106:109], v[162:165], v[196:199], v[106:109]
	v_mfma_f32_16x16x32_bf16 v[94:97], v[154:157], v[204:207], v[94:97]
	v_mfma_f32_16x16x32_bf16 v[90:93], v[162:165], v[204:207], v[90:93]
	v_mfma_f32_16x16x32_bf16 v[78:81], v[154:157], v[212:215], v[78:81]
	v_mfma_f32_16x16x32_bf16 v[74:77], v[162:165], v[212:215], v[74:77]
	v_mfma_f32_16x16x32_bf16 v[126:129], v[158:161], v[192:195], v[126:129]
	v_mfma_f32_16x16x32_bf16 v[122:125], v[166:169], v[192:195], v[122:125]
	v_mfma_f32_16x16x32_bf16 v[110:113], v[158:161], v[200:203], v[110:113]
	v_mfma_f32_16x16x32_bf16 v[106:109], v[166:169], v[200:203], v[106:109]
	v_mfma_f32_16x16x32_bf16 v[94:97], v[158:161], v[208:211], v[94:97]
	v_mfma_f32_16x16x32_bf16 v[90:93], v[166:169], v[208:211], v[90:93]
	v_mfma_f32_16x16x32_bf16 v[78:81], v[158:161], v[216:219], v[78:81]
	v_mfma_f32_16x16x32_bf16 v[74:77], v[166:169], v[216:219], v[74:77]
	s_setprio 0
	s_setprio 1
	v_mfma_f32_16x16x32_bf16 v[118:121], v[170:173], v[188:191], v[118:121]
	v_mfma_f32_16x16x32_bf16 v[114:117], v[178:181], v[188:191], v[114:117]
	v_mfma_f32_16x16x32_bf16 v[102:105], v[170:173], v[196:199], v[102:105]
	v_mfma_f32_16x16x32_bf16 v[98:101], v[178:181], v[196:199], v[98:101]
	v_mfma_f32_16x16x32_bf16 v[86:89], v[170:173], v[204:207], v[86:89]
	v_mfma_f32_16x16x32_bf16 v[82:85], v[178:181], v[204:207], v[82:85]
	v_mfma_f32_16x16x32_bf16 v[70:73], v[170:173], v[212:215], v[70:73]
	v_mfma_f32_16x16x32_bf16 v[66:69], v[178:181], v[212:215], v[66:69]
	v_mfma_f32_16x16x32_bf16 v[118:121], v[174:177], v[192:195], v[118:121]
	v_mfma_f32_16x16x32_bf16 v[114:117], v[182:185], v[192:195], v[114:117]
	v_mfma_f32_16x16x32_bf16 v[102:105], v[174:177], v[200:203], v[102:105]
	v_mfma_f32_16x16x32_bf16 v[98:101], v[182:185], v[200:203], v[98:101]
	v_mfma_f32_16x16x32_bf16 v[86:89], v[174:177], v[208:211], v[86:89]
	v_mfma_f32_16x16x32_bf16 v[82:85], v[182:185], v[208:211], v[82:85]
	v_mfma_f32_16x16x32_bf16 v[70:73], v[174:177], v[216:219], v[70:73]
	v_mfma_f32_16x16x32_bf16 v[66:69], v[182:185], v[216:219], v[66:69]
	s_setprio 0
	s_barrier
	s_add_i32 s54, s45, s3
	v_lshl_add_u64 v[146:147], s[30:31], 0, v[134:135]
	s_mov_b32 m0, s54
	ds_read_b128 v[188:191], v153 offset:16384
	ds_read_b128 v[192:195], v153 offset:17408
	ds_read_b128 v[196:199], v153 offset:18432
	ds_read_b128 v[200:203], v153 offset:19456
	ds_read_b128 v[204:207], v153 offset:20480
	ds_read_b128 v[208:211], v153 offset:21504
	ds_read_b128 v[212:215], v153 offset:22528
	ds_read_b128 v[216:219], v153 offset:23552
	global_load_lds_dwordx4 v[146:147], off
	s_add_i32 m0, s54, 0x2000
	s_add_u32 s54, s30, 0x80000
	v_lshl_add_u64 v[220:221], s[30:31], 0, v[130:131]
	s_addc_u32 s55, s31, 0
	s_add_i32 s56, s46, s3
	global_load_lds_dwordx4 v[220:221], off
	v_lshl_add_u64 v[222:223], s[54:55], 0, v[134:135]
	s_mov_b32 m0, s56
	v_lshl_add_u64 v[224:225], s[34:35], 0, v[132:133]
	global_load_lds_dwordx4 v[222:223], off
	v_lshl_add_u64 v[222:223], s[54:55], 0, v[130:131]
	s_add_i32 m0, s56, 0x2000
	s_nop 0
	global_load_lds_dwordx4 v[222:223], off
	v_lshl_add_u64 v[222:223], s[34:35], 0, v[136:137]
	s_mov_b32 m0, s27
	s_nop 0
	s_mov_b32 m0, s37
	s_nop 0
	s_waitcnt vmcnt(6)
	s_waitcnt lgkmcnt(0)
	s_barrier
; #define PG8_STAGE(bufoff, gbase, voff) do { _Pragma("unroll") for (int _i = 0; _i < 2; ++_i) \
;         __builtin_amdgcn_global_load_lds((const unsigned*)((const char*)(gbase) + (voff)[_i]), (PG8_LAS unsigned*)(lds + (bufoff) + ldsw + _i * 8192), 16, 0, 0); } while (0)
; #define PG8_LDA(dst, b, h) do { _Pragma("unroll") for (int m = 0; m < 4; ++m) _Pragma("unroll") for (int k = 0; k < 2; ++k) dst[m][k] = *(const PG8_LAS bf16x8*)(lds + PG8_SA(b, h) + aoff + m * 2048 + k * 1024); } while (0)
; #define PG8_LDB(dst, b, h) do { _Pragma("unroll") for (int n = 0; n < 2; ++n) _Pragma("unroll") for (int k = 0; k < 2; ++k) dst[n][k] = *(const PG8_LAS bf16x8*)(lds + PG8_SB(b, h) + boff + n * 2048 + k * 1024); } while (0)
; #define PG8_MMA(ai, bj, At, Bt) do { __builtin_amdgcn_s_setprio(1); _Pragma("unroll") for (int m = 0; m < 4; ++m) _Pragma("unroll") for (int n = 0; n < 2; ++n) _Pragma("unroll") for (int k = 0; k < 2; ++k) \
;         acc[ai][bj][m][n] = __builtin_amdgcn_mfma_f32_16x16x32_bf16(Bt[n][k], At[m][k], acc[ai][bj][m][n], 0, 0, 0); __builtin_amdgcn_s_setprio(0); } while (0)
; #define PG8_WAIT_V(n) asm volatile("s_waitcnt vmcnt(" #n ")" ::: "memory")
; #define PG8_WAIT_L(n) asm volatile("s_waitcnt lgkmcnt(" #n ")" ::: "memory")
; #define PG8_BAR __builtin_amdgcn_s_barrier()
; #define PG8_SCHED __builtin_amdgcn_sched_barrier(0)
; template <class Epi, class Sched, bool ALIGN_EPI = false, bool SP2 = false>
; __device__ __forceinline__ void gemm_phase(PG8_LAS unsigned char* lds, const Gemm g, const Sched& S, const Epi& E) {
;     ...
;             PG8_WAIT_V(8); PG8_WAIT_L(0); PG8_BAR; PG8_MMA(1, 0, At, B0); PG8_MMA(1, 1, At, B1); PG8_BAR; PG8_SCHED;
;             PG8_LDB(B0, 1, 0); PG8_LDB(B1, 1, 1); PG8_SCHED; PG8_LDA(At, 1, 0); PG8_STAGE(PG8_SA(0, 1), a2 + hstep, voffA);
;             PG8_WAIT_V(8); PG8_WAIT_L(0); PG8_BAR; PG8_MMA(0, 0, At, B0); PG8_MMA(0, 1, At, B1); PG8_BAR; PG8_SCHED;
	s_setprio 1
	s_waitcnt lgkmcnt(0)
	v_mfma_f32_16x16x32_bf16 v[62:65], v[154:157], v[188:191], v[62:65]
	v_mfma_f32_16x16x32_bf16 v[58:61], v[162:165], v[188:191], v[58:61]
	v_mfma_f32_16x16x32_bf16 v[46:49], v[154:157], v[196:199], v[46:49]
	v_mfma_f32_16x16x32_bf16 v[42:45], v[162:165], v[196:199], v[42:45]
	v_mfma_f32_16x16x32_bf16 v[30:33], v[154:157], v[204:207], v[30:33]
	v_mfma_f32_16x16x32_bf16 v[26:29], v[162:165], v[204:207], v[26:29]
	v_mfma_f32_16x16x32_bf16 v[14:17], v[154:157], v[212:215], v[14:17]
	v_mfma_f32_16x16x32_bf16 v[10:13], v[162:165], v[212:215], v[10:13]
	v_mfma_f32_16x16x32_bf16 v[62:65], v[158:161], v[192:195], v[62:65]
	v_mfma_f32_16x16x32_bf16 v[58:61], v[166:169], v[192:195], v[58:61]
	v_mfma_f32_16x16x32_bf16 v[46:49], v[158:161], v[200:203], v[46:49]
	v_mfma_f32_16x16x32_bf16 v[42:45], v[166:169], v[200:203], v[42:45]
	v_mfma_f32_16x16x32_bf16 v[30:33], v[158:161], v[208:211], v[30:33]
	v_mfma_f32_16x16x32_bf16 v[26:29], v[166:169], v[208:211], v[26:29]
	v_mfma_f32_16x16x32_bf16 v[14:17], v[158:161], v[216:219], v[14:17]
	v_mfma_f32_16x16x32_bf16 v[10:13], v[166:169], v[216:219], v[10:13]
	s_setprio 0
	s_setprio 1
	v_mfma_f32_16x16x32_bf16 v[54:57], v[170:173], v[188:191], v[54:57]
	v_mfma_f32_16x16x32_bf16 v[50:53], v[178:181], v[188:191], v[50:53]
	v_mfma_f32_16x16x32_bf16 v[38:41], v[170:173], v[196:199], v[38:41]
	v_mfma_f32_16x16x32_bf16 v[34:37], v[178:181], v[196:199], v[34:37]
	v_mfma_f32_16x16x32_bf16 v[22:25], v[170:173], v[204:207], v[22:25]
	v_mfma_f32_16x16x32_bf16 v[18:21], v[178:181], v[204:207], v[18:21]
	v_mfma_f32_16x16x32_bf16 v[6:9], v[170:173], v[212:215], v[6:9]
	v_mfma_f32_16x16x32_bf16 v[2:5], v[178:181], v[212:215], v[2:5]
	v_mfma_f32_16x16x32_bf16 v[54:57], v[174:177], v[192:195], v[54:57]
	v_mfma_f32_16x16x32_bf16 v[50:53], v[182:185], v[192:195], v[50:53]
	v_mfma_f32_16x16x32_bf16 v[38:41], v[174:177], v[200:203], v[38:41]
	v_mfma_f32_16x16x32_bf16 v[34:37], v[182:185], v[200:203], v[34:37]
	v_mfma_f32_16x16x32_bf16 v[22:25], v[174:177], v[208:211], v[22:25]
	v_mfma_f32_16x16x32_bf16 v[18:21], v[182:185], v[208:211], v[18:21]
	v_mfma_f32_16x16x32_bf16 v[6:9], v[174:177], v[216:219], v[6:9]
	v_mfma_f32_16x16x32_bf16 v[2:5], v[182:185], v[216:219], v[2:5]
	s_setprio 0
	s_barrier
	s_add_i32 s54, 0, 0x18000
	s_add_i32 s55, 0, 0x1c000
	v_add_u32_e32 v166, s54, v149
	v_add_u32_e32 v182, s55, v149
	ds_read_b128 v[154:157], v166
	ds_read_b128 v[158:161], v166 offset:1024
	ds_read_b128 v[162:165], v166 offset:2048
	ds_read_b128 v[166:169], v166 offset:3072
	ds_read_b128 v[170:173], v182
	ds_read_b128 v[174:177], v182 offset:1024
	ds_read_b128 v[178:181], v182 offset:2048
	ds_read_b128 v[182:185], v182 offset:3072
	s_add_u32 s34, s34, 0x80000
	s_addc_u32 s35, s35, 0
	s_mov_b32 m0, s38
	v_lshl_add_u64 v[226:227], s[34:35], 0, v[136:137]
	ds_read_b128 v[188:191], v153 offset:32768
	ds_read_b128 v[192:195], v153 offset:33792
	ds_read_b128 v[196:199], v153 offset:34816
	ds_read_b128 v[200:203], v153 offset:35840
	ds_read_b128 v[204:207], v153 offset:36864
	ds_read_b128 v[208:211], v153 offset:37888
	ds_read_b128 v[212:215], v153 offset:38912
	ds_read_b128 v[216:219], v153 offset:39936
	s_add_u32 s98, s34, 0xfff80000
	s_addc_u32 s99, s35, -1
	s_mov_b32 m0, s27
	s_nop 0
	global_load_lds_dwordx4 v136, s[98:99]
	s_mov_b32 m0, s37
	s_nop 0
	global_load_lds_dwordx4 v132, s[98:99]
	s_mov_b32 m0, s38
	s_nop 0
	global_load_lds_dwordx4 v[226:227], off
	v_lshl_add_u64 v[226:227], s[34:35], 0, v[132:133]
	s_mov_b32 m0, s39
	s_nop 0
	global_load_lds_dwordx4 v[226:227], off
	s_waitcnt vmcnt(8)
	s_waitcnt lgkmcnt(0)
	s_barrier
	s_setprio 1
	s_waitcnt lgkmcnt(0)
	v_mfma_f32_16x16x32_bf16 v[126:129], v[154:157], v[188:191], v[126:129]
	v_mfma_f32_16x16x32_bf16 v[122:125], v[162:165], v[188:191], v[122:125]
	v_mfma_f32_16x16x32_bf16 v[110:113], v[154:157], v[196:199], v[110:113]
	v_mfma_f32_16x16x32_bf16 v[106:109], v[162:165], v[196:199], v[106:109]
	v_mfma_f32_16x16x32_bf16 v[94:97], v[154:157], v[204:207], v[94:97]
	v_mfma_f32_16x16x32_bf16 v[90:93], v[162:165], v[204:207], v[90:93]
	v_mfma_f32_16x16x32_bf16 v[78:81], v[154:157], v[212:215], v[78:81]
	v_mfma_f32_16x16x32_bf16 v[74:77], v[162:165], v[212:215], v[74:77]
	v_mfma_f32_16x16x32_bf16 v[126:129], v[158:161], v[192:195], v[126:129]
	v_mfma_f32_16x16x32_bf16 v[122:125], v[166:169], v[192:195], v[122:125]
	v_mfma_f32_16x16x32_bf16 v[110:113], v[158:161], v[200:203], v[110:113]
	v_mfma_f32_16x16x32_bf16 v[106:109], v[166:169], v[200:203], v[106:109]
	v_mfma_f32_16x16x32_bf16 v[94:97], v[158:161], v[208:211], v[94:97]
	v_mfma_f32_16x16x32_bf16 v[90:93], v[166:169], v[208:211], v[90:93]
	v_mfma_f32_16x16x32_bf16 v[78:81], v[158:161], v[216:219], v[78:81]
	v_mfma_f32_16x16x32_bf16 v[74:77], v[166:169], v[216:219], v[74:77]
	s_setprio 0
	s_setprio 1
	v_mfma_f32_16x16x32_bf16 v[118:121], v[170:173], v[188:191], v[118:121]
	v_mfma_f32_16x16x32_bf16 v[114:117], v[178:181], v[188:191], v[114:117]
	v_mfma_f32_16x16x32_bf16 v[102:105], v[170:173], v[196:199], v[102:105]
	v_mfma_f32_16x16x32_bf16 v[98:101], v[178:181], v[196:199], v[98:101]
	v_mfma_f32_16x16x32_bf16 v[86:89], v[170:173], v[204:207], v[86:89]
	v_mfma_f32_16x16x32_bf16 v[82:85], v[178:181], v[204:207], v[82:85]
	v_mfma_f32_16x16x32_bf16 v[70:73], v[170:173], v[212:215], v[70:73]
	v_mfma_f32_16x16x32_bf16 v[66:69], v[178:181], v[212:215], v[66:69]
	v_mfma_f32_16x16x32_bf16 v[118:121], v[174:177], v[192:195], v[118:121]
	v_mfma_f32_16x16x32_bf16 v[114:117], v[182:185], v[192:195], v[114:117]
	v_mfma_f32_16x16x32_bf16 v[102:105], v[174:177], v[200:203], v[102:105]
	v_mfma_f32_16x16x32_bf16 v[98:101], v[182:185], v[200:203], v[98:101]
	v_mfma_f32_16x16x32_bf16 v[86:89], v[174:177], v[208:211], v[86:89]
	v_mfma_f32_16x16x32_bf16 v[82:85], v[182:185], v[208:211], v[82:85]
	v_mfma_f32_16x16x32_bf16 v[70:73], v[174:177], v[216:219], v[70:73]
	v_mfma_f32_16x16x32_bf16 v[66:69], v[182:185], v[216:219], v[66:69]
	s_setprio 0
	s_barrier
; #define PG8_STAGE(bufoff, gbase, voff) do { _Pragma("unroll") for (int _i = 0; _i < 2; ++_i) \
;         __builtin_amdgcn_global_load_lds((const unsigned*)((const char*)(gbase) + (voff)[_i]), (PG8_LAS unsigned*)(lds + (bufoff) + ldsw + _i * 8192), 16, 0, 0); } while (0)
; #define PG8_LDA(dst, b, h) do { _Pragma("unroll") for (int m = 0; m < 4; ++m) _Pragma("unroll") for (int k = 0; k < 2; ++k) dst[m][k] = *(const PG8_LAS bf16x8*)(lds + PG8_SA(b, h) + aoff + m * 2048 + k * 1024); } while (0)
; #define PG8_MMA(ai, bj, At, Bt) do { __builtin_amdgcn_s_setprio(1); _Pragma("unroll") for (int m = 0; m < 4; ++m) _Pragma("unroll") for (int n = 0; n < 2; ++n) _Pragma("unroll") for (int k = 0; k < 2; ++k) \
;         acc[ai][bj][m][n] = __builtin_amdgcn_mfma_f32_16x16x32_bf16(Bt[n][k], At[m][k], acc[ai][bj][m][n], 0, 0, 0); __builtin_amdgcn_s_setprio(0); } while (0)
; #define PG8_WAIT_V(n) asm volatile("s_waitcnt vmcnt(" #n ")" ::: "memory")
; #define PG8_WAIT_L(n) asm volatile("s_waitcnt lgkmcnt(" #n ")" ::: "memory")
; #define PG8_BAR __builtin_amdgcn_s_barrier()
; #define PG8_SCHED __builtin_amdgcn_sched_barrier(0)
; template <class Epi, class Sched, bool ALIGN_EPI = false, bool SP2 = false>
; __device__ __forceinline__ void gemm_phase(PG8_LAS unsigned char* lds, const Gemm g, const Sched& S, const Epi& E) {
;     ...
;         for (int t = 0; t < nt; t += 2) {
;             const bool last = (t == nt - 2);
;             const char* a1 = cA + (size_t)(t + 1) * kstep;
;             const char* a2 = last ? nA : cA + (size_t)(t + 2) * kstep; const char* b2 = last ? nB : cB + (size_t)(t + 2) * kstep;
;     ...
;             PG8_LDA(At, 1, 1); PG8_STAGE(PG8_SB(1, 0), b3, voffB); PG8_STAGE(PG8_SB(1, 1), b3 + hstep, voffB); PG8_STAGE(PG8_SA(1, 0), a3, voffA);
;             PG8_WAIT_V(8); PG8_WAIT_L(0); PG8_BAR; PG8_MMA(1, 0, At, B0); PG8_MMA(1, 1, At, B1); PG8_BAR; PG8_SCHED;
	s_add_i32 s34, s54, s3
	v_lshl_add_u64 v[146:147], v[146:147], 0, s[8:9]
	s_mov_b32 m0, s34
	ds_read_b128 v[188:191], v153 offset:49152
	ds_read_b128 v[192:195], v153 offset:50176
	ds_read_b128 v[196:199], v153 offset:51200
	ds_read_b128 v[200:203], v153 offset:52224
	ds_read_b128 v[204:207], v153 offset:53248
	ds_read_b128 v[208:211], v153 offset:54272
	ds_read_b128 v[212:215], v153 offset:55296
	ds_read_b128 v[216:219], v153 offset:56320
	global_load_lds_dwordx4 v[146:147], off
	s_add_i32 m0, s34, 0x2000
	s_add_u32 s30, s30, 0x80080
	v_lshl_add_u64 v[146:147], v[220:221], 0, s[8:9]
	s_addc_u32 s31, s31, 0
	s_add_i32 s34, s55, s3
	global_load_lds_dwordx4 v[146:147], off
	v_lshl_add_u64 v[146:147], s[30:31], 0, v[134:135]
	s_mov_b32 m0, s34
	s_nop 0
	global_load_lds_dwordx4 v[146:147], off
	v_lshl_add_u64 v[146:147], s[30:31], 0, v[130:131]
	s_add_i32 m0, s34, 0x2000
	s_nop 0
	global_load_lds_dwordx4 v[146:147], off
	v_lshl_add_u64 v[146:147], v[222:223], 0, s[8:9]
	s_mov_b32 m0, s41
	s_nop 0
	v_lshl_add_u64 v[146:147], v[224:225], 0, s[8:9]
	s_mov_b32 m0, s42
	s_nop 0
	s_waitcnt vmcnt(6)
	s_waitcnt lgkmcnt(0)
	s_barrier
	s_setprio 1
	s_waitcnt lgkmcnt(0)
	v_mfma_f32_16x16x32_bf16 v[62:65], v[154:157], v[188:191], v[62:65]
	v_mfma_f32_16x16x32_bf16 v[58:61], v[162:165], v[188:191], v[58:61]
	v_mfma_f32_16x16x32_bf16 v[46:49], v[154:157], v[196:199], v[46:49]
	v_mfma_f32_16x16x32_bf16 v[42:45], v[162:165], v[196:199], v[42:45]
	v_mfma_f32_16x16x32_bf16 v[30:33], v[154:157], v[204:207], v[30:33]
	v_mfma_f32_16x16x32_bf16 v[26:29], v[162:165], v[204:207], v[26:29]
	v_mfma_f32_16x16x32_bf16 v[14:17], v[154:157], v[212:215], v[14:17]
	v_mfma_f32_16x16x32_bf16 v[10:13], v[162:165], v[212:215], v[10:13]
	v_mfma_f32_16x16x32_bf16 v[62:65], v[158:161], v[192:195], v[62:65]
	v_mfma_f32_16x16x32_bf16 v[58:61], v[166:169], v[192:195], v[58:61]
	v_mfma_f32_16x16x32_bf16 v[46:49], v[158:161], v[200:203], v[46:49]
	v_mfma_f32_16x16x32_bf16 v[42:45], v[166:169], v[200:203], v[42:45]
	v_mfma_f32_16x16x32_bf16 v[30:33], v[158:161], v[208:211], v[30:33]
	v_mfma_f32_16x16x32_bf16 v[26:29], v[166:169], v[208:211], v[26:29]
	v_mfma_f32_16x16x32_bf16 v[14:17], v[158:161], v[216:219], v[14:17]
	v_mfma_f32_16x16x32_bf16 v[10:13], v[166:169], v[216:219], v[10:13]
	s_setprio 0
	s_setprio 1
	v_mfma_f32_16x16x32_bf16 v[54:57], v[170:173], v[188:191], v[54:57]
	v_mfma_f32_16x16x32_bf16 v[50:53], v[178:181], v[188:191], v[50:53]
	v_mfma_f32_16x16x32_bf16 v[38:41], v[170:173], v[196:199], v[38:41]
	v_mfma_f32_16x16x32_bf16 v[34:37], v[178:181], v[196:199], v[34:37]
	v_mfma_f32_16x16x32_bf16 v[22:25], v[170:173], v[204:207], v[22:25]
	v_mfma_f32_16x16x32_bf16 v[18:21], v[178:181], v[204:207], v[18:21]
	v_mfma_f32_16x16x32_bf16 v[6:9], v[170:173], v[212:215], v[6:9]
	v_mfma_f32_16x16x32_bf16 v[2:5], v[178:181], v[212:215], v[2:5]
	v_mfma_f32_16x16x32_bf16 v[54:57], v[174:177], v[192:195], v[54:57]
	v_mfma_f32_16x16x32_bf16 v[50:53], v[182:185], v[192:195], v[50:53]
	v_mfma_f32_16x16x32_bf16 v[38:41], v[174:177], v[200:203], v[38:41]
	v_mfma_f32_16x16x32_bf16 v[34:37], v[182:185], v[200:203], v[34:37]
	v_mfma_f32_16x16x32_bf16 v[22:25], v[174:177], v[208:211], v[22:25]
	v_mfma_f32_16x16x32_bf16 v[18:21], v[182:185], v[208:211], v[18:21]
	v_mfma_f32_16x16x32_bf16 v[6:9], v[174:177], v[216:219], v[6:9]
	v_mfma_f32_16x16x32_bf16 v[2:5], v[182:185], v[216:219], v[2:5]
	s_setprio 0
	s_barrier
	s_add_i32 s53, s53, 2
	s_add_u32 s28, s28, 0x100
	s_addc_u32 s29, s29, 0
	s_add_u32 s51, s51, 0x100
	s_addc_u32 s52, s52, 0
	s_cmp_gt_u32 s53, 29
	s_cbranch_scc0 .LBB0_1098
	s_and_b64 vcc, exec, s[16:17]
	s_cbranch_vccz .LBB0_1101
	s_barrier

; #define PG8_STAGE(bufoff, gbase, voff) do { _Pragma("unroll") for (int _i = 0; _i < 2; ++_i) \
;         __builtin_amdgcn_global_load_lds((const unsigned*)((const char*)(gbase) + (voff)[_i]), (PG8_LAS unsigned*)(lds + (bufoff) + ldsw + _i * 8192), 16, 0, 0); } while (0)
; #define PG8_LDA(dst, b, h) do { _Pragma("unroll") for (int m = 0; m < 4; ++m) _Pragma("unroll") for (int k = 0; k < 2; ++k) dst[m][k] = *(const PG8_LAS bf16x8*)(lds + PG8_SA(b, h) + aoff + m * 2048 + k * 1024); } while (0)
; #define PG8_LDB(dst, b, h) do { _Pragma("unroll") for (int n = 0; n < 2; ++n) _Pragma("unroll") for (int k = 0; k < 2; ++k) dst[n][k] = *(const PG8_LAS bf16x8*)(lds + PG8_SB(b, h) + boff + n * 2048 + k * 1024); } while (0)
; #define PG8_MMA(ai, bj, At, Bt) do { __builtin_amdgcn_s_setprio(1); _Pragma("unroll") for (int m = 0; m < 4; ++m) _Pragma("unroll") for (int n = 0; n < 2; ++n) _Pragma("unroll") for (int k = 0; k < 2; ++k) \
;         acc[ai][bj][m][n] = __builtin_amdgcn_mfma_f32_16x16x32_bf16(Bt[n][k], At[m][k], acc[ai][bj][m][n], 0, 0, 0); __builtin_amdgcn_s_setprio(0); } while (0)
; #define PG8_WAIT_V(n) asm volatile("s_waitcnt vmcnt(" #n ")" ::: "memory")
; #define PG8_WAIT_L(n) asm volatile("s_waitcnt lgkmcnt(" #n ")" ::: "memory")
; #define PG8_BAR __builtin_amdgcn_s_barrier()
; #define PG8_SCHED __builtin_amdgcn_sched_barrier(0)
; template <class Epi, class Sched, bool ALIGN_EPI = false, bool SP2 = false>
; __device__ __forceinline__ void gemm_phase(PG8_LAS unsigned char* lds, const Gemm g, const Sched& S, const Epi& E) {
;     ...
;             PG8_LDB(B0, 0, 0); PG8_LDB(B1, 0, 1); PG8_SCHED; PG8_LDA(At, 0, 0); PG8_STAGE(PG8_SA(1, 1), a1 + hstep, voffA);
;             PG8_WAIT_V(8); PG8_WAIT_L(0); PG8_BAR; PG8_MMA(0, 0, At, B0); PG8_MMA(0, 1, At, B1); PG8_BAR; PG8_SCHED;
;             PG8_LDA(At, 0, 1); PG8_STAGE(PG8_SB(0, 0), b2, voffB); PG8_STAGE(PG8_SB(0, 1), b2 + hstep, voffB); PG8_STAGE(PG8_SA(0, 0), a2, voffA);
;             PG8_WAIT_V(8); PG8_WAIT_L(0); PG8_BAR; PG8_MMA(1, 0, At, B0); PG8_MMA(1, 1, At, B1); PG8_BAR; PG8_SCHED;
.LBB0_1195:
	ds_read_b128 v[130:133], v165
	ds_read_b128 v[134:137], v165 offset:1024
	ds_read_b128 v[138:141], v165 offset:2048
	ds_read_b128 v[142:145], v165 offset:3072
	ds_read_b128 v[158:161], v166
	ds_read_b128 v[168:171], v166 offset:1024
	ds_read_b128 v[172:175], v166 offset:2048
	ds_read_b128 v[176:179], v166 offset:3072
	s_add_u32 s24, s22, 0xffea0080
	s_addc_u32 s25, s23, -1
	s_cmpk_eq_i32 s49, 0x54
	s_cselect_b32 s27, s5, s25
	s_cselect_b32 s26, s4, s24
	s_cselect_b32 s25, s21, s48
	s_cselect_b32 s24, s20, s47
	v_lshl_add_u64 v[184:185], s[22:23], 0, v[150:151]
	s_add_i32 m0, s29, 0xc000
	ds_read_b128 v[180:183], v167
	ds_read_b128 v[188:191], v167 offset:1024
	ds_read_b128 v[192:195], v167 offset:2048
	ds_read_b128 v[196:199], v167 offset:3072
	ds_read_b128 v[200:203], v167 offset:4096
	ds_read_b128 v[204:207], v167 offset:5120
	ds_read_b128 v[208:211], v167 offset:6144
	ds_read_b128 v[212:215], v167 offset:7168
	s_add_u32 s98, s22, 0xffea0000
	s_addc_u32 s99, s23, -1
	s_mov_b32 m0, s37
	s_nop 0
	global_load_lds_dwordx4 v150, s[98:99]
	s_mov_b32 m0, s38
	s_nop 0
	global_load_lds_dwordx4 v152, s[98:99]
	s_add_i32 m0, s29, 0xc000
	s_nop 0
	global_load_lds_dwordx4 v[184:185], off
	v_lshl_add_u64 v[184:185], s[22:23], 0, v[152:153]
	s_add_i32 m0, s29, 0xe000
	s_nop 0
	global_load_lds_dwordx4 v[184:185], off
	s_waitcnt vmcnt(8)
	s_waitcnt lgkmcnt(0)
	s_barrier
	s_setprio 1
	s_waitcnt lgkmcnt(0)
	v_mfma_f32_16x16x32_bf16 v[126:129], v[130:133], v[180:183], v[126:129]
	v_mfma_f32_16x16x32_bf16 v[122:125], v[138:141], v[180:183], v[122:125]
	v_mfma_f32_16x16x32_bf16 v[118:121], v[130:133], v[192:195], v[118:121]
	v_mfma_f32_16x16x32_bf16 v[114:117], v[138:141], v[192:195], v[114:117]
	v_mfma_f32_16x16x32_bf16 v[94:97], v[130:133], v[200:203], v[94:97]
	v_mfma_f32_16x16x32_bf16 v[90:93], v[138:141], v[200:203], v[90:93]
	v_mfma_f32_16x16x32_bf16 v[86:89], v[130:133], v[208:211], v[86:89]
	v_mfma_f32_16x16x32_bf16 v[82:85], v[138:141], v[208:211], v[82:85]
	v_mfma_f32_16x16x32_bf16 v[126:129], v[134:137], v[188:191], v[126:129]
	v_mfma_f32_16x16x32_bf16 v[122:125], v[142:145], v[188:191], v[122:125]
	v_mfma_f32_16x16x32_bf16 v[118:121], v[134:137], v[196:199], v[118:121]
	v_mfma_f32_16x16x32_bf16 v[114:117], v[142:145], v[196:199], v[114:117]
	v_mfma_f32_16x16x32_bf16 v[94:97], v[134:137], v[204:207], v[94:97]
	v_mfma_f32_16x16x32_bf16 v[90:93], v[142:145], v[204:207], v[90:93]
	v_mfma_f32_16x16x32_bf16 v[86:89], v[134:137], v[212:215], v[86:89]
	v_mfma_f32_16x16x32_bf16 v[82:85], v[142:145], v[212:215], v[82:85]
	s_setprio 0
	s_setprio 1
	v_mfma_f32_16x16x32_bf16 v[110:113], v[158:161], v[180:183], v[110:113]
	v_mfma_f32_16x16x32_bf16 v[106:109], v[172:175], v[180:183], v[106:109]
	v_mfma_f32_16x16x32_bf16 v[102:105], v[158:161], v[192:195], v[102:105]
	v_mfma_f32_16x16x32_bf16 v[98:101], v[172:175], v[192:195], v[98:101]
	v_mfma_f32_16x16x32_bf16 v[78:81], v[158:161], v[200:203], v[78:81]
	v_mfma_f32_16x16x32_bf16 v[74:77], v[172:175], v[200:203], v[74:77]
	v_mfma_f32_16x16x32_bf16 v[70:73], v[158:161], v[208:211], v[70:73]
	v_mfma_f32_16x16x32_bf16 v[66:69], v[172:175], v[208:211], v[66:69]
	v_mfma_f32_16x16x32_bf16 v[110:113], v[168:171], v[188:191], v[110:113]
	v_mfma_f32_16x16x32_bf16 v[106:109], v[176:179], v[188:191], v[106:109]
	v_mfma_f32_16x16x32_bf16 v[102:105], v[168:171], v[196:199], v[102:105]
	v_mfma_f32_16x16x32_bf16 v[98:101], v[176:179], v[196:199], v[98:101]
	v_mfma_f32_16x16x32_bf16 v[78:81], v[168:171], v[204:207], v[78:81]
	v_mfma_f32_16x16x32_bf16 v[74:77], v[176:179], v[204:207], v[74:77]
	v_mfma_f32_16x16x32_bf16 v[70:73], v[168:171], v[212:215], v[70:73]
	v_mfma_f32_16x16x32_bf16 v[66:69], v[176:179], v[212:215], v[66:69]
	s_setprio 0
	s_barrier
	s_add_i32 s50, s41, s28
	v_lshl_add_u64 v[184:185], s[24:25], 0, v[146:147]
	s_mov_b32 m0, s50
	ds_read_b128 v[180:183], v167 offset:16384
	ds_read_b128 v[188:191], v167 offset:17408
	ds_read_b128 v[192:195], v167 offset:18432
	ds_read_b128 v[196:199], v167 offset:19456
	ds_read_b128 v[200:203], v167 offset:20480
	ds_read_b128 v[204:207], v167 offset:21504
	ds_read_b128 v[208:211], v167 offset:22528
	ds_read_b128 v[212:215], v167 offset:23552
	global_load_lds_dwordx4 v[184:185], off
	s_add_i32 m0, s50, 0x2000
	s_add_u32 s50, s24, 0x160000
	v_lshl_add_u64 v[216:217], s[24:25], 0, v[148:149]
	s_addc_u32 s51, s25, 0
	s_add_i32 s52, s42, s28
	global_load_lds_dwordx4 v[216:217], off
	v_lshl_add_u64 v[218:219], s[50:51], 0, v[146:147]
	s_mov_b32 m0, s52
	v_lshl_add_u64 v[220:221], s[26:27], 0, v[148:149]
	global_load_lds_dwordx4 v[218:219], off
	v_lshl_add_u64 v[218:219], s[50:51], 0, v[148:149]
	s_add_i32 m0, s52, 0x2000
	s_nop 0
	global_load_lds_dwordx4 v[218:219], off
	v_lshl_add_u64 v[218:219], s[26:27], 0, v[146:147]
	s_mov_b32 m0, s29
	s_nop 0
	s_mov_b32 m0, s30
	s_nop 0
	s_waitcnt vmcnt(6)
	s_waitcnt lgkmcnt(0)
	s_barrier
; #define PG8_STAGE(bufoff, gbase, voff) do { _Pragma("unroll") for (int _i = 0; _i < 2; ++_i) \
;         __builtin_amdgcn_global_load_lds((const unsigned*)((const char*)(gbase) + (voff)[_i]), (PG8_LAS unsigned*)(lds + (bufoff) + ldsw + _i * 8192), 16, 0, 0); } while (0)
; #define PG8_LDA(dst, b, h) do { _Pragma("unroll") for (int m = 0; m < 4; ++m) _Pragma("unroll") for (int k = 0; k < 2; ++k) dst[m][k] = *(const PG8_LAS bf16x8*)(lds + PG8_SA(b, h) + aoff + m * 2048 + k * 1024); } while (0)
; #define PG8_LDB(dst, b, h) do { _Pragma("unroll") for (int n = 0; n < 2; ++n) _Pragma("unroll") for (int k = 0; k < 2; ++k) dst[n][k] = *(const PG8_LAS bf16x8*)(lds + PG8_SB(b, h) + boff + n * 2048 + k * 1024); } while (0)
; #define PG8_MMA(ai, bj, At, Bt) do { __builtin_amdgcn_s_setprio(1); _Pragma("unroll") for (int m = 0; m < 4; ++m) _Pragma("unroll") for (int n = 0; n < 2; ++n) _Pragma("unroll") for (int k = 0; k < 2; ++k) \
;         acc[ai][bj][m][n] = __builtin_amdgcn_mfma_f32_16x16x32_bf16(Bt[n][k], At[m][k], acc[ai][bj][m][n], 0, 0, 0); __builtin_amdgcn_s_setprio(0); } while (0)
; #define PG8_WAIT_V(n) asm volatile("s_waitcnt vmcnt(" #n ")" ::: "memory")
; #define PG8_WAIT_L(n) asm volatile("s_waitcnt lgkmcnt(" #n ")" ::: "memory")
; #define PG8_BAR __builtin_amdgcn_s_barrier()
; #define PG8_SCHED __builtin_amdgcn_sched_barrier(0)
; template <class Epi, class Sched, bool ALIGN_EPI = false, bool SP2 = false>
; __device__ __forceinline__ void gemm_phase(PG8_LAS unsigned char* lds, const Gemm g, const Sched& S, const Epi& E) {
;     ...
;             PG8_WAIT_V(8); PG8_WAIT_L(0); PG8_BAR; PG8_MMA(1, 0, At, B0); PG8_MMA(1, 1, At, B1); PG8_BAR; PG8_SCHED;
;             PG8_LDB(B0, 1, 0); PG8_LDB(B1, 1, 1); PG8_SCHED; PG8_LDA(At, 1, 0); PG8_STAGE(PG8_SA(0, 1), a2 + hstep, voffA);
;             PG8_WAIT_V(8); PG8_WAIT_L(0); PG8_BAR; PG8_MMA(0, 0, At, B0); PG8_MMA(0, 1, At, B1); PG8_BAR; PG8_SCHED;
	s_setprio 1
	s_waitcnt lgkmcnt(0)
	v_mfma_f32_16x16x32_bf16 v[62:65], v[130:133], v[180:183], v[62:65]
	v_mfma_f32_16x16x32_bf16 v[58:61], v[138:141], v[180:183], v[58:61]
	v_mfma_f32_16x16x32_bf16 v[54:57], v[130:133], v[192:195], v[54:57]
	v_mfma_f32_16x16x32_bf16 v[50:53], v[138:141], v[192:195], v[50:53]
	v_mfma_f32_16x16x32_bf16 v[30:33], v[130:133], v[200:203], v[30:33]
	v_mfma_f32_16x16x32_bf16 v[26:29], v[138:141], v[200:203], v[26:29]
	v_mfma_f32_16x16x32_bf16 v[22:25], v[130:133], v[208:211], v[22:25]
	v_mfma_f32_16x16x32_bf16 v[18:21], v[138:141], v[208:211], v[18:21]
	v_mfma_f32_16x16x32_bf16 v[62:65], v[134:137], v[188:191], v[62:65]
	v_mfma_f32_16x16x32_bf16 v[58:61], v[142:145], v[188:191], v[58:61]
	v_mfma_f32_16x16x32_bf16 v[54:57], v[134:137], v[196:199], v[54:57]
	v_mfma_f32_16x16x32_bf16 v[50:53], v[142:145], v[196:199], v[50:53]
	v_mfma_f32_16x16x32_bf16 v[30:33], v[134:137], v[204:207], v[30:33]
	v_mfma_f32_16x16x32_bf16 v[26:29], v[142:145], v[204:207], v[26:29]
	v_mfma_f32_16x16x32_bf16 v[22:25], v[134:137], v[212:215], v[22:25]
	v_mfma_f32_16x16x32_bf16 v[18:21], v[142:145], v[212:215], v[18:21]
	s_setprio 0
	s_setprio 1
	v_mfma_f32_16x16x32_bf16 v[46:49], v[158:161], v[180:183], v[46:49]
	v_mfma_f32_16x16x32_bf16 v[42:45], v[172:175], v[180:183], v[42:45]
	v_mfma_f32_16x16x32_bf16 v[38:41], v[158:161], v[192:195], v[38:41]
	v_mfma_f32_16x16x32_bf16 v[34:37], v[172:175], v[192:195], v[34:37]
	v_mfma_f32_16x16x32_bf16 v[14:17], v[158:161], v[200:203], v[14:17]
	v_mfma_f32_16x16x32_bf16 v[10:13], v[172:175], v[200:203], v[10:13]
	v_mfma_f32_16x16x32_bf16 v[6:9], v[158:161], v[208:211], v[6:9]
	v_mfma_f32_16x16x32_bf16 v[2:5], v[172:175], v[208:211], v[2:5]
	v_mfma_f32_16x16x32_bf16 v[46:49], v[168:171], v[188:191], v[46:49]
	v_mfma_f32_16x16x32_bf16 v[42:45], v[176:179], v[188:191], v[42:45]
	v_mfma_f32_16x16x32_bf16 v[38:41], v[168:171], v[196:199], v[38:41]
	v_mfma_f32_16x16x32_bf16 v[34:37], v[176:179], v[196:199], v[34:37]
	v_mfma_f32_16x16x32_bf16 v[14:17], v[168:171], v[204:207], v[14:17]
	v_mfma_f32_16x16x32_bf16 v[10:13], v[176:179], v[204:207], v[10:13]
	v_mfma_f32_16x16x32_bf16 v[6:9], v[168:171], v[212:215], v[6:9]
	v_mfma_f32_16x16x32_bf16 v[2:5], v[176:179], v[212:215], v[2:5]
	s_setprio 0
	s_barrier
	s_add_i32 s50, 0, 0x18000
	s_add_i32 s51, 0, 0x1c000
	v_add_u32_e32 v142, s50, v163
	v_add_u32_e32 v176, s51, v163
	ds_read_b128 v[130:133], v142
	ds_read_b128 v[134:137], v142 offset:1024
	ds_read_b128 v[138:141], v142 offset:2048
	ds_read_b128 v[142:145], v142 offset:3072
	ds_read_b128 v[158:161], v176
	ds_read_b128 v[168:171], v176 offset:1024
	ds_read_b128 v[172:175], v176 offset:2048
	ds_read_b128 v[176:179], v176 offset:3072
	s_add_u32 s26, s26, 0x160000
	s_addc_u32 s27, s27, 0
	s_mov_b32 m0, s31
	v_lshl_add_u64 v[222:223], s[26:27], 0, v[146:147]
	ds_read_b128 v[180:183], v167 offset:32768
	ds_read_b128 v[188:191], v167 offset:33792
	ds_read_b128 v[192:195], v167 offset:34816
	ds_read_b128 v[196:199], v167 offset:35840
	ds_read_b128 v[200:203], v167 offset:36864
	ds_read_b128 v[204:207], v167 offset:37888
	ds_read_b128 v[208:211], v167 offset:38912
	ds_read_b128 v[212:215], v167 offset:39936
	s_add_u32 s98, s26, 0xffea0000
	s_addc_u32 s99, s27, -1
	s_mov_b32 m0, s29
	s_nop 0
	global_load_lds_dwordx4 v146, s[98:99]
	s_mov_b32 m0, s30
	s_nop 0
	global_load_lds_dwordx4 v148, s[98:99]
	s_mov_b32 m0, s31
	s_nop 0
	global_load_lds_dwordx4 v[222:223], off
	v_lshl_add_u64 v[222:223], s[26:27], 0, v[148:149]
	s_mov_b32 m0, s33
	s_nop 0
	global_load_lds_dwordx4 v[222:223], off
	s_waitcnt vmcnt(8)
	s_waitcnt lgkmcnt(0)
	s_barrier
	s_setprio 1
	s_waitcnt lgkmcnt(0)
	v_mfma_f32_16x16x32_bf16 v[126:129], v[130:133], v[180:183], v[126:129]
	v_mfma_f32_16x16x32_bf16 v[122:125], v[138:141], v[180:183], v[122:125]
	v_mfma_f32_16x16x32_bf16 v[118:121], v[130:133], v[192:195], v[118:121]
	v_mfma_f32_16x16x32_bf16 v[114:117], v[138:141], v[192:195], v[114:117]
	v_mfma_f32_16x16x32_bf16 v[94:97], v[130:133], v[200:203], v[94:97]
	v_mfma_f32_16x16x32_bf16 v[90:93], v[138:141], v[200:203], v[90:93]
	v_mfma_f32_16x16x32_bf16 v[86:89], v[130:133], v[208:211], v[86:89]
	v_mfma_f32_16x16x32_bf16 v[82:85], v[138:141], v[208:211], v[82:85]
	v_mfma_f32_16x16x32_bf16 v[126:129], v[134:137], v[188:191], v[126:129]
	v_mfma_f32_16x16x32_bf16 v[122:125], v[142:145], v[188:191], v[122:125]
	v_mfma_f32_16x16x32_bf16 v[118:121], v[134:137], v[196:199], v[118:121]
	v_mfma_f32_16x16x32_bf16 v[114:117], v[142:145], v[196:199], v[114:117]
	v_mfma_f32_16x16x32_bf16 v[94:97], v[134:137], v[204:207], v[94:97]
	v_mfma_f32_16x16x32_bf16 v[90:93], v[142:145], v[204:207], v[90:93]
	v_mfma_f32_16x16x32_bf16 v[86:89], v[134:137], v[212:215], v[86:89]
	v_mfma_f32_16x16x32_bf16 v[82:85], v[142:145], v[212:215], v[82:85]
	s_setprio 0
	s_setprio 1
	v_mfma_f32_16x16x32_bf16 v[110:113], v[158:161], v[180:183], v[110:113]
	v_mfma_f32_16x16x32_bf16 v[106:109], v[172:175], v[180:183], v[106:109]
	v_mfma_f32_16x16x32_bf16 v[102:105], v[158:161], v[192:195], v[102:105]
	v_mfma_f32_16x16x32_bf16 v[98:101], v[172:175], v[192:195], v[98:101]
	v_mfma_f32_16x16x32_bf16 v[78:81], v[158:161], v[200:203], v[78:81]
	v_mfma_f32_16x16x32_bf16 v[74:77], v[172:175], v[200:203], v[74:77]
	v_mfma_f32_16x16x32_bf16 v[70:73], v[158:161], v[208:211], v[70:73]
	v_mfma_f32_16x16x32_bf16 v[66:69], v[172:175], v[208:211], v[66:69]
	v_mfma_f32_16x16x32_bf16 v[110:113], v[168:171], v[188:191], v[110:113]
	v_mfma_f32_16x16x32_bf16 v[106:109], v[176:179], v[188:191], v[106:109]
	v_mfma_f32_16x16x32_bf16 v[102:105], v[168:171], v[196:199], v[102:105]
	v_mfma_f32_16x16x32_bf16 v[98:101], v[176:179], v[196:199], v[98:101]
	v_mfma_f32_16x16x32_bf16 v[78:81], v[168:171], v[204:207], v[78:81]
	v_mfma_f32_16x16x32_bf16 v[74:77], v[176:179], v[204:207], v[74:77]
	v_mfma_f32_16x16x32_bf16 v[70:73], v[168:171], v[212:215], v[70:73]
	v_mfma_f32_16x16x32_bf16 v[66:69], v[176:179], v[212:215], v[66:69]
	s_setprio 0
	s_barrier
; #define PG8_STAGE(bufoff, gbase, voff) do { _Pragma("unroll") for (int _i = 0; _i < 2; ++_i) \
;         __builtin_amdgcn_global_load_lds((const unsigned*)((const char*)(gbase) + (voff)[_i]), (PG8_LAS unsigned*)(lds + (bufoff) + ldsw + _i * 8192), 16, 0, 0); } while (0)
; #define PG8_LDA(dst, b, h) do { _Pragma("unroll") for (int m = 0; m < 4; ++m) _Pragma("unroll") for (int k = 0; k < 2; ++k) dst[m][k] = *(const PG8_LAS bf16x8*)(lds + PG8_SA(b, h) + aoff + m * 2048 + k * 1024); } while (0)
; #define PG8_MMA(ai, bj, At, Bt) do { __builtin_amdgcn_s_setprio(1); _Pragma("unroll") for (int m = 0; m < 4; ++m) _Pragma("unroll") for (int n = 0; n < 2; ++n) _Pragma("unroll") for (int k = 0; k < 2; ++k) \
;         acc[ai][bj][m][n] = __builtin_amdgcn_mfma_f32_16x16x32_bf16(Bt[n][k], At[m][k], acc[ai][bj][m][n], 0, 0, 0); __builtin_amdgcn_s_setprio(0); } while (0)
; #define PG8_WAIT_V(n) asm volatile("s_waitcnt vmcnt(" #n ")" ::: "memory")
; #define PG8_WAIT_L(n) asm volatile("s_waitcnt lgkmcnt(" #n ")" ::: "memory")
; #define PG8_BAR __builtin_amdgcn_s_barrier()
; #define PG8_SCHED __builtin_amdgcn_sched_barrier(0)
; template <class Epi, class Sched, bool ALIGN_EPI = false, bool SP2 = false>
; __device__ __forceinline__ void gemm_phase(PG8_LAS unsigned char* lds, const Gemm g, const Sched& S, const Epi& E) {
;     ...
;             PG8_LDA(At, 1, 1); PG8_STAGE(PG8_SB(1, 0), b3, voffB); PG8_STAGE(PG8_SB(1, 1), b3 + hstep, voffB); PG8_STAGE(PG8_SA(1, 0), a3, voffA);
;             PG8_WAIT_V(8); PG8_WAIT_L(0); PG8_BAR; PG8_MMA(1, 0, At, B0); PG8_MMA(1, 1, At, B1); PG8_BAR; PG8_SCHED;
;     ...
;         if constexpr (ALIGN_EPI) { if (wr == 0) PG8_BAR; }
	s_add_i32 s26, s50, s28
	v_lshl_add_u64 v[184:185], v[184:185], 0, s[16:17]
	s_mov_b32 m0, s26
	ds_read_b128 v[180:183], v167 offset:49152
	ds_read_b128 v[188:191], v167 offset:50176
	ds_read_b128 v[192:195], v167 offset:51200
	ds_read_b128 v[196:199], v167 offset:52224
	ds_read_b128 v[200:203], v167 offset:53248
	ds_read_b128 v[204:207], v167 offset:54272
	ds_read_b128 v[208:211], v167 offset:55296
	ds_read_b128 v[212:215], v167 offset:56320
	global_load_lds_dwordx4 v[184:185], off
	s_add_i32 m0, s26, 0x2000
	s_add_u32 s24, s24, 0x160080
	v_lshl_add_u64 v[184:185], v[216:217], 0, s[16:17]
	s_addc_u32 s25, s25, 0
	s_add_i32 s26, s51, s28
	global_load_lds_dwordx4 v[184:185], off
	v_lshl_add_u64 v[184:185], s[24:25], 0, v[146:147]
	s_mov_b32 m0, s26
	s_nop 0
	global_load_lds_dwordx4 v[184:185], off
	v_lshl_add_u64 v[184:185], s[24:25], 0, v[148:149]
	s_add_i32 m0, s26, 0x2000
	s_nop 0
	global_load_lds_dwordx4 v[184:185], off
	v_lshl_add_u64 v[184:185], v[218:219], 0, s[16:17]
	s_mov_b32 m0, s37
	s_nop 0
	v_lshl_add_u64 v[184:185], v[220:221], 0, s[16:17]
	s_mov_b32 m0, s38
	s_nop 0
	s_waitcnt vmcnt(6)
	s_waitcnt lgkmcnt(0)
	s_barrier
	s_setprio 1
	s_waitcnt lgkmcnt(0)
	v_mfma_f32_16x16x32_bf16 v[62:65], v[130:133], v[180:183], v[62:65]
	v_mfma_f32_16x16x32_bf16 v[58:61], v[138:141], v[180:183], v[58:61]
	v_mfma_f32_16x16x32_bf16 v[54:57], v[130:133], v[192:195], v[54:57]
	v_mfma_f32_16x16x32_bf16 v[50:53], v[138:141], v[192:195], v[50:53]
	v_mfma_f32_16x16x32_bf16 v[30:33], v[130:133], v[200:203], v[30:33]
	v_mfma_f32_16x16x32_bf16 v[26:29], v[138:141], v[200:203], v[26:29]
	v_mfma_f32_16x16x32_bf16 v[22:25], v[130:133], v[208:211], v[22:25]
	v_mfma_f32_16x16x32_bf16 v[18:21], v[138:141], v[208:211], v[18:21]
	v_mfma_f32_16x16x32_bf16 v[62:65], v[134:137], v[188:191], v[62:65]
	v_mfma_f32_16x16x32_bf16 v[58:61], v[142:145], v[188:191], v[58:61]
	v_mfma_f32_16x16x32_bf16 v[54:57], v[134:137], v[196:199], v[54:57]
	v_mfma_f32_16x16x32_bf16 v[50:53], v[142:145], v[196:199], v[50:53]
	v_mfma_f32_16x16x32_bf16 v[30:33], v[134:137], v[204:207], v[30:33]
	v_mfma_f32_16x16x32_bf16 v[26:29], v[142:145], v[204:207], v[26:29]
	v_mfma_f32_16x16x32_bf16 v[22:25], v[134:137], v[212:215], v[22:25]
	v_mfma_f32_16x16x32_bf16 v[18:21], v[142:145], v[212:215], v[18:21]
	s_setprio 0
	s_setprio 1
	v_mfma_f32_16x16x32_bf16 v[46:49], v[158:161], v[180:183], v[46:49]
	v_mfma_f32_16x16x32_bf16 v[42:45], v[172:175], v[180:183], v[42:45]
	v_mfma_f32_16x16x32_bf16 v[38:41], v[158:161], v[192:195], v[38:41]
	v_mfma_f32_16x16x32_bf16 v[34:37], v[172:175], v[192:195], v[34:37]
	v_mfma_f32_16x16x32_bf16 v[14:17], v[158:161], v[200:203], v[14:17]
	v_mfma_f32_16x16x32_bf16 v[10:13], v[172:175], v[200:203], v[10:13]
	v_mfma_f32_16x16x32_bf16 v[6:9], v[158:161], v[208:211], v[6:9]
	v_mfma_f32_16x16x32_bf16 v[2:5], v[172:175], v[208:211], v[2:5]
	v_mfma_f32_16x16x32_bf16 v[46:49], v[168:171], v[188:191], v[46:49]
	v_mfma_f32_16x16x32_bf16 v[42:45], v[176:179], v[188:191], v[42:45]
	v_mfma_f32_16x16x32_bf16 v[38:41], v[168:171], v[196:199], v[38:41]
	v_mfma_f32_16x16x32_bf16 v[34:37], v[176:179], v[196:199], v[34:37]
	v_mfma_f32_16x16x32_bf16 v[14:17], v[168:171], v[204:207], v[14:17]
	v_mfma_f32_16x16x32_bf16 v[10:13], v[176:179], v[204:207], v[10:13]
	v_mfma_f32_16x16x32_bf16 v[6:9], v[168:171], v[212:215], v[6:9]
	v_mfma_f32_16x16x32_bf16 v[2:5], v[176:179], v[212:215], v[2:5]
	s_setprio 0
	s_barrier
	s_add_i32 s49, s49, 2
	s_add_u32 s22, s22, 0x100
	s_addc_u32 s23, s23, 0
	s_add_u32 s47, s47, 0x100
	s_addc_u32 s48, s48, 0
	s_cmpk_gt_u32 s49, 0x55
	s_cbranch_scc0 .LBB0_1195
	s_and_b64 vcc, exec, s[18:19]
	s_cbranch_vccz .LBB0_1198
	s_barrier

; template <bool NT_LD, bool NT_ST> DI void norm_row2(const float* xrow0, const float* xrow1, const float* g, const float* sc, const float* sh, bf16* obf0, bf16* obf1, float* of0, float* of1, int lane) {
;     ...
;     for (int j = 0; j < 8; ++j) { if (NT_LD) { v0[j] = __builtin_nontemporal_load(xr0 + 64 * j); v1[j] = __builtin_nontemporal_load(xr1 + 64 * j); } else { v0[j] = xr0[64 * j]; v1[j] = xr1[64 * j]; } }
; #pragma unroll
;     for (int j = 0; j < 8; ++j) { s0 += (v0[j].x * v0[j].x + v0[j].y * v0[j].y) + (v0[j].z * v0[j].z + v0[j].w * v0[j].w); s1 += (v1[j].x * v1[j].x + v1[j].y * v1[j].y) + (v1[j].z * v1[j].z + v1[j].w * v1[j].w); }
; __global__ void __launch_bounds__(512, 2) fwd_mega(Args args) {
;     ...
;         for (int m = 2 * gw; m < M; m += 2 * NGW) norm_row2<false, true>(out + (size_t)m * DM, out + (size_t)(m + 1) * DM, final_g, nullptr, nullptr, nullptr, nullptr, out + (size_t)m * DM, out + (size_t)(m + 1) * DM, lane);
.LBB0_1273:
	global_load_dwordx4 v[12:15], v[66:67], off
	global_load_dwordx4 v[8:11], v[66:67], off offset:1024
	global_load_dwordx4 v[4:7], v[66:67], off offset:2048
	global_load_dwordx4 v[0:3], v[66:67], off offset:3072
	v_add_co_u32_e32 v68, vcc, 0x2000, v66
	global_load_dwordx4 v[82:85], v[56:57], off
	s_nop 0
	v_addc_co_u32_e32 v69, vcc, 0, v67, vcc
	global_load_dwordx4 v[86:89], v[68:69], off
	global_load_dwordx4 v[90:93], v[68:69], off offset:1024
	global_load_dwordx4 v[52:55], v[68:69], off offset:2048
	global_load_dwordx4 v[48:51], v[68:69], off offset:3072
	v_add_co_u32_e32 v70, vcc, 0x1000, v66
	s_add_i32 s4, s4, s6
	s_nop 0
	v_addc_co_u32_e32 v71, vcc, 0, v67, vcc
	v_add_co_u32_e32 v72, vcc, 0x3000, v66
	global_load_dwordx4 v[44:47], v[70:71], off
	global_load_dwordx4 v[32:35], v[70:71], off offset:1024
	global_load_dwordx4 v[16:19], v[70:71], off offset:3072
	global_load_dwordx4 v[24:27], v[70:71], off offset:2048
	v_addc_co_u32_e32 v73, vcc, 0, v67, vcc
	global_load_dwordx4 v[40:43], v[72:73], off
	global_load_dwordx4 v[36:39], v[72:73], off offset:1024
	global_load_dwordx4 v[20:23], v[72:73], off offset:3072
	global_load_dwordx4 v[28:31], v[72:73], off offset:2048
	s_cmp_lt_i32 s4, 0x8000
	s_waitcnt vmcnt(16)
	v_mov_b32_e32 v96, v13
	s_waitcnt vmcnt(15)
	v_mov_b32_e32 v97, v9
	v_mov_b32_e32 v100, v15
	v_mov_b32_e32 v101, v11
	v_mov_b32_e32 v94, v12
	v_mov_b32_e32 v95, v8
	v_mov_b32_e32 v98, v14
	v_mov_b32_e32 v99, v10
	s_waitcnt vmcnt(14)
	v_pk_mul_f32 v[102:103], v[6:7], v[6:7]
	v_pk_mul_f32 v[104:105], v[4:5], v[4:5]
	v_pk_mul_f32 v[96:97], v[96:97], v[96:97]
	v_pk_mul_f32 v[100:101], v[100:101], v[100:101]
	s_waitcnt vmcnt(13)
	v_mul_f32_e32 v106, v1, v1
	v_mul_f32_e32 v108, v3, v3
	v_pk_mov_b32 v[110:111], v[104:105], v[102:103] op_sel:[1,0]
	v_mov_b32_e32 v105, v103
	v_pk_fma_f32 v[94:95], v[94:95], v[94:95], v[96:97]
	v_pk_fma_f32 v[96:97], v[98:99], v[98:99], v[100:101]
	s_waitcnt vmcnt(11)
	v_mov_b32_e32 v100, v87
	s_waitcnt vmcnt(10)
	v_mov_b32_e32 v101, v91
	v_mov_b32_e32 v112, v89
	v_mov_b32_e32 v113, v93
	v_pk_fma_f32 v[102:103], v[0:1], v[0:1], v[106:107] op_sel_hi:[1,1,0]
	v_pk_fma_f32 v[106:107], v[2:3], v[2:3], v[108:109] op_sel_hi:[1,1,0]
	v_mov_b32_e32 v98, v86
	v_mov_b32_e32 v99, v90
	v_mov_b32_e32 v108, v88
	v_mov_b32_e32 v109, v92
	v_pk_add_f32 v[104:105], v[110:111], v[104:105]
	s_waitcnt vmcnt(9)
	v_pk_mul_f32 v[110:111], v[54:55], v[54:55]
	v_pk_mul_f32 v[114:115], v[52:53], v[52:53]
	v_pk_add_f32 v[94:95], v[94:95], v[96:97]
	v_pk_mul_f32 v[96:97], v[100:101], v[100:101]
	v_pk_mul_f32 v[100:101], v[112:113], v[112:113]
	s_waitcnt vmcnt(8)
	v_mul_f32_e32 v116, v49, v49
	v_mul_f32_e32 v118, v51, v51
	v_pk_mov_b32 v[112:113], v[114:115], v[110:111] op_sel:[1,0]
	v_mov_b32_e32 v115, v111
	s_waitcnt vmcnt(7)
	v_mul_f32_e32 v125, v44, v44
	v_mul_f32_e32 v103, v45, v45
	v_mul_f32_e32 v107, v46, v46
	v_mul_f32_e32 v123, v47, v47
	v_pk_add_f32 v[104:105], v[104:105], v[104:105] op_sel:[0,1] op_sel_hi:[1,0]
	v_pk_fma_f32 v[96:97], v[98:99], v[98:99], v[96:97]
	v_pk_fma_f32 v[98:99], v[108:109], v[108:109], v[100:101]
	v_pk_add_f32 v[94:95], v[94:95], v[94:95] op_sel:[0,1] op_sel_hi:[1,0]
	v_pk_fma_f32 v[110:111], v[48:49], v[48:49], v[116:117] op_sel_hi:[1,1,0]
	v_pk_fma_f32 v[116:117], v[50:51], v[50:51], v[118:119] op_sel_hi:[1,1,0]
	s_waitcnt vmcnt(6)
	v_pk_mul_f32 v[118:119], v[34:35], v[34:35]
	v_pk_mul_f32 v[120:121], v[32:33], v[32:33]
	v_pk_add_f32 v[100:101], v[112:113], v[114:115]
	v_mov_b32_e32 v105, v103
	v_mov_b32_e32 v103, v107
	v_mov_b32_e32 v107, v123
	v_pk_add_f32 v[96:97], v[96:97], v[98:99]
	v_mov_b32_e32 v95, v125
	s_waitcnt vmcnt(3)
	v_mul_f32_e32 v131, v40, v40
	v_mul_f32_e32 v132, v41, v41
	v_pk_mov_b32 v[108:109], v[120:121], v[118:119] op_sel:[1,0]
	v_mov_b32_e32 v121, v119
	v_pk_add_f32 v[98:99], v[102:103], v[106:107]
	v_pk_add_f32 v[100:101], v[100:101], v[100:101] op_sel:[0,1] op_sel_hi:[1,0]
	v_pk_add_f32 v[94:95], v[94:95], v[104:105]
	v_pk_add_f32 v[96:97], v[96:97], v[96:97] op_sel:[0,1] op_sel_hi:[1,0]
	v_mul_f32_e32 v122, v25, v25
	v_mul_f32_e32 v124, v27, v27
	v_mul_f32_e32 v111, v42, v42
	v_mul_f32_e32 v117, v43, v43
	s_waitcnt vmcnt(2)
	v_pk_mul_f32 v[112:113], v[38:39], v[38:39]
	v_pk_mul_f32 v[114:115], v[36:37], v[36:37]
	v_pk_add_f32 v[102:103], v[108:109], v[120:121]
	v_mov_b32_e32 v101, v132
	v_pk_add_f32 v[94:95], v[94:95], v[98:99]
	v_mov_b32_e32 v97, v131
	v_mul_f32_e32 v127, v16, v16
	v_mul_f32_e32 v128, v17, v17
	v_mul_f32_e32 v129, v18, v18
	v_mul_f32_e32 v130, v19, v19
	v_pk_fma_f32 v[118:119], v[24:25], v[24:25], v[122:123] op_sel_hi:[1,1,0]
	v_pk_fma_f32 v[122:123], v[26:27], v[26:27], v[124:125] op_sel_hi:[1,1,0]
	v_pk_mov_b32 v[106:107], v[114:115], v[112:113] op_sel:[1,0]
	v_mov_b32_e32 v115, v113
	v_pk_add_f32 v[104:105], v[110:111], v[116:117]
	v_pk_add_f32 v[102:103], v[102:103], v[102:103] op_sel:[0,1] op_sel_hi:[1,0]
	v_pk_add_f32 v[96:97], v[96:97], v[100:101]
	v_pk_add_f32 v[94:95], v[94:95], v[94:95] op_sel:[0,1] op_sel_hi:[1,0]
	s_waitcnt vmcnt(0)
	v_mul_f32_e32 v124, v29, v29
	v_mul_f32_e32 v126, v31, v31
	v_mov_b32_e32 v119, v129
	v_mov_b32_e32 v123, v130
	v_pk_add_f32 v[106:107], v[106:107], v[114:115]
	v_mov_b32_e32 v103, v128
	v_pk_add_f32 v[96:97], v[96:97], v[104:105]
	v_mov_b32_e32 v95, v127
	v_mul_f32_e32 v133, v20, v20
	v_mul_f32_e32 v134, v21, v21
	v_mul_f32_e32 v135, v22, v22
	v_mul_f32_e32 v136, v23, v23
	v_pk_fma_f32 v[108:109], v[28:29], v[28:29], v[124:125] op_sel_hi:[1,1,0]
	v_pk_fma_f32 v[112:113], v[30:31], v[30:31], v[126:127] op_sel_hi:[1,1,0]
	v_pk_add_f32 v[110:111], v[118:119], v[122:123]
	v_pk_add_f32 v[98:99], v[106:107], v[106:107] op_sel:[0,1] op_sel_hi:[1,0]
	v_pk_add_f32 v[94:95], v[94:95], v[102:103]
	v_pk_add_f32 v[96:97], v[96:97], v[96:97] op_sel:[0,1] op_sel_hi:[1,0]
	v_mov_b32_e32 v109, v135
	v_mov_b32_e32 v113, v136
	v_mov_b32_e32 v99, v134
	v_pk_add_f32 v[94:95], v[94:95], v[110:111]
	v_mov_b32_e32 v97, v133
	v_pk_add_f32 v[106:107], v[108:109], v[112:113]
	v_add_f32_e32 v100, v94, v95
	v_pk_add_f32 v[94:95], v[96:97], v[98:99]
	ds_bpermute_b32 v96, v74, v100
	v_pk_add_f32 v[94:95], v[94:95], v[106:107]
	s_waitcnt lgkmcnt(0)
; DI unsigned pk2(float lo, float hi) { f32x2_t v = {lo, hi}; bf16x2_t b = __builtin_convertvector(v, bf16x2_t); return __builtin_bit_cast(unsigned, b); }
; template <bool NT_LD, bool NT_ST> DI void norm_row2(const float* xrow0, const float* xrow1, const float* g, const float* sc, const float* sh, bf16* obf0, bf16* obf1, float* of0, float* of1, int lane) {
;     ...
; #pragma unroll
;     for (int o = 1; o < 64; o <<= 1) { s0 += __shfl_xor(s0, o); s1 += __shfl_xor(s1, o); }
;     const float r0 = 1.0f / sqrtf(s0 * (1.0f / DM) + EPS), r1 = 1.0f / sqrtf(s1 * (1.0f / DM) + EPS);
; #pragma unroll
;     for (int j = 0; j < 8; ++j) {
;         const int c4 = lane + 64 * j;
;         const f32x4 gg = ((const f32x4*)g)[c4];
;         f32x4 y0 = v0[j] * r0 * gg, y1 = v1[j] * r1 * gg;
;         if (sc) { const f32x4 a = ((const f32x4*)sc)[c4] + 1.0f, bsh = ((const f32x4*)sh)[c4]; y0 = y0 * a + bsh; y1 = y1 * a + bsh; }
;         if (obf0) { u32x2 o0; o0.x = pk2(y0.x, y0.y); o0.y = pk2(y0.z, y0.w); ((u32x2*)obf0)[c4] = o0; u32x2 o1; o1.x = pk2(y1.x, y1.y); o1.y = pk2(y1.z, y1.w); ((u32x2*)obf1)[c4] = o1; }
;         else if (NT_ST) { __builtin_nontemporal_store(y0, (f32x4*)of0 + c4); __builtin_nontemporal_store(y1, (f32x4*)of1 + c4); }
	v_add_f32_e32 v96, v100, v96
	v_add_f32_e32 v94, v94, v95
	ds_bpermute_b32 v95, v74, v94
	ds_bpermute_b32 v97, v75, v96
	s_waitcnt lgkmcnt(1)
	v_add_f32_e32 v94, v94, v95
	ds_bpermute_b32 v95, v75, v94
	s_waitcnt lgkmcnt(1)
	v_add_f32_e32 v96, v96, v97
	ds_bpermute_b32 v97, v76, v96
	s_waitcnt lgkmcnt(1)
	v_add_f32_e32 v94, v94, v95
	ds_bpermute_b32 v95, v76, v94
	s_waitcnt lgkmcnt(1)
	v_add_f32_e32 v96, v96, v97
	ds_bpermute_b32 v97, v77, v96
	s_waitcnt lgkmcnt(1)
	v_add_f32_e32 v94, v94, v95
	ds_bpermute_b32 v95, v77, v94
	s_waitcnt lgkmcnt(1)
	v_add_f32_e32 v96, v96, v97
	ds_bpermute_b32 v97, v78, v96
	s_waitcnt lgkmcnt(1)
	v_add_f32_e32 v94, v94, v95
	ds_bpermute_b32 v95, v78, v94
	s_waitcnt lgkmcnt(1)
	v_add_f32_e32 v96, v96, v97
	ds_bpermute_b32 v97, v79, v96
	s_waitcnt lgkmcnt(1)
	v_add_f32_e32 v94, v94, v95
	ds_bpermute_b32 v95, v79, v94
	s_waitcnt lgkmcnt(1)
	v_add_f32_e32 v96, v96, v97
	v_fmamk_f32 v96, v96, 0x3a000000, v80
	v_cmp_gt_f32_e32 vcc, s5, v96
	s_waitcnt lgkmcnt(0)
	v_add_f32_e32 v94, v94, v95
	v_mul_f32_e32 v95, 0x4f800000, v96
	v_cndmask_b32_e32 v95, v96, v95, vcc
	v_fmamk_f32 v94, v94, 0x3a000000, v80
	v_sqrt_f32_e32 v96, v95
	v_mul_f32_e32 v97, 0x4f800000, v94
	v_cmp_gt_f32_e64 s[0:1], s5, v94
	v_add_u32_e32 v98, -1, v96
	s_nop 0
	v_cndmask_b32_e64 v94, v94, v97, s[0:1]
	v_sqrt_f32_e32 v97, v94
	v_add_u32_e32 v99, 1, v96
	v_fma_f32 v100, -v98, v96, v95
	v_fma_f32 v101, -v99, v96, v95
	v_cmp_ge_f32_e64 s[2:3], 0, v100
	v_add_u32_e32 v100, 1, v97
	s_nop 0
	v_cndmask_b32_e64 v96, v96, v98, s[2:3]
	v_add_u32_e32 v98, -1, v97
	v_cmp_lt_f32_e64 s[2:3], 0, v101
	v_fma_f32 v101, -v100, v97, v94
	s_nop 0
	v_cndmask_b32_e64 v96, v96, v99, s[2:3]
	v_fma_f32 v99, -v98, v97, v94
	v_cmp_ge_f32_e64 s[2:3], 0, v99
	v_mul_f32_e32 v102, 0x37800000, v96
	v_cndmask_b32_e32 v96, v96, v102, vcc
	v_cndmask_b32_e64 v97, v97, v98, s[2:3]
	v_cmp_lt_f32_e64 s[2:3], 0, v101
	v_cmp_class_f32_e32 vcc, v95, v81
	s_nop 0
	v_cndmask_b32_e64 v97, v97, v100, s[2:3]
	v_cndmask_b32_e32 v95, v96, v95, vcc
	v_mul_f32_e32 v96, 0x37800000, v97
	v_div_scale_f32 v98, s[2:3], v95, v95, 1.0
	v_cndmask_b32_e64 v96, v97, v96, s[0:1]
	v_cmp_class_f32_e64 s[0:1], v94, v81
	v_rcp_f32_e32 v97, v98
	v_div_scale_f32 v99, vcc, 1.0, v95, 1.0
	v_cndmask_b32_e64 v96, v96, v94, s[0:1]
	v_div_scale_f32 v100, s[0:1], v96, v96, 1.0
	v_rcp_f32_e32 v102, v100
	v_fma_f32 v94, -v98, v97, 1.0
	v_fmac_f32_e32 v97, v94, v97
	v_mul_f32_e32 v94, v99, v97
	v_fma_f32 v103, -v100, v102, 1.0
	v_div_scale_f32 v101, s[0:1], 1.0, v96, 1.0
	v_fma_f32 v104, -v98, v94, v99
	v_fmac_f32_e32 v102, v103, v102
	v_fmac_f32_e32 v94, v104, v97
	v_mul_f32_e32 v103, v101, v102
	v_fma_f32 v98, -v98, v94, v99
	v_fma_f32 v99, -v100, v103, v101
	v_div_fmas_f32 v94, v98, v97, v94
	v_fmac_f32_e32 v103, v99, v102
	v_div_fixup_f32 v94, v94, v95, 1.0
	v_fma_f32 v95, -v100, v103, v101
	s_mov_b64 vcc, s[0:1]
	v_div_fmas_f32 v95, v95, v102, v103
	v_pk_mul_f32 v[12:13], v[12:13], v[94:95] op_sel_hi:[1,0]
	v_pk_mul_f32 v[14:15], v[14:15], v[94:95] op_sel_hi:[1,0]
	v_div_fixup_f32 v96, v95, v96, 1.0
	v_pk_mul_f32 v[14:15], v[84:85], v[14:15]
	v_pk_mul_f32 v[12:13], v[82:83], v[12:13]
	v_pk_mul_f32 v[86:87], v[86:87], v[96:97] op_sel_hi:[1,0]
	v_pk_mul_f32 v[88:89], v[88:89], v[96:97] op_sel_hi:[1,0]
	global_store_dwordx4 v[66:67], v[12:15], off nt
	v_pk_mul_f32 v[10:11], v[10:11], v[94:95] op_sel_hi:[1,0]
	v_pk_mul_f32 v[8:9], v[8:9], v[94:95] op_sel_hi:[1,0]
	v_pk_mul_f32 v[14:15], v[84:85], v[88:89]
	v_pk_mul_f32 v[12:13], v[82:83], v[86:87]
	global_store_dwordx4 v[68:69], v[12:15], off nt
	global_load_dwordx4 v[12:15], v[56:57], off offset:1024
	v_pk_mul_f32 v[82:83], v[92:93], v[96:97] op_sel_hi:[1,0]
	v_pk_mul_f32 v[84:85], v[90:91], v[96:97] op_sel_hi:[1,0]
	v_pk_mul_f32 v[6:7], v[6:7], v[94:95] op_sel_hi:[1,0]
	v_pk_mul_f32 v[4:5], v[4:5], v[94:95] op_sel_hi:[1,0]
	v_pk_mul_f32 v[2:3], v[2:3], v[94:95] op_sel_hi:[1,0]
	v_pk_mul_f32 v[0:1], v[0:1], v[94:95] op_sel_hi:[1,0]
	s_waitcnt vmcnt(0)
; DI unsigned pk2(float lo, float hi) { f32x2_t v = {lo, hi}; bf16x2_t b = __builtin_convertvector(v, bf16x2_t); return __builtin_bit_cast(unsigned, b); }
; template <bool NT_LD, bool NT_ST> DI void norm_row2(const float* xrow0, const float* xrow1, const float* g, const float* sc, const float* sh, bf16* obf0, bf16* obf1, float* of0, float* of1, int lane) {
;     ...
;     for (int j = 0; j < 8; ++j) {
;         const int c4 = lane + 64 * j;
;         const f32x4 gg = ((const f32x4*)g)[c4];
;         f32x4 y0 = v0[j] * r0 * gg, y1 = v1[j] * r1 * gg;
;         if (sc) { const f32x4 a = ((const f32x4*)sc)[c4] + 1.0f, bsh = ((const f32x4*)sh)[c4]; y0 = y0 * a + bsh; y1 = y1 * a + bsh; }
;         if (obf0) { u32x2 o0; o0.x = pk2(y0.x, y0.y); o0.y = pk2(y0.z, y0.w); ((u32x2*)obf0)[c4] = o0; u32x2 o1; o1.x = pk2(y1.x, y1.y); o1.y = pk2(y1.z, y1.w); ((u32x2*)obf1)[c4] = o1; }
;         else if (NT_ST) { __builtin_nontemporal_store(y0, (f32x4*)of0 + c4); __builtin_nontemporal_store(y1, (f32x4*)of1 + c4); }
;         else { ((f32x4*)of0)[c4] = y0; ((f32x4*)of1)[c4] = y1; }
; __global__ void __launch_bounds__(512, 2) fwd_mega(Args args) {
;     ...
;         for (int m = 2 * gw; m < M; m += 2 * NGW) norm_row2<false, true>(out + (size_t)m * DM, out + (size_t)(m + 1) * DM, final_g, nullptr, nullptr, nullptr, nullptr, out + (size_t)m * DM, out + (size_t)(m + 1) * DM, lane);
	v_pk_mul_f32 v[8:9], v[12:13], v[8:9]
	v_pk_mul_f32 v[10:11], v[14:15], v[10:11]
	v_pk_mul_f32 v[12:13], v[12:13], v[84:85]
	v_pk_mul_f32 v[14:15], v[14:15], v[82:83]
	global_store_dwordx4 v[66:67], v[8:11], off offset:1024 nt
	global_store_dwordx4 v[68:69], v[12:15], off offset:1024 nt
	global_load_dwordx4 v[8:11], v[56:57], off offset:2048
	s_waitcnt vmcnt(0)
	v_pk_mul_f32 v[4:5], v[8:9], v[4:5]
	v_pk_mul_f32 v[12:13], v[54:55], v[96:97] op_sel_hi:[1,0]
	v_pk_mul_f32 v[14:15], v[52:53], v[96:97] op_sel_hi:[1,0]
	v_pk_mul_f32 v[6:7], v[10:11], v[6:7]
	v_pk_mul_f32 v[8:9], v[8:9], v[14:15]
	v_pk_mul_f32 v[10:11], v[10:11], v[12:13]
	global_store_dwordx4 v[66:67], v[4:7], off offset:2048 nt
	global_store_dwordx4 v[68:69], v[8:11], off offset:2048 nt
	global_load_dwordx4 v[4:7], v[56:57], off offset:3072
	s_waitcnt vmcnt(0)
	v_pk_mul_f32 v[0:1], v[0:1], v[4:5]
	v_pk_mul_f32 v[8:9], v[50:51], v[96:97] op_sel_hi:[1,0]
	v_pk_mul_f32 v[10:11], v[48:49], v[96:97] op_sel_hi:[1,0]
	v_pk_mul_f32 v[2:3], v[2:3], v[6:7]
	v_pk_mul_f32 v[4:5], v[10:11], v[4:5]
	v_pk_mul_f32 v[6:7], v[8:9], v[6:7]
	global_store_dwordx4 v[66:67], v[0:3], off offset:3072 nt
	global_store_dwordx4 v[68:69], v[4:7], off offset:3072 nt
	global_load_dwordx4 v[0:3], v[58:59], off
	v_pk_mul_f32 v[8:9], v[42:43], v[96:97] op_sel_hi:[1,0]
	v_pk_mul_f32 v[6:7], v[46:47], v[94:95] op_sel_hi:[1,0]
	v_pk_mul_f32 v[4:5], v[44:45], v[94:95] op_sel_hi:[1,0]
	v_pk_mul_f32 v[10:11], v[40:41], v[96:97] op_sel_hi:[1,0]
	v_lshl_add_u64 v[66:67], v[66:67], 0, s[8:9]
	s_waitcnt vmcnt(0)
	v_pk_mul_f32 v[4:5], v[4:5], v[0:1]
	v_pk_mul_f32 v[6:7], v[6:7], v[2:3]
	v_pk_mul_f32 v[0:1], v[10:11], v[0:1]
	v_pk_mul_f32 v[2:3], v[8:9], v[2:3]
	global_store_dwordx4 v[70:71], v[4:7], off nt
	global_store_dwordx4 v[72:73], v[0:3], off nt
	global_load_dwordx4 v[0:3], v[60:61], off
	v_pk_mul_f32 v[6:7], v[34:35], v[94:95] op_sel_hi:[1,0]
	v_pk_mul_f32 v[4:5], v[32:33], v[94:95] op_sel_hi:[1,0]
	v_pk_mul_f32 v[8:9], v[38:39], v[96:97] op_sel_hi:[1,0]
	v_pk_mul_f32 v[10:11], v[36:37], v[96:97] op_sel_hi:[1,0]
	s_waitcnt vmcnt(0)
	v_pk_mul_f32 v[4:5], v[4:5], v[0:1]
	v_pk_mul_f32 v[6:7], v[6:7], v[2:3]
	v_pk_mul_f32 v[0:1], v[10:11], v[0:1]
	v_pk_mul_f32 v[2:3], v[8:9], v[2:3]
	global_store_dwordx4 v[70:71], v[4:7], off offset:1024 nt
	global_store_dwordx4 v[72:73], v[0:3], off offset:1024 nt
	global_load_dwordx4 v[0:3], v[62:63], off
	v_pk_mul_f32 v[6:7], v[26:27], v[94:95] op_sel_hi:[1,0]
	v_pk_mul_f32 v[4:5], v[24:25], v[94:95] op_sel_hi:[1,0]
	v_pk_mul_f32 v[8:9], v[30:31], v[96:97] op_sel_hi:[1,0]
	v_pk_mul_f32 v[10:11], v[28:29], v[96:97] op_sel_hi:[1,0]
	s_waitcnt vmcnt(0)
	v_pk_mul_f32 v[4:5], v[4:5], v[0:1]
	v_pk_mul_f32 v[6:7], v[6:7], v[2:3]
	v_pk_mul_f32 v[0:1], v[10:11], v[0:1]
	v_pk_mul_f32 v[2:3], v[8:9], v[2:3]
	global_store_dwordx4 v[70:71], v[4:7], off offset:2048 nt
	global_store_dwordx4 v[72:73], v[0:3], off offset:2048 nt
	global_load_dwordx4 v[0:3], v[64:65], off
	v_pk_mul_f32 v[6:7], v[18:19], v[94:95] op_sel_hi:[1,0]
	v_pk_mul_f32 v[4:5], v[16:17], v[94:95] op_sel_hi:[1,0]
	v_pk_mul_f32 v[8:9], v[22:23], v[96:97] op_sel_hi:[1,0]
	v_pk_mul_f32 v[10:11], v[20:21], v[96:97] op_sel_hi:[1,0]
	s_waitcnt vmcnt(0)
	v_pk_mul_f32 v[4:5], v[4:5], v[0:1]
	v_pk_mul_f32 v[6:7], v[6:7], v[2:3]
	v_pk_mul_f32 v[0:1], v[10:11], v[0:1]
	v_pk_mul_f32 v[2:3], v[8:9], v[2:3]
	global_store_dwordx4 v[70:71], v[4:7], off offset:3072 nt
	global_store_dwordx4 v[72:73], v[0:3], off offset:3072 nt
	s_cbranch_scc1 .LBB0_1273

; __global__ void __launch_bounds__(512, 2) fwd_mega(Args args) {
	.amdhsa_kernel _Z8fwd_mega4Args
		.amdhsa_group_segment_fixed_size 0
		.amdhsa_private_segment_fixed_size 0
		.amdhsa_kernarg_size 424
		.amdhsa_user_sgpr_count 2
		.amdhsa_user_sgpr_dispatch_ptr 0
		.amdhsa_user_sgpr_queue_ptr 0
		.amdhsa_user_sgpr_kernarg_segment_ptr 1
		.amdhsa_user_sgpr_dispatch_id 0
		.amdhsa_user_sgpr_kernarg_preload_length 0
		.amdhsa_user_sgpr_kernarg_preload_offset 0
		.amdhsa_user_sgpr_private_segment_size 0
		.amdhsa_uses_dynamic_stack 0
		.amdhsa_enable_private_segment 0
		.amdhsa_system_sgpr_workgroup_id_x 1
		.amdhsa_system_sgpr_workgroup_id_y 0
		.amdhsa_system_sgpr_workgroup_id_z 0
		.amdhsa_system_sgpr_workgroup_info 0
		.amdhsa_system_vgpr_workitem_id 2
		.amdhsa_next_free_vgpr 250
		.amdhsa_next_free_sgpr 102
		.amdhsa_accum_offset 252
		.amdhsa_reserve_vcc 1
		.amdhsa_float_round_mode_32 0
		.amdhsa_float_round_mode_16_64 0
		.amdhsa_float_denorm_mode_32 3
		.amdhsa_float_denorm_mode_16_64 3
		.amdhsa_dx10_clamp 1
		.amdhsa_ieee_mode 1
		.amdhsa_fp16_overflow 0
		.amdhsa_tg_split 0
		.amdhsa_exception_fp_ieee_invalid_op 0
		.amdhsa_exception_fp_denorm_src 0
		.amdhsa_exception_fp_ieee_div_zero 0
		.amdhsa_exception_fp_ieee_overflow 0
		.amdhsa_exception_fp_ieee_underflow 0
		.amdhsa_exception_fp_ieee_inexact 0
		.amdhsa_exception_int_div_zero 0
	.end_amdhsa_kernel

; __global__ void __launch_bounds__(512, 2) fwd_mega(Args args) {
amdhsa.kernels:
  - .agpr_count:     0
    .args:
      - .offset:         0
        .size:           168
        .value_kind:     by_value
      - .offset:         168
        .size:           4
        .value_kind:     hidden_block_count_x
      - .offset:         172
        .size:           4
        .value_kind:     hidden_block_count_y
      - .offset:         176
        .size:           4
        .value_kind:     hidden_block_count_z
      - .offset:         180
        .size:           2
        .value_kind:     hidden_group_size_x
      - .offset:         182
        .size:           2
        .value_kind:     hidden_group_size_y
      - .offset:         184
        .size:           2
        .value_kind:     hidden_group_size_z
      - .offset:         186
        .size:           2
        .value_kind:     hidden_remainder_x
      - .offset:         188
        .size:           2
        .value_kind:     hidden_remainder_y
      - .offset:         190
        .size:           2
        .value_kind:     hidden_remainder_z
      - .offset:         208
        .size:           8
        .value_kind:     hidden_global_offset_x
      - .offset:         216
        .size:           8
        .value_kind:     hidden_global_offset_y
      - .offset:         224
        .size:           8
        .value_kind:     hidden_global_offset_z
      - .offset:         232
        .size:           2
        .value_kind:     hidden_grid_dims
      - .offset:         256
        .size:           8
        .value_kind:     hidden_multigrid_sync_arg
      - .offset:         288
        .size:           4
        .value_kind:     hidden_dynamic_lds_size
    .group_segment_fixed_size: 0
    .kernarg_segment_align: 8
    .kernarg_segment_size: 424
    .language:       OpenCL C
    .language_version:
      - 2
      - 0
    .max_flat_workgroup_size: 512
    .name:           _Z8fwd_mega4Args
    .private_segment_fixed_size: 0
    .sgpr_count:     108
    .sgpr_spill_count: 82
    .symbol:         _Z8fwd_mega4Args.kd
    .uniform_work_group_size: 1
    .uses_dynamic_stack: false
    .vgpr_count:     250
    .vgpr_spill_count: 0
    .wavefront_size: 64
